# MFMA-shadow fill at unit boundary: wr0 re-sync barrier moved up to 110 instructions into the epilogue so wr0 works while wr1 finishes its last MFMA step
# baseline (speedup 1.0000x reference)
; #define PG8_STAGE(bufoff, gbase, voff) do { _Pragma("unroll") for (int _i = 0; _i < 2; ++_i) \
;         __builtin_amdgcn_global_load_lds((const unsigned*)((const char*)(gbase) + (voff)[_i]), (LAS unsigned*)(lds + (bufoff) + ldsw + _i * 8192), 16, 0, 0); } while (0)
; #define PG8_LDA(dst, b, h) do { _Pragma("unroll") for (int m = 0; m < 4; ++m) _Pragma("unroll") for (int k = 0; k < 2; ++k) dst[m][k] = *(const LAS bf16x8*)(lds + PG8_SA(b, h) + aoff + m * 2048 + k * 1024); } while (0)
; #define PG8_LDB(dst, b, h) do { _Pragma("unroll") for (int n = 0; n < 2; ++n) _Pragma("unroll") for (int k = 0; k < 2; ++k) dst[n][k] = *(const LAS bf16x8*)(lds + PG8_SB(b, h) + boff + n * 2048 + k * 1024); } while (0)
; #define PG8_MMA(ai, bj, At, Bt) do { __builtin_amdgcn_s_setprio(1); _Pragma("unroll") for (int m = 0; m < 4; ++m) _Pragma("unroll") for (int n = 0; n < 2; ++n) _Pragma("unroll") for (int k = 0; k < 2; ++k) \
;         acc[ai][bj][m][n] = __builtin_amdgcn_mfma_f32_16x16x32_bf16(Bt[n][k], At[m][k], acc[ai][bj][m][n], 0, 0, 0); __builtin_amdgcn_s_setprio(0); } while (0)
; #define PG8_WAIT_V(n) asm volatile("s_waitcnt vmcnt(" #n ")" ::: "memory")
; #define PG8_WAIT_L(n) asm volatile("s_waitcnt lgkmcnt(" #n ")" ::: "memory")
; template <class Epi>
; __device__ __forceinline__ void gemm_phase(LAS unsigned char* lds, const Gemm g, const Sched& S, const Epi& E) {
;     ...
;         for (int t = 0; t < nt; t += 2) {
;             const bool last = (t == nt - 2);
;             const char* a1 = cA + (size_t)(t + 1) * kstep;
;             const char* a2 = last ? nA : cA + (size_t)(t + 2) * kstep; const char* b2 = last ? nB : cB + (size_t)(t + 2) * kstep;
;             const char* a3 = a2 + kstep; const char* b3 = b2 + kstep;
;             PG8_LDB(B0, 0, 0); PG8_SCHED; PG8_LDA(At, 0, 0); PG8_STAGE(PG8_SA(1, 1), a1 + hstepA, voffA);
;             PG8_WAIT_L(8); PG8_BAR; PG8_WAIT_L(0); PG8_MMA(0, 0, At, B0); PG8_BAR; PG8_SCHED;
;             PG8_LDB(B1, 0, 1); PG8_STAGE(PG8_SB(0, 0), b2, voffB);
;             PG8_BAR; PG8_WAIT_L(0); PG8_MMA(0, 1, At, B1); PG8_BAR;
;             PG8_LDA(At, 0, 1); PG8_STAGE(PG8_SA(0, 0), a2, voffA);
;             PG8_BAR; PG8_WAIT_L(0); PG8_MMA(1, 0, At, B0); PG8_BAR; PG8_SCHED;
;             PG8_STAGE(PG8_SB(0, 1), b2 + hstepB, voffB);
;             PG8_WAIT_V(6); PG8_BAR; PG8_MMA(1, 1, At, B1); PG8_BAR;
.Lresync_y_400:
.LBB0_400:
	s_add_i32 s14, s66, 2
	s_add_u32 s8, s92, 0x80
	s_addc_u32 s9, s93, 0
	s_add_i32 s15, 0, 0x10000
	v_add_u32_e32 v148, s15, v152
	ds_read_b128 v[144:147], v148
	ds_read_b128 v[172:175], v148 offset:1024
	ds_read_b128 v[176:179], v148 offset:2048
	ds_read_b128 v[180:183], v148 offset:3072
	s_cmp_eq_u32 s71, s66
	s_cselect_b32 s95, s55, s9
	s_cselect_b32 s94, s57, s8
	s_cselect_b32 s97, s59, s35
	s_cselect_b32 s96, s65, s34
	v_lshl_add_u64 v[148:149], s[92:93], 0, v[138:139]
	s_add_i32 m0, s42, 0xc000
	ds_read_b128 v[184:187], v171
	ds_read_b128 v[188:191], v171 offset:1024
	ds_read_b128 v[196:199], v171 offset:2048
	ds_read_b128 v[200:203], v171 offset:3072
	ds_read_b128 v[204:207], v171 offset:4096
	ds_read_b128 v[208:211], v171 offset:5120
	ds_read_b128 v[212:215], v171 offset:6144
	ds_read_b128 v[222:225], v171 offset:7168
	global_load_lds_dwordx4 v[148:149], off
	v_lshl_add_u64 v[148:149], s[92:93], 0, v[140:141]
	s_add_i32 m0, s42, 0xe000
	s_nop 0
	global_load_lds_dwordx4 v[148:149], off
	s_add_i32 s8, 0, 0x14000
	v_add_u32_e32 v148, s8, v152
	ds_read_b128 v[226:229], v148
	ds_read_b128 v[230:233], v148 offset:1024
	ds_read_b128 v[234:237], v148 offset:2048
	ds_read_b128 v[238:241], v148 offset:3072
	s_waitcnt vmcnt(8)
	s_waitcnt lgkmcnt(0)
	v_mfma_f32_16x16x32_bf16 v[126:129], v[144:147], v[184:187], v[126:129]
	v_mfma_f32_16x16x32_bf16 v[122:125], v[176:179], v[184:187], v[122:125]
	v_mfma_f32_16x16x32_bf16 v[110:113], v[144:147], v[196:199], v[110:113]
	v_mfma_f32_16x16x32_bf16 v[106:109], v[176:179], v[196:199], v[106:109]
	s_barrier
	s_setprio 1
	v_mfma_f32_16x16x32_bf16 v[94:97], v[144:147], v[204:207], v[94:97]
	v_mfma_f32_16x16x32_bf16 v[90:93], v[176:179], v[204:207], v[90:93]
	v_mfma_f32_16x16x32_bf16 v[78:81], v[144:147], v[212:215], v[78:81]
	v_mfma_f32_16x16x32_bf16 v[74:77], v[176:179], v[212:215], v[74:77]
	v_mfma_f32_16x16x32_bf16 v[126:129], v[172:175], v[188:191], v[126:129]
	v_mfma_f32_16x16x32_bf16 v[122:125], v[180:183], v[188:191], v[122:125]
	v_mfma_f32_16x16x32_bf16 v[110:113], v[172:175], v[200:203], v[110:113]
	v_mfma_f32_16x16x32_bf16 v[106:109], v[180:183], v[200:203], v[106:109]
	v_mfma_f32_16x16x32_bf16 v[94:97], v[172:175], v[208:211], v[94:97]
	v_mfma_f32_16x16x32_bf16 v[90:93], v[180:183], v[208:211], v[90:93]
	v_mfma_f32_16x16x32_bf16 v[78:81], v[172:175], v[222:225], v[78:81]
	v_mfma_f32_16x16x32_bf16 v[74:77], v[180:183], v[222:225], v[74:77]
	v_mfma_f32_16x16x32_bf16 v[118:121], v[226:229], v[184:187], v[118:121]
	v_mfma_f32_16x16x32_bf16 v[114:117], v[234:237], v[184:187], v[114:117]
	v_mfma_f32_16x16x32_bf16 v[102:105], v[226:229], v[196:199], v[102:105]
	v_mfma_f32_16x16x32_bf16 v[98:101], v[234:237], v[196:199], v[98:101]
	v_mfma_f32_16x16x32_bf16 v[86:89], v[226:229], v[204:207], v[86:89]
	v_mfma_f32_16x16x32_bf16 v[82:85], v[234:237], v[204:207], v[82:85]
	v_mfma_f32_16x16x32_bf16 v[70:73], v[226:229], v[212:215], v[70:73]
	v_mfma_f32_16x16x32_bf16 v[66:69], v[234:237], v[212:215], v[66:69]
	v_mfma_f32_16x16x32_bf16 v[118:121], v[230:233], v[188:191], v[118:121]
	v_mfma_f32_16x16x32_bf16 v[114:117], v[238:241], v[188:191], v[114:117]
	v_mfma_f32_16x16x32_bf16 v[102:105], v[230:233], v[200:203], v[102:105]
	v_mfma_f32_16x16x32_bf16 v[98:101], v[238:241], v[200:203], v[98:101]
	v_mfma_f32_16x16x32_bf16 v[86:89], v[230:233], v[208:211], v[86:89]
	v_mfma_f32_16x16x32_bf16 v[82:85], v[238:241], v[208:211], v[82:85]
	v_mfma_f32_16x16x32_bf16 v[70:73], v[230:233], v[222:225], v[70:73]
	v_mfma_f32_16x16x32_bf16 v[66:69], v[238:241], v[222:225], v[66:69]
	s_setprio 0
	s_barrier
	s_add_i32 s9, s15, s39
	v_lshl_add_u64 v[148:149], s[96:97], 0, v[132:133]
	s_mov_b32 m0, s9
	v_lshl_add_u64 v[192:193], s[96:97], 0, v[136:137]
	global_load_lds_dwordx4 v[148:149], off
	s_add_i32 m0, s9, 0x2000
	s_nop 0
	global_load_lds_dwordx4 v[192:193], off
	s_mov_b32 m0, s42
	v_lshl_add_u64 v[194:195], s[94:95], 0, v[130:131]
	ds_read_b128 v[184:187], v171 offset:16384
	ds_read_b128 v[188:191], v171 offset:17408
	ds_read_b128 v[196:199], v171 offset:18432
	ds_read_b128 v[200:203], v171 offset:19456
	ds_read_b128 v[204:207], v171 offset:20480
	ds_read_b128 v[208:211], v171 offset:21504
	ds_read_b128 v[212:215], v171 offset:22528
	ds_read_b128 v[222:225], v171 offset:23552
	global_load_lds_dwordx4 v[194:195], off
	v_lshl_add_u64 v[216:217], s[94:95], 0, v[134:135]
	s_mov_b32 m0, s43
	s_nop 0
	global_load_lds_dwordx4 v[216:217], off
	s_add_u32 s96, s96, s78
	s_addc_u32 s97, s97, s79
	s_add_i32 s8, s8, s39
	v_lshl_add_u64 v[242:243], s[96:97], 0, v[132:133]
	s_mov_b32 m0, s8
	v_lshl_add_u64 v[244:245], s[96:97], 0, v[136:137]
	global_load_lds_dwordx4 v[242:243], off
	s_add_i32 m0, s8, 0x2000
	s_nop 0
	global_load_lds_dwordx4 v[244:245], off
	s_waitcnt vmcnt(8)
	s_waitcnt lgkmcnt(0)
	v_mfma_f32_16x16x32_bf16 v[62:65], v[144:147], v[184:187], v[62:65]
	v_mfma_f32_16x16x32_bf16 v[58:61], v[176:179], v[184:187], v[58:61]
	v_mfma_f32_16x16x32_bf16 v[50:53], v[144:147], v[196:199], v[50:53]
	v_mfma_f32_16x16x32_bf16 v[42:45], v[176:179], v[196:199], v[42:45]
	s_barrier
; #define PG8_STAGE(bufoff, gbase, voff) do { _Pragma("unroll") for (int _i = 0; _i < 2; ++_i) \
;         __builtin_amdgcn_global_load_lds((const unsigned*)((const char*)(gbase) + (voff)[_i]), (LAS unsigned*)(lds + (bufoff) + ldsw + _i * 8192), 16, 0, 0); } while (0)
; #define PG8_LDA(dst, b, h) do { _Pragma("unroll") for (int m = 0; m < 4; ++m) _Pragma("unroll") for (int k = 0; k < 2; ++k) dst[m][k] = *(const LAS bf16x8*)(lds + PG8_SA(b, h) + aoff + m * 2048 + k * 1024); } while (0)
; #define PG8_LDB(dst, b, h) do { _Pragma("unroll") for (int n = 0; n < 2; ++n) _Pragma("unroll") for (int k = 0; k < 2; ++k) dst[n][k] = *(const LAS bf16x8*)(lds + PG8_SB(b, h) + boff + n * 2048 + k * 1024); } while (0)
; #define PG8_MMA(ai, bj, At, Bt) do { __builtin_amdgcn_s_setprio(1); _Pragma("unroll") for (int m = 0; m < 4; ++m) _Pragma("unroll") for (int n = 0; n < 2; ++n) _Pragma("unroll") for (int k = 0; k < 2; ++k) \
;         acc[ai][bj][m][n] = __builtin_amdgcn_mfma_f32_16x16x32_bf16(Bt[n][k], At[m][k], acc[ai][bj][m][n], 0, 0, 0); __builtin_amdgcn_s_setprio(0); } while (0)
; #define PG8_WAIT_V(n) asm volatile("s_waitcnt vmcnt(" #n ")" ::: "memory")
; #define PG8_WAIT_L(n) asm volatile("s_waitcnt lgkmcnt(" #n ")" ::: "memory")
; #define PG8_BAR __builtin_amdgcn_s_barrier()
; #define PG8_SCHED __builtin_amdgcn_sched_barrier(0)
; template <class Epi>
; __device__ __forceinline__ void gemm_phase(LAS unsigned char* lds, const Gemm g, const Sched& S, const Epi& E) {
;     ...
;             PG8_BAR; PG8_WAIT_L(0); PG8_MMA(1, 0, At, B0); PG8_BAR; PG8_SCHED;
;             PG8_STAGE(PG8_SB(0, 1), b2 + hstepB, voffB);
;             PG8_WAIT_V(6); PG8_BAR; PG8_MMA(1, 1, At, B1); PG8_BAR;
;             PG8_LDB(B0, 1, 0); PG8_SCHED; PG8_LDA(At, 1, 0); PG8_STAGE(PG8_SA(0, 1), a2 + hstepA, voffA);
;             PG8_WAIT_L(8); PG8_BAR; PG8_WAIT_L(0); PG8_MMA(0, 0, At, B0); PG8_BAR; PG8_SCHED;
;             PG8_LDB(B1, 1, 1); PG8_STAGE(PG8_SB(1, 0), b3, voffB);
;             PG8_BAR; PG8_WAIT_L(0); PG8_MMA(0, 1, At, B1); PG8_BAR;
	s_setprio 1
	v_mfma_f32_16x16x32_bf16 v[34:37], v[144:147], v[204:207], v[34:37]
	v_mfma_f32_16x16x32_bf16 v[26:29], v[176:179], v[204:207], v[26:29]
	v_mfma_f32_16x16x32_bf16 v[18:21], v[144:147], v[212:215], v[18:21]
	v_mfma_f32_16x16x32_bf16 v[10:13], v[176:179], v[212:215], v[10:13]
	v_mfma_f32_16x16x32_bf16 v[62:65], v[172:175], v[188:191], v[62:65]
	v_mfma_f32_16x16x32_bf16 v[58:61], v[180:183], v[188:191], v[58:61]
	v_mfma_f32_16x16x32_bf16 v[50:53], v[172:175], v[200:203], v[50:53]
	v_mfma_f32_16x16x32_bf16 v[42:45], v[180:183], v[200:203], v[42:45]
	v_mfma_f32_16x16x32_bf16 v[34:37], v[172:175], v[208:211], v[34:37]
	v_mfma_f32_16x16x32_bf16 v[26:29], v[180:183], v[208:211], v[26:29]
	v_mfma_f32_16x16x32_bf16 v[18:21], v[172:175], v[222:225], v[18:21]
	v_mfma_f32_16x16x32_bf16 v[10:13], v[180:183], v[222:225], v[10:13]
	v_mfma_f32_16x16x32_bf16 v[54:57], v[226:229], v[184:187], v[54:57]
	v_mfma_f32_16x16x32_bf16 v[46:49], v[234:237], v[184:187], v[46:49]
	v_mfma_f32_16x16x32_bf16 v[38:41], v[226:229], v[196:199], v[38:41]
	v_mfma_f32_16x16x32_bf16 v[30:33], v[234:237], v[196:199], v[30:33]
	v_mfma_f32_16x16x32_bf16 v[22:25], v[226:229], v[204:207], v[22:25]
	v_mfma_f32_16x16x32_bf16 v[14:17], v[234:237], v[204:207], v[14:17]
	v_mfma_f32_16x16x32_bf16 v[6:9], v[226:229], v[212:215], v[6:9]
	v_mfma_f32_16x16x32_bf16 v[2:5], v[234:237], v[212:215], v[2:5]
	v_mfma_f32_16x16x32_bf16 v[54:57], v[230:233], v[188:191], v[54:57]
	v_mfma_f32_16x16x32_bf16 v[46:49], v[238:241], v[188:191], v[46:49]
	v_mfma_f32_16x16x32_bf16 v[38:41], v[230:233], v[200:203], v[38:41]
	v_mfma_f32_16x16x32_bf16 v[30:33], v[238:241], v[200:203], v[30:33]
	v_mfma_f32_16x16x32_bf16 v[22:25], v[230:233], v[208:211], v[22:25]
	v_mfma_f32_16x16x32_bf16 v[14:17], v[238:241], v[208:211], v[14:17]
	v_mfma_f32_16x16x32_bf16 v[6:9], v[230:233], v[222:225], v[6:9]
	v_mfma_f32_16x16x32_bf16 v[2:5], v[238:241], v[222:225], v[2:5]
	s_setprio 0
	s_barrier
	s_add_i32 s8, 0, 0x18000
	v_add_u32_e32 v180, s8, v152
	ds_read_b128 v[144:147], v180
	ds_read_b128 v[172:175], v180 offset:1024
	ds_read_b128 v[176:179], v180 offset:2048
	ds_read_b128 v[180:183], v180 offset:3072
	s_add_u32 s94, s94, s4
	s_addc_u32 s95, s95, s5
	s_mov_b32 m0, s52
	v_lshl_add_u64 v[226:227], s[94:95], 0, v[130:131]
	ds_read_b128 v[184:187], v171 offset:32768
	ds_read_b128 v[188:191], v171 offset:33792
	ds_read_b128 v[196:199], v171 offset:34816
	ds_read_b128 v[200:203], v171 offset:35840
	ds_read_b128 v[204:207], v171 offset:36864
	ds_read_b128 v[208:211], v171 offset:37888
	ds_read_b128 v[212:215], v171 offset:38912
	ds_read_b128 v[222:225], v171 offset:39936
	global_load_lds_dwordx4 v[226:227], off
	v_lshl_add_u64 v[226:227], s[94:95], 0, v[134:135]
	s_mov_b32 m0, s53
	s_nop 0
	global_load_lds_dwordx4 v[226:227], off
	s_add_i32 s9, 0, 0x1c000
	v_add_u32_e32 v218, s9, v152
	ds_read_b128 v[226:229], v218
	ds_read_b128 v[230:233], v218 offset:1024
	ds_read_b128 v[234:237], v218 offset:2048
	ds_read_b128 v[238:241], v218 offset:3072
	s_waitcnt vmcnt(8)
	s_waitcnt lgkmcnt(0)
	v_mfma_f32_16x16x32_bf16 v[126:129], v[144:147], v[184:187], v[126:129]
	v_mfma_f32_16x16x32_bf16 v[122:125], v[176:179], v[184:187], v[122:125]
	v_mfma_f32_16x16x32_bf16 v[110:113], v[144:147], v[196:199], v[110:113]
	v_mfma_f32_16x16x32_bf16 v[106:109], v[176:179], v[196:199], v[106:109]
	s_barrier
	s_setprio 1
	v_mfma_f32_16x16x32_bf16 v[94:97], v[144:147], v[204:207], v[94:97]
	v_mfma_f32_16x16x32_bf16 v[90:93], v[176:179], v[204:207], v[90:93]
	v_mfma_f32_16x16x32_bf16 v[78:81], v[144:147], v[212:215], v[78:81]
	v_mfma_f32_16x16x32_bf16 v[74:77], v[176:179], v[212:215], v[74:77]
	v_mfma_f32_16x16x32_bf16 v[126:129], v[172:175], v[188:191], v[126:129]
	v_mfma_f32_16x16x32_bf16 v[122:125], v[180:183], v[188:191], v[122:125]
	v_mfma_f32_16x16x32_bf16 v[110:113], v[172:175], v[200:203], v[110:113]
	v_mfma_f32_16x16x32_bf16 v[106:109], v[180:183], v[200:203], v[106:109]
	v_mfma_f32_16x16x32_bf16 v[94:97], v[172:175], v[208:211], v[94:97]
	v_mfma_f32_16x16x32_bf16 v[90:93], v[180:183], v[208:211], v[90:93]
	v_mfma_f32_16x16x32_bf16 v[78:81], v[172:175], v[222:225], v[78:81]
	v_mfma_f32_16x16x32_bf16 v[74:77], v[180:183], v[222:225], v[74:77]
	v_mfma_f32_16x16x32_bf16 v[118:121], v[226:229], v[184:187], v[118:121]
	v_mfma_f32_16x16x32_bf16 v[114:117], v[234:237], v[184:187], v[114:117]
	v_mfma_f32_16x16x32_bf16 v[102:105], v[226:229], v[196:199], v[102:105]
	v_mfma_f32_16x16x32_bf16 v[98:101], v[234:237], v[196:199], v[98:101]
	v_mfma_f32_16x16x32_bf16 v[86:89], v[226:229], v[204:207], v[86:89]
	v_mfma_f32_16x16x32_bf16 v[82:85], v[234:237], v[204:207], v[82:85]
	v_mfma_f32_16x16x32_bf16 v[70:73], v[226:229], v[212:215], v[70:73]
	v_mfma_f32_16x16x32_bf16 v[66:69], v[234:237], v[212:215], v[66:69]
	v_mfma_f32_16x16x32_bf16 v[118:121], v[230:233], v[188:191], v[118:121]
	v_mfma_f32_16x16x32_bf16 v[114:117], v[238:241], v[188:191], v[114:117]
	v_mfma_f32_16x16x32_bf16 v[102:105], v[230:233], v[200:203], v[102:105]
	v_mfma_f32_16x16x32_bf16 v[98:101], v[238:241], v[200:203], v[98:101]
	v_mfma_f32_16x16x32_bf16 v[86:89], v[230:233], v[208:211], v[86:89]
	v_mfma_f32_16x16x32_bf16 v[82:85], v[238:241], v[208:211], v[82:85]
	v_mfma_f32_16x16x32_bf16 v[70:73], v[230:233], v[222:225], v[70:73]
	v_mfma_f32_16x16x32_bf16 v[66:69], v[238:241], v[222:225], v[66:69]
	s_setprio 0
	s_barrier
; __device__ __forceinline__ float pre_get(const Pre& p, int ai, int m, int fr) { return __shfl(p.v[ai], m * 16 + fr); }
; __device__ __forceinline__ float rstd_pre(const float* ss, float v) { return ss ? rsqrtf(v * (1.0f / 2048.0f) + 1e-6f) : 1.0f; }
; #define PG8_STAGE(bufoff, gbase, voff) do { _Pragma("unroll") for (int _i = 0; _i < 2; ++_i) \
;         __builtin_amdgcn_global_load_lds((const unsigned*)((const char*)(gbase) + (voff)[_i]), (LAS unsigned*)(lds + (bufoff) + ldsw + _i * 8192), 16, 0, 0); } while (0)
; #define PG8_LDA(dst, b, h) do { _Pragma("unroll") for (int m = 0; m < 4; ++m) _Pragma("unroll") for (int k = 0; k < 2; ++k) dst[m][k] = *(const LAS bf16x8*)(lds + PG8_SA(b, h) + aoff + m * 2048 + k * 1024); } while (0)
; #define PG8_WAIT_V(n) asm volatile("s_waitcnt vmcnt(" #n ")" ::: "memory")
; #define PG8_WAIT_L(n) asm volatile("s_waitcnt lgkmcnt(" #n ")" ::: "memory")
; #define PG8_BAR __builtin_amdgcn_s_barrier()
; #define PG8_SCHED __builtin_amdgcn_sched_barrier(0)
; template <class Epi>
; __device__ __forceinline__ void gemm_phase(LAS unsigned char* lds, const Gemm g, const Sched& S, const Epi& E) {
;     ...
;             PG8_LDA(At, 1, 1); PG8_STAGE(PG8_SA(1, 0), a3, voffA);
;             PG8_BAR; PG8_WAIT_L(0); PG8_MMA(1, 0, At, B0); PG8_BAR; PG8_SCHED;
;             PG8_STAGE(PG8_SB(1, 1), b3 + hstepB, voffB);
;             PG8_WAIT_V(6); PG8_BAR; PG8_MMA(1, 1, At, B1); PG8_BAR;
;         }
;     __device__ __forceinline__ void operator()(const Acc& acc, const Unit& u, int wr, int wc, int fr, int fq, const Pre& pre) const {
;     ...
;         for (int ai = 0; ai < 2; ++ai)
; #pragma unroll
;             for (int m = 0; m < 4; ++m) rs[ai][m] = rstd_pre(ss, pre_get(pre, ai, m, fr));
; #pragma unroll
;         for (int ai = 0; ai < 2; ++ai)
; #pragma unroll
;             for (int m = 0; m < 4; ++m) { float mx = -INFINITY;
; #pragma unroll
;                 for (int bj = 0; bj < 2; ++bj)
; #pragma unroll
;                     for (int n = 0; n < 2; ++n) { const f32x4 a = acc[ai][bj][m][n]; mx = fmaxf(mx, fmaxf(fmaxf(a[0], a[1]), fmaxf(a[2], a[3]))); }
;                 mx *= rs[ai][m];
;                 mx = fmaxf(mx, __shfl_xor(mx, 16)); mx = fmaxf(mx, __shfl_xor(mx, 32));
;                 if (fq == 0) X[(ai * 128 + wr * 64 + m * 16 + fr) * 4 + wc] = mx; }
	s_add_i32 s8, s8, s39
	v_lshl_add_u64 v[148:149], v[148:149], 0, s[60:61]
	s_mov_b32 m0, s8
	s_nop 0
	global_load_lds_dwordx4 v[148:149], off
	v_lshl_add_u64 v[148:149], v[192:193], 0, s[60:61]
	s_add_i32 m0, s8, 0x2000
	s_nop 0
	global_load_lds_dwordx4 v[148:149], off
	s_mov_b32 m0, s67
	v_lshl_add_u64 v[148:149], v[194:195], 0, s[60:61]
	ds_read_b128 v[184:187], v171 offset:49152
	ds_read_b128 v[188:191], v171 offset:50176
	ds_read_b128 v[196:199], v171 offset:51200
	ds_read_b128 v[200:203], v171 offset:52224
	ds_read_b128 v[204:207], v171 offset:53248
	ds_read_b128 v[208:211], v171 offset:54272
	ds_read_b128 v[212:215], v171 offset:55296
	ds_read_b128 v[222:225], v171 offset:56320
	global_load_lds_dwordx4 v[148:149], off
	v_lshl_add_u64 v[148:149], v[216:217], 0, s[60:61]
	s_mov_b32 m0, s2
	s_nop 0
	global_load_lds_dwordx4 v[148:149], off
	s_add_i32 s8, s9, s39
	v_lshl_add_u64 v[148:149], v[242:243], 0, s[60:61]
	s_mov_b32 m0, s8
	s_nop 0
	global_load_lds_dwordx4 v[148:149], off
	v_lshl_add_u64 v[148:149], v[244:245], 0, s[60:61]
	s_add_i32 m0, s8, 0x2000
	s_nop 0
	global_load_lds_dwordx4 v[148:149], off
	s_waitcnt vmcnt(8)
	s_waitcnt lgkmcnt(0)
	v_mfma_f32_16x16x32_bf16 v[62:65], v[144:147], v[184:187], v[62:65]
	v_mfma_f32_16x16x32_bf16 v[58:61], v[176:179], v[184:187], v[58:61]
	v_mfma_f32_16x16x32_bf16 v[50:53], v[144:147], v[196:199], v[50:53]
	v_mfma_f32_16x16x32_bf16 v[42:45], v[176:179], v[196:199], v[42:45]
	s_barrier
	s_setprio 1
	v_mfma_f32_16x16x32_bf16 v[34:37], v[144:147], v[204:207], v[34:37]
	v_mfma_f32_16x16x32_bf16 v[26:29], v[176:179], v[204:207], v[26:29]
	v_mfma_f32_16x16x32_bf16 v[18:21], v[144:147], v[212:215], v[18:21]
	v_mfma_f32_16x16x32_bf16 v[10:13], v[176:179], v[212:215], v[10:13]
	v_mfma_f32_16x16x32_bf16 v[62:65], v[172:175], v[188:191], v[62:65]
	v_mfma_f32_16x16x32_bf16 v[58:61], v[180:183], v[188:191], v[58:61]
	v_mfma_f32_16x16x32_bf16 v[50:53], v[172:175], v[200:203], v[50:53]
	v_mfma_f32_16x16x32_bf16 v[42:45], v[180:183], v[200:203], v[42:45]
	v_mfma_f32_16x16x32_bf16 v[34:37], v[172:175], v[208:211], v[34:37]
	v_mfma_f32_16x16x32_bf16 v[26:29], v[180:183], v[208:211], v[26:29]
	v_mfma_f32_16x16x32_bf16 v[18:21], v[172:175], v[222:225], v[18:21]
	v_mfma_f32_16x16x32_bf16 v[10:13], v[180:183], v[222:225], v[10:13]
	v_mfma_f32_16x16x32_bf16 v[54:57], v[226:229], v[184:187], v[54:57]
	v_mfma_f32_16x16x32_bf16 v[46:49], v[234:237], v[184:187], v[46:49]
	v_mfma_f32_16x16x32_bf16 v[38:41], v[226:229], v[196:199], v[38:41]
	v_mfma_f32_16x16x32_bf16 v[30:33], v[234:237], v[196:199], v[30:33]
	v_mfma_f32_16x16x32_bf16 v[22:25], v[226:229], v[204:207], v[22:25]
	v_mfma_f32_16x16x32_bf16 v[14:17], v[234:237], v[204:207], v[14:17]
	v_mfma_f32_16x16x32_bf16 v[6:9], v[226:229], v[212:215], v[6:9]
	v_mfma_f32_16x16x32_bf16 v[2:5], v[234:237], v[212:215], v[2:5]
	v_mfma_f32_16x16x32_bf16 v[54:57], v[230:233], v[188:191], v[54:57]
	v_mfma_f32_16x16x32_bf16 v[46:49], v[238:241], v[188:191], v[46:49]
	v_mfma_f32_16x16x32_bf16 v[38:41], v[230:233], v[200:203], v[38:41]
	v_mfma_f32_16x16x32_bf16 v[30:33], v[238:241], v[200:203], v[30:33]
	v_mfma_f32_16x16x32_bf16 v[22:25], v[230:233], v[208:211], v[22:25]
	v_mfma_f32_16x16x32_bf16 v[14:17], v[238:241], v[208:211], v[14:17]
	v_mfma_f32_16x16x32_bf16 v[6:9], v[230:233], v[222:225], v[6:9]
	v_mfma_f32_16x16x32_bf16 v[2:5], v[238:241], v[222:225], v[2:5]
	s_setprio 0
	s_add_u32 s92, s92, 0x100
	s_addc_u32 s93, s93, 0
	s_add_u32 s34, s34, 0x100
	s_addc_u32 s35, s35, 0
	s_cmp_ge_u32 s14, s73
	s_mov_b32 s66, s14
	s_barrier
	s_cbranch_scc0 .LBB0_400
	v_and_b32_e32 v144, 64, v220
	v_or_b32_e32 v144, v144, v150
	v_lshlrev_b32_e32 v172, 2, v144
	ds_bpermute_b32 v145, v172, v143
	ds_bpermute_b32 v144, v172, v143 offset:64
	s_mov_b32 s8, 0x3a000000
	v_mov_b32_e32 v232, 0x358637bd
	s_mov_b32 s97, 0x800000
	ds_bpermute_b32 v147, v172, v143 offset:128
	s_waitcnt lgkmcnt(0)
	v_pk_fma_f32 v[148:149], v[144:145], s[8:9], v[232:233] op_sel_hi:[1,0,0]
	ds_bpermute_b32 v146, v172, v143 offset:192
	v_mul_f32_e32 v143, 0x4b800000, v149
	v_cmp_gt_f32_e32 vcc, s97, v149
	v_max_f32_e32 v174, v128, v128
	v_max_f32_e32 v175, v124, v124
	v_cndmask_b32_e32 v143, v149, v143, vcc
	v_rsq_f32_e32 v149, v143
	v_max_f32_e32 v176, v116, v116
	ds_bpermute_b32 v145, v172, v142
	ds_bpermute_b32 v144, v172, v142 offset:64
	v_mul_f32_e32 v173, 0x45800000, v149
	v_cndmask_b32_e32 v149, v149, v173, vcc
	v_max_f32_e32 v173, v129, v129
	v_max_f32_e32 v173, v174, v173
	v_max_f32_e32 v174, v125, v125
	v_max_f32_e32 v174, v175, v174
	v_max3_f32 v173, v126, v127, v173
	v_max3_f32 v174, v122, v123, v174
	v_max3_f32 v173, v173, s72, v174
	v_max_f32_e32 v174, v121, v121
	v_max_f32_e32 v175, v120, v120
	v_max_f32_e32 v174, v175, v174
	v_max_f32_e32 v175, v117, v117
	v_max_f32_e32 v175, v176, v175
	v_cmp_lt_i32_e32 vcc, v221, v247
	v_max3_f32 v174, v118, v119, v174
	v_max3_f32 v175, v114, v115, v175
	v_cndmask_b32_e64 v177, v149, 1.0, s[80:81]
	v_cndmask_b32_e32 v149, v220, v221, vcc
	v_max3_f32 v173, v173, v174, v175
	v_lshlrev_b32_e32 v149, 2, v149
	v_mul_f32_e32 v173, v173, v177
	ds_bpermute_b32 v174, v149, v173
	v_cmp_lt_i32_e32 vcc, v248, v247
	ds_bpermute_b32 v143, v172, v142 offset:128
	ds_bpermute_b32 v142, v172, v142 offset:192
	v_cndmask_b32_e32 v172, v220, v248, vcc
	s_waitcnt lgkmcnt(0)
	v_max_f32_e32 v174, v174, v174
	v_lshlrev_b32_e32 v172, 2, v172
	v_max_f32_e32 v173, v173, v174
	ds_bpermute_b32 v174, v172, v173
	v_cmp_gt_f32_e32 vcc, s97, v148
	v_add_u32_e32 v178, s51, v154
	v_readfirstlane_b32 s98, v219
	s_nop 1
	s_bitcmp1_b32 s98, 8
	s_cbranch_scc1 .Lresync_x_400
	s_barrier
.Lresync_x_400:
	s_and_saveexec_b64 s[92:93], s[0:1]
	s_cbranch_execz .LBB0_403
	s_waitcnt lgkmcnt(0)
	v_max_f32_e32 v174, v174, v174
	v_max_f32_e32 v173, v173, v173
	v_max_f32_e32 v173, v173, v174
	ds_write_b32 v178, v173

; #define PG8_STAGE(bufoff, gbase, voff) do { _Pragma("unroll") for (int _i = 0; _i < 2; ++_i) \
;         __builtin_amdgcn_global_load_lds((const unsigned*)((const char*)(gbase) + (voff)[_i]), (LAS unsigned*)(lds + (bufoff) + ldsw + _i * 8192), 16, 0, 0); } while (0)
; #define PG8_LDA(dst, b, h) do { _Pragma("unroll") for (int m = 0; m < 4; ++m) _Pragma("unroll") for (int k = 0; k < 2; ++k) dst[m][k] = *(const LAS bf16x8*)(lds + PG8_SA(b, h) + aoff + m * 2048 + k * 1024); } while (0)
; #define PG8_LDB(dst, b, h) do { _Pragma("unroll") for (int n = 0; n < 2; ++n) _Pragma("unroll") for (int k = 0; k < 2; ++k) dst[n][k] = *(const LAS bf16x8*)(lds + PG8_SB(b, h) + boff + n * 2048 + k * 1024); } while (0)
; #define PG8_MMA(ai, bj, At, Bt) do { __builtin_amdgcn_s_setprio(1); _Pragma("unroll") for (int m = 0; m < 4; ++m) _Pragma("unroll") for (int n = 0; n < 2; ++n) _Pragma("unroll") for (int k = 0; k < 2; ++k) \
;         acc[ai][bj][m][n] = __builtin_amdgcn_mfma_f32_16x16x32_bf16(Bt[n][k], At[m][k], acc[ai][bj][m][n], 0, 0, 0); __builtin_amdgcn_s_setprio(0); } while (0)
; #define PG8_WAIT_V(n) asm volatile("s_waitcnt vmcnt(" #n ")" ::: "memory")
; #define PG8_WAIT_L(n) asm volatile("s_waitcnt lgkmcnt(" #n ")" ::: "memory")
; template <class Epi>
; __device__ __forceinline__ void gemm_phase(LAS unsigned char* lds, const Gemm g, const Sched& S, const Epi& E) {
;     ...
;         for (int t = 0; t < nt; t += 2) {
;             const bool last = (t == nt - 2);
;             const char* a1 = cA + (size_t)(t + 1) * kstep;
;             const char* a2 = last ? nA : cA + (size_t)(t + 2) * kstep; const char* b2 = last ? nB : cB + (size_t)(t + 2) * kstep;
;             const char* a3 = a2 + kstep; const char* b3 = b2 + kstep;
;             PG8_LDB(B0, 0, 0); PG8_SCHED; PG8_LDA(At, 0, 0); PG8_STAGE(PG8_SA(1, 1), a1 + hstepA, voffA);
;             PG8_WAIT_L(8); PG8_BAR; PG8_WAIT_L(0); PG8_MMA(0, 0, At, B0); PG8_BAR; PG8_SCHED;
;             PG8_LDB(B1, 0, 1); PG8_STAGE(PG8_SB(0, 0), b2, voffB);
;             PG8_BAR; PG8_WAIT_L(0); PG8_MMA(0, 1, At, B1); PG8_BAR;
;             PG8_LDA(At, 0, 1); PG8_STAGE(PG8_SA(0, 0), a2, voffA);
;             PG8_BAR; PG8_WAIT_L(0); PG8_MMA(1, 0, At, B0); PG8_BAR; PG8_SCHED;
;             PG8_STAGE(PG8_SB(0, 1), b2 + hstepB, voffB);
;             PG8_WAIT_V(6); PG8_BAR; PG8_MMA(1, 1, At, B1); PG8_BAR;
.Lresync_y_461:
.LBB0_461:
	s_add_i32 s14, s88, 2
	s_add_u32 s8, s4, 0x80
	s_addc_u32 s9, s5, 0
	s_add_i32 s15, 0, 0x10000
	v_add_u32_e32 v114, s15, v211
	ds_read_b128 v[82:85], v114
	ds_read_b128 v[94:97], v114 offset:1024
	ds_read_b128 v[98:101], v114 offset:2048
	ds_read_b128 v[114:117], v114 offset:3072
	s_cmp_eq_u32 s42, s88
	s_cselect_b32 s88, s57, s8
	s_cselect_b32 s89, s71, s9
	s_cselect_b32 s91, s59, s35
	s_cselect_b32 s90, s72, s34
	v_lshl_add_u64 v[178:179], s[4:5], 0, v[202:203]
	s_add_i32 m0, s24, 0xc000
	ds_read_b128 v[122:125], v213
	ds_read_b128 v[130:133], v213 offset:1024
	ds_read_b128 v[146:149], v213 offset:2048
	ds_read_b128 v[150:153], v213 offset:3072
	ds_read_b128 v[162:165], v213 offset:4096
	ds_read_b128 v[166:169], v213 offset:5120
	ds_read_b128 v[170:173], v213 offset:6144
	ds_read_b128 v[174:177], v213 offset:7168
	global_load_lds_dwordx4 v[178:179], off
	v_lshl_add_u64 v[178:179], s[4:5], 0, v[204:205]
	s_add_i32 m0, s24, 0xe000
	s_nop 0
	global_load_lds_dwordx4 v[178:179], off
	s_add_i32 s8, 0, 0x14000
	v_add_u32_e32 v190, s8, v211
	ds_read_b128 v[178:181], v190
	ds_read_b128 v[182:185], v190 offset:1024
	ds_read_b128 v[186:189], v190 offset:2048
	ds_read_b128 v[190:193], v190 offset:3072
	s_waitcnt vmcnt(8)
	s_waitcnt lgkmcnt(0)
	v_mfma_f32_16x16x32_bf16 v[158:161], v[82:85], v[122:125], v[158:161]
	v_mfma_f32_16x16x32_bf16 v[154:157], v[98:101], v[122:125], v[154:157]
	v_mfma_f32_16x16x32_bf16 v[134:137], v[82:85], v[146:149], v[134:137]
	v_mfma_f32_16x16x32_bf16 v[126:129], v[98:101], v[146:149], v[126:129]
	s_barrier
	s_setprio 1
	v_mfma_f32_16x16x32_bf16 v[106:109], v[82:85], v[162:165], v[106:109]
	v_mfma_f32_16x16x32_bf16 v[102:105], v[98:101], v[162:165], v[102:105]
	v_mfma_f32_16x16x32_bf16 v[78:81], v[82:85], v[170:173], v[78:81]
	v_mfma_f32_16x16x32_bf16 v[74:77], v[98:101], v[170:173], v[74:77]
	v_mfma_f32_16x16x32_bf16 v[158:161], v[94:97], v[130:133], v[158:161]
	v_mfma_f32_16x16x32_bf16 v[154:157], v[114:117], v[130:133], v[154:157]
	v_mfma_f32_16x16x32_bf16 v[134:137], v[94:97], v[150:153], v[134:137]
	v_mfma_f32_16x16x32_bf16 v[126:129], v[114:117], v[150:153], v[126:129]
	v_mfma_f32_16x16x32_bf16 v[106:109], v[94:97], v[166:169], v[106:109]
	v_mfma_f32_16x16x32_bf16 v[102:105], v[114:117], v[166:169], v[102:105]
	v_mfma_f32_16x16x32_bf16 v[78:81], v[94:97], v[174:177], v[78:81]
	v_mfma_f32_16x16x32_bf16 v[74:77], v[114:117], v[174:177], v[74:77]
	v_mfma_f32_16x16x32_bf16 v[142:145], v[178:181], v[122:125], v[142:145]
	v_mfma_f32_16x16x32_bf16 v[118:121], v[178:181], v[146:149], v[118:121]
	v_mfma_f32_16x16x32_bf16 v[110:113], v[186:189], v[146:149], v[110:113]
	v_mfma_f32_16x16x32_bf16 v[90:93], v[178:181], v[162:165], v[90:93]
	v_mfma_f32_16x16x32_bf16 v[86:89], v[186:189], v[162:165], v[86:89]
	v_mfma_f32_16x16x32_bf16 v[70:73], v[178:181], v[170:173], v[70:73]
	v_mfma_f32_16x16x32_bf16 v[66:69], v[186:189], v[170:173], v[66:69]
	v_mfma_f32_16x16x32_bf16 v[142:145], v[182:185], v[130:133], v[142:145]
	v_mfma_f32_16x16x32_bf16 v[122:125], v[186:189], v[122:125], v[138:141]
	v_mfma_f32_16x16x32_bf16 v[118:121], v[182:185], v[150:153], v[118:121]
	v_mfma_f32_16x16x32_bf16 v[110:113], v[190:193], v[150:153], v[110:113]
	v_mfma_f32_16x16x32_bf16 v[90:93], v[182:185], v[166:169], v[90:93]
	v_mfma_f32_16x16x32_bf16 v[86:89], v[190:193], v[166:169], v[86:89]
	v_mfma_f32_16x16x32_bf16 v[70:73], v[182:185], v[174:177], v[70:73]
	v_mfma_f32_16x16x32_bf16 v[66:69], v[190:193], v[174:177], v[66:69]
	v_mfma_f32_16x16x32_bf16 v[122:125], v[190:193], v[130:133], v[122:125]
	s_setprio 0
	s_barrier
	s_add_i32 s9, s15, s3
	v_lshl_add_u64 v[194:195], s[90:91], 0, v[0:1]
	s_mov_b32 m0, s9
	s_nop 0
	global_load_lds_dwordx4 v[194:195], off
	v_lshl_add_u64 v[206:207], s[90:91], 0, v[200:201]
	s_add_i32 m0, s9, 0x2000
	s_nop 0
	global_load_lds_dwordx4 v[206:207], off
	s_mov_b32 m0, s24
	v_lshl_add_u64 v[208:209], s[88:89], 0, v[196:197]
	ds_read_b128 v[130:133], v213 offset:16384
	ds_read_b128 v[138:141], v213 offset:17408
	ds_read_b128 v[146:149], v213 offset:18432
	ds_read_b128 v[150:153], v213 offset:19456
	ds_read_b128 v[162:165], v213 offset:20480
	ds_read_b128 v[166:169], v213 offset:21504
	ds_read_b128 v[170:173], v213 offset:22528
	ds_read_b128 v[174:177], v213 offset:23552
	global_load_lds_dwordx4 v[208:209], off
	v_lshl_add_u64 v[214:215], s[88:89], 0, v[198:199]
	s_mov_b32 m0, s33
	s_nop 0
	global_load_lds_dwordx4 v[214:215], off
	s_add_u32 s90, s90, s78
	s_addc_u32 s91, s91, s79
	s_add_i32 s8, s8, s3
	v_lshl_add_u64 v[216:217], s[90:91], 0, v[0:1]
	s_mov_b32 m0, s8
	v_lshl_add_u64 v[222:223], s[90:91], 0, v[200:201]
	global_load_lds_dwordx4 v[216:217], off
	s_add_i32 m0, s8, 0x2000
	s_nop 0
	global_load_lds_dwordx4 v[222:223], off
	s_waitcnt vmcnt(8)
	s_waitcnt lgkmcnt(0)
	v_mfma_f32_16x16x32_bf16 v[62:65], v[82:85], v[130:133], v[62:65]
	v_mfma_f32_16x16x32_bf16 v[58:61], v[98:101], v[130:133], v[58:61]
	v_mfma_f32_16x16x32_bf16 v[46:49], v[82:85], v[146:149], v[46:49]
	v_mfma_f32_16x16x32_bf16 v[42:45], v[98:101], v[146:149], v[42:45]
	s_barrier
; #define PG8_STAGE(bufoff, gbase, voff) do { _Pragma("unroll") for (int _i = 0; _i < 2; ++_i) \
;         __builtin_amdgcn_global_load_lds((const unsigned*)((const char*)(gbase) + (voff)[_i]), (LAS unsigned*)(lds + (bufoff) + ldsw + _i * 8192), 16, 0, 0); } while (0)
; #define PG8_LDA(dst, b, h) do { _Pragma("unroll") for (int m = 0; m < 4; ++m) _Pragma("unroll") for (int k = 0; k < 2; ++k) dst[m][k] = *(const LAS bf16x8*)(lds + PG8_SA(b, h) + aoff + m * 2048 + k * 1024); } while (0)
; #define PG8_LDB(dst, b, h) do { _Pragma("unroll") for (int n = 0; n < 2; ++n) _Pragma("unroll") for (int k = 0; k < 2; ++k) dst[n][k] = *(const LAS bf16x8*)(lds + PG8_SB(b, h) + boff + n * 2048 + k * 1024); } while (0)
; #define PG8_MMA(ai, bj, At, Bt) do { __builtin_amdgcn_s_setprio(1); _Pragma("unroll") for (int m = 0; m < 4; ++m) _Pragma("unroll") for (int n = 0; n < 2; ++n) _Pragma("unroll") for (int k = 0; k < 2; ++k) \
;         acc[ai][bj][m][n] = __builtin_amdgcn_mfma_f32_16x16x32_bf16(Bt[n][k], At[m][k], acc[ai][bj][m][n], 0, 0, 0); __builtin_amdgcn_s_setprio(0); } while (0)
; #define PG8_WAIT_V(n) asm volatile("s_waitcnt vmcnt(" #n ")" ::: "memory")
; #define PG8_WAIT_L(n) asm volatile("s_waitcnt lgkmcnt(" #n ")" ::: "memory")
; #define PG8_BAR __builtin_amdgcn_s_barrier()
; #define PG8_SCHED __builtin_amdgcn_sched_barrier(0)
; template <class Epi>
; __device__ __forceinline__ void gemm_phase(LAS unsigned char* lds, const Gemm g, const Sched& S, const Epi& E) {
;     ...
;             PG8_BAR; PG8_WAIT_L(0); PG8_MMA(1, 0, At, B0); PG8_BAR; PG8_SCHED;
;             PG8_STAGE(PG8_SB(0, 1), b2 + hstepB, voffB);
;             PG8_WAIT_V(6); PG8_BAR; PG8_MMA(1, 1, At, B1); PG8_BAR;
;             PG8_LDB(B0, 1, 0); PG8_SCHED; PG8_LDA(At, 1, 0); PG8_STAGE(PG8_SA(0, 1), a2 + hstepA, voffA);
;             PG8_WAIT_L(8); PG8_BAR; PG8_WAIT_L(0); PG8_MMA(0, 0, At, B0); PG8_BAR; PG8_SCHED;
;             PG8_LDB(B1, 1, 1); PG8_STAGE(PG8_SB(1, 0), b3, voffB);
;             PG8_BAR; PG8_WAIT_L(0); PG8_MMA(0, 1, At, B1); PG8_BAR;
	s_setprio 1
	v_mfma_f32_16x16x32_bf16 v[30:33], v[82:85], v[162:165], v[30:33]
	v_mfma_f32_16x16x32_bf16 v[26:29], v[98:101], v[162:165], v[26:29]
	v_mfma_f32_16x16x32_bf16 v[14:17], v[82:85], v[170:173], v[14:17]
	v_mfma_f32_16x16x32_bf16 v[10:13], v[98:101], v[170:173], v[10:13]
	v_mfma_f32_16x16x32_bf16 v[62:65], v[94:97], v[138:141], v[62:65]
	v_mfma_f32_16x16x32_bf16 v[58:61], v[114:117], v[138:141], v[58:61]
	v_mfma_f32_16x16x32_bf16 v[46:49], v[94:97], v[150:153], v[46:49]
	v_mfma_f32_16x16x32_bf16 v[42:45], v[114:117], v[150:153], v[42:45]
	v_mfma_f32_16x16x32_bf16 v[30:33], v[94:97], v[166:169], v[30:33]
	v_mfma_f32_16x16x32_bf16 v[26:29], v[114:117], v[166:169], v[26:29]
	v_mfma_f32_16x16x32_bf16 v[14:17], v[94:97], v[174:177], v[14:17]
	v_mfma_f32_16x16x32_bf16 v[10:13], v[114:117], v[174:177], v[10:13]
	v_mfma_f32_16x16x32_bf16 v[54:57], v[178:181], v[130:133], v[54:57]
	v_mfma_f32_16x16x32_bf16 v[50:53], v[186:189], v[130:133], v[50:53]
	v_mfma_f32_16x16x32_bf16 v[38:41], v[178:181], v[146:149], v[38:41]
	v_mfma_f32_16x16x32_bf16 v[34:37], v[186:189], v[146:149], v[34:37]
	v_mfma_f32_16x16x32_bf16 v[22:25], v[178:181], v[162:165], v[22:25]
	v_mfma_f32_16x16x32_bf16 v[18:21], v[186:189], v[162:165], v[18:21]
	v_mfma_f32_16x16x32_bf16 v[6:9], v[178:181], v[170:173], v[6:9]
	v_mfma_f32_16x16x32_bf16 v[2:5], v[186:189], v[170:173], v[2:5]
	v_mfma_f32_16x16x32_bf16 v[54:57], v[182:185], v[138:141], v[54:57]
	v_mfma_f32_16x16x32_bf16 v[50:53], v[190:193], v[138:141], v[50:53]
	v_mfma_f32_16x16x32_bf16 v[38:41], v[182:185], v[150:153], v[38:41]
	v_mfma_f32_16x16x32_bf16 v[34:37], v[190:193], v[150:153], v[34:37]
	v_mfma_f32_16x16x32_bf16 v[22:25], v[182:185], v[166:169], v[22:25]
	v_mfma_f32_16x16x32_bf16 v[18:21], v[190:193], v[166:169], v[18:21]
	v_mfma_f32_16x16x32_bf16 v[6:9], v[182:185], v[174:177], v[6:9]
	v_mfma_f32_16x16x32_bf16 v[2:5], v[190:193], v[174:177], v[2:5]
	s_setprio 0
	s_barrier
	s_add_i32 s8, 0, 0x18000
	v_add_u32_e32 v114, s8, v211
	ds_read_b128 v[82:85], v114
	ds_read_b128 v[94:97], v114 offset:1024
	ds_read_b128 v[98:101], v114 offset:2048
	ds_read_b128 v[114:117], v114 offset:3072
	s_add_u32 s88, s88, s36
	s_addc_u32 s89, s89, s37
	s_mov_b32 m0, s38
	v_lshl_add_u64 v[178:179], s[88:89], 0, v[196:197]
	ds_read_b128 v[130:133], v213 offset:32768
	ds_read_b128 v[138:141], v213 offset:33792
	ds_read_b128 v[146:149], v213 offset:34816
	ds_read_b128 v[150:153], v213 offset:35840
	ds_read_b128 v[162:165], v213 offset:36864
	ds_read_b128 v[166:169], v213 offset:37888
	ds_read_b128 v[170:173], v213 offset:38912
	ds_read_b128 v[174:177], v213 offset:39936
	global_load_lds_dwordx4 v[178:179], off
	v_lshl_add_u64 v[178:179], s[88:89], 0, v[198:199]
	s_mov_b32 m0, s39
	s_nop 0
	global_load_lds_dwordx4 v[178:179], off
	s_add_i32 s9, 0, 0x1c000
	v_add_u32_e32 v190, s9, v211
	ds_read_b128 v[178:181], v190
	ds_read_b128 v[182:185], v190 offset:1024
	ds_read_b128 v[186:189], v190 offset:2048
	ds_read_b128 v[190:193], v190 offset:3072
	s_waitcnt vmcnt(8)
	s_waitcnt lgkmcnt(0)
	v_mfma_f32_16x16x32_bf16 v[158:161], v[82:85], v[130:133], v[158:161]
	v_mfma_f32_16x16x32_bf16 v[154:157], v[98:101], v[130:133], v[154:157]
	v_mfma_f32_16x16x32_bf16 v[134:137], v[82:85], v[146:149], v[134:137]
	v_mfma_f32_16x16x32_bf16 v[126:129], v[98:101], v[146:149], v[126:129]
	s_barrier
	s_setprio 1
	v_mfma_f32_16x16x32_bf16 v[106:109], v[82:85], v[162:165], v[106:109]
	v_mfma_f32_16x16x32_bf16 v[102:105], v[98:101], v[162:165], v[102:105]
	v_mfma_f32_16x16x32_bf16 v[78:81], v[82:85], v[170:173], v[78:81]
	v_mfma_f32_16x16x32_bf16 v[74:77], v[98:101], v[170:173], v[74:77]
	v_mfma_f32_16x16x32_bf16 v[158:161], v[94:97], v[138:141], v[158:161]
	v_mfma_f32_16x16x32_bf16 v[154:157], v[114:117], v[138:141], v[154:157]
	v_mfma_f32_16x16x32_bf16 v[134:137], v[94:97], v[150:153], v[134:137]
	v_mfma_f32_16x16x32_bf16 v[126:129], v[114:117], v[150:153], v[126:129]
	v_mfma_f32_16x16x32_bf16 v[106:109], v[94:97], v[166:169], v[106:109]
	v_mfma_f32_16x16x32_bf16 v[102:105], v[114:117], v[166:169], v[102:105]
	v_mfma_f32_16x16x32_bf16 v[78:81], v[94:97], v[174:177], v[78:81]
	v_mfma_f32_16x16x32_bf16 v[74:77], v[114:117], v[174:177], v[74:77]
	v_mfma_f32_16x16x32_bf16 v[142:145], v[178:181], v[130:133], v[142:145]
	v_mfma_f32_16x16x32_bf16 v[122:125], v[186:189], v[130:133], v[122:125]
	v_mfma_f32_16x16x32_bf16 v[118:121], v[178:181], v[146:149], v[118:121]
	v_mfma_f32_16x16x32_bf16 v[110:113], v[186:189], v[146:149], v[110:113]
	v_mfma_f32_16x16x32_bf16 v[90:93], v[178:181], v[162:165], v[90:93]
	v_mfma_f32_16x16x32_bf16 v[86:89], v[186:189], v[162:165], v[86:89]
	v_mfma_f32_16x16x32_bf16 v[70:73], v[178:181], v[170:173], v[70:73]
	v_mfma_f32_16x16x32_bf16 v[66:69], v[186:189], v[170:173], v[66:69]
	v_mfma_f32_16x16x32_bf16 v[142:145], v[182:185], v[138:141], v[142:145]
	v_mfma_f32_16x16x32_bf16 v[138:141], v[190:193], v[138:141], v[122:125]
	v_mfma_f32_16x16x32_bf16 v[118:121], v[182:185], v[150:153], v[118:121]
	v_mfma_f32_16x16x32_bf16 v[110:113], v[190:193], v[150:153], v[110:113]
	v_mfma_f32_16x16x32_bf16 v[90:93], v[182:185], v[166:169], v[90:93]
	v_mfma_f32_16x16x32_bf16 v[86:89], v[190:193], v[166:169], v[86:89]
	v_mfma_f32_16x16x32_bf16 v[70:73], v[182:185], v[174:177], v[70:73]
	v_mfma_f32_16x16x32_bf16 v[66:69], v[190:193], v[174:177], v[66:69]
	s_setprio 0
	s_barrier
; #define PG8_STAGE(bufoff, gbase, voff) do { _Pragma("unroll") for (int _i = 0; _i < 2; ++_i) \
;         __builtin_amdgcn_global_load_lds((const unsigned*)((const char*)(gbase) + (voff)[_i]), (LAS unsigned*)(lds + (bufoff) + ldsw + _i * 8192), 16, 0, 0); } while (0)
; #define PG8_LDA(dst, b, h) do { _Pragma("unroll") for (int m = 0; m < 4; ++m) _Pragma("unroll") for (int k = 0; k < 2; ++k) dst[m][k] = *(const LAS bf16x8*)(lds + PG8_SA(b, h) + aoff + m * 2048 + k * 1024); } while (0)
; #define PG8_MMA(ai, bj, At, Bt) do { __builtin_amdgcn_s_setprio(1); _Pragma("unroll") for (int m = 0; m < 4; ++m) _Pragma("unroll") for (int n = 0; n < 2; ++n) _Pragma("unroll") for (int k = 0; k < 2; ++k) \
;         acc[ai][bj][m][n] = __builtin_amdgcn_mfma_f32_16x16x32_bf16(Bt[n][k], At[m][k], acc[ai][bj][m][n], 0, 0, 0); __builtin_amdgcn_s_setprio(0); } while (0)
; #define PG8_WAIT_V(n) asm volatile("s_waitcnt vmcnt(" #n ")" ::: "memory")
; #define PG8_WAIT_L(n) asm volatile("s_waitcnt lgkmcnt(" #n ")" ::: "memory")
; #define PG8_BAR __builtin_amdgcn_s_barrier()
; #define PG8_SCHED __builtin_amdgcn_sched_barrier(0)
; template <class Epi>
; __device__ __forceinline__ void gemm_phase(LAS unsigned char* lds, const Gemm g, const Sched& S, const Epi& E) {
;     ...
;             PG8_LDA(At, 1, 1); PG8_STAGE(PG8_SA(1, 0), a3, voffA);
;             PG8_BAR; PG8_WAIT_L(0); PG8_MMA(1, 0, At, B0); PG8_BAR; PG8_SCHED;
;             PG8_STAGE(PG8_SB(1, 1), b3 + hstepB, voffB);
;             PG8_WAIT_V(6); PG8_BAR; PG8_MMA(1, 1, At, B1); PG8_BAR;
;         }
;     __device__ __forceinline__ void operator()(const Acc& acc, const Unit& u, int wr, int wc, int fr, int fq, const Pre& pre) const {
;         const int row0 = u.pm * 256 + wr * 64 + fr, col0 = u.pn * 256 + wc * 32 + 8 * fq;
; #pragma unroll
;         for (int ai = 0; ai < 2; ++ai) {
;             u32x4 gw[4][2], pw[4][2];
; #pragma unroll
;             for (int m = 0; m < 4; ++m)
; #pragma unroll
;                 for (int bj = 0; bj < 2; ++bj) { const size_t off = (size_t)(row0 + ai * 128 + m * 16) * ldc + col0 + bj * 128;
;                     gw[m][bj] = *(const u32x4*)(gate + off); if (add) pw[m][bj] = *(const u32x4*)(O + off); }
	s_add_i32 s8, s8, s3
	v_lshl_add_u64 v[194:195], v[194:195], 0, s[60:61]
	s_mov_b32 m0, s8
	s_nop 0
	global_load_lds_dwordx4 v[194:195], off
	v_lshl_add_u64 v[194:195], v[206:207], 0, s[60:61]
	s_add_i32 m0, s8, 0x2000
	s_nop 0
	global_load_lds_dwordx4 v[194:195], off
	s_mov_b32 m0, s40
	v_lshl_add_u64 v[194:195], v[208:209], 0, s[60:61]
	ds_read_b128 v[122:125], v213 offset:49152
	ds_read_b128 v[130:133], v213 offset:50176
	ds_read_b128 v[146:149], v213 offset:51200
	ds_read_b128 v[150:153], v213 offset:52224
	ds_read_b128 v[162:165], v213 offset:53248
	ds_read_b128 v[166:169], v213 offset:54272
	ds_read_b128 v[170:173], v213 offset:55296
	ds_read_b128 v[174:177], v213 offset:56320
	global_load_lds_dwordx4 v[194:195], off
	v_lshl_add_u64 v[194:195], v[214:215], 0, s[60:61]
	s_mov_b32 m0, s41
	s_nop 0
	global_load_lds_dwordx4 v[194:195], off
	s_add_i32 s8, s9, s3
	v_lshl_add_u64 v[194:195], v[216:217], 0, s[60:61]
	s_mov_b32 m0, s8
	s_nop 0
	global_load_lds_dwordx4 v[194:195], off
	v_lshl_add_u64 v[194:195], v[222:223], 0, s[60:61]
	s_add_i32 m0, s8, 0x2000
	s_nop 0
	global_load_lds_dwordx4 v[194:195], off
	s_waitcnt vmcnt(8)
	s_waitcnt lgkmcnt(0)
	v_mfma_f32_16x16x32_bf16 v[62:65], v[82:85], v[122:125], v[62:65]
	v_mfma_f32_16x16x32_bf16 v[58:61], v[98:101], v[122:125], v[58:61]
	v_mfma_f32_16x16x32_bf16 v[46:49], v[82:85], v[146:149], v[46:49]
	v_mfma_f32_16x16x32_bf16 v[42:45], v[98:101], v[146:149], v[42:45]
	s_barrier
	s_setprio 1
	v_mfma_f32_16x16x32_bf16 v[30:33], v[82:85], v[162:165], v[30:33]
	v_mfma_f32_16x16x32_bf16 v[26:29], v[98:101], v[162:165], v[26:29]
	v_mfma_f32_16x16x32_bf16 v[14:17], v[82:85], v[170:173], v[14:17]
	v_mfma_f32_16x16x32_bf16 v[10:13], v[98:101], v[170:173], v[10:13]
	v_mfma_f32_16x16x32_bf16 v[62:65], v[94:97], v[130:133], v[62:65]
	v_mfma_f32_16x16x32_bf16 v[58:61], v[114:117], v[130:133], v[58:61]
	v_mfma_f32_16x16x32_bf16 v[46:49], v[94:97], v[150:153], v[46:49]
	v_mfma_f32_16x16x32_bf16 v[42:45], v[114:117], v[150:153], v[42:45]
	v_mfma_f32_16x16x32_bf16 v[30:33], v[94:97], v[166:169], v[30:33]
	v_mfma_f32_16x16x32_bf16 v[26:29], v[114:117], v[166:169], v[26:29]
	v_mfma_f32_16x16x32_bf16 v[14:17], v[94:97], v[174:177], v[14:17]
	v_mfma_f32_16x16x32_bf16 v[10:13], v[114:117], v[174:177], v[10:13]
	v_mfma_f32_16x16x32_bf16 v[54:57], v[178:181], v[122:125], v[54:57]
	v_mfma_f32_16x16x32_bf16 v[50:53], v[186:189], v[122:125], v[50:53]
	v_mfma_f32_16x16x32_bf16 v[38:41], v[178:181], v[146:149], v[38:41]
	v_mfma_f32_16x16x32_bf16 v[34:37], v[186:189], v[146:149], v[34:37]
	v_mfma_f32_16x16x32_bf16 v[22:25], v[178:181], v[162:165], v[22:25]
	v_mfma_f32_16x16x32_bf16 v[18:21], v[186:189], v[162:165], v[18:21]
	v_mfma_f32_16x16x32_bf16 v[6:9], v[178:181], v[170:173], v[6:9]
	v_mfma_f32_16x16x32_bf16 v[2:5], v[186:189], v[170:173], v[2:5]
	v_mfma_f32_16x16x32_bf16 v[54:57], v[182:185], v[130:133], v[54:57]
	v_mfma_f32_16x16x32_bf16 v[50:53], v[190:193], v[130:133], v[50:53]
	v_mfma_f32_16x16x32_bf16 v[38:41], v[182:185], v[150:153], v[38:41]
	v_mfma_f32_16x16x32_bf16 v[34:37], v[190:193], v[150:153], v[34:37]
	v_mfma_f32_16x16x32_bf16 v[22:25], v[182:185], v[166:169], v[22:25]
	v_mfma_f32_16x16x32_bf16 v[18:21], v[190:193], v[166:169], v[18:21]
	v_mfma_f32_16x16x32_bf16 v[6:9], v[182:185], v[174:177], v[6:9]
	v_mfma_f32_16x16x32_bf16 v[2:5], v[190:193], v[174:177], v[2:5]
	s_setprio 0
	s_add_u32 s4, s4, 0x100
	s_addc_u32 s5, s5, 0
	s_add_u32 s34, s34, 0x100
	s_addc_u32 s35, s35, 0
	s_cmp_ge_u32 s14, s73
	s_mov_b32 s88, s14
	s_barrier
	s_cbranch_scc0 .LBB0_461
	v_lshl_add_u32 v214, s67, 8, v210
	v_lshl_or_b32 v206, s55, 8, v212
	v_ashrrev_i32_e32 v207, 31, v206
	v_ashrrev_i32_e32 v82, 31, v214
	v_mul_lo_u32 v215, s12, v82
	v_mul_lo_u32 v238, s13, v214
	v_mad_u64_u32 v[82:83], s[4:5], s12, v214, v[206:207]
	v_add3_u32 v83, v238, v83, v215
	v_lshl_add_u64 v[84:85], v[82:83], 1, s[6:7]
	global_load_dwordx4 v[190:193], v[84:85], off
	v_cndmask_b32_e64 v94, 0, 1, s[76:77]
	v_cmp_ne_u32_e64 s[4:5], 1, v94
	v_readfirstlane_b32 s98, v219
	s_nop 1
	s_bitcmp1_b32 s98, 8
	s_cbranch_scc1 .Lresync_x_461
	s_barrier
.Lresync_x_461:
	s_andn2_b64 vcc, exec, s[76:77]
	v_lshl_add_u64 v[82:83], v[82:83], 1, s[62:63]
	s_cbranch_vccnz .LBB0_464
	global_load_dwordx4 v[150:153], v[82:83], off

; #define PG8_STAGE(bufoff, gbase, voff) do { _Pragma("unroll") for (int _i = 0; _i < 2; ++_i) \
;         __builtin_amdgcn_global_load_lds((const unsigned*)((const char*)(gbase) + (voff)[_i]), (LAS unsigned*)(lds + (bufoff) + ldsw + _i * 8192), 16, 0, 0); } while (0)
; #define PG8_LDA(dst, b, h) do { _Pragma("unroll") for (int m = 0; m < 4; ++m) _Pragma("unroll") for (int k = 0; k < 2; ++k) dst[m][k] = *(const LAS bf16x8*)(lds + PG8_SA(b, h) + aoff + m * 2048 + k * 1024); } while (0)
; #define PG8_LDB(dst, b, h) do { _Pragma("unroll") for (int n = 0; n < 2; ++n) _Pragma("unroll") for (int k = 0; k < 2; ++k) dst[n][k] = *(const LAS bf16x8*)(lds + PG8_SB(b, h) + boff + n * 2048 + k * 1024); } while (0)
; #define PG8_MMA(ai, bj, At, Bt) do { __builtin_amdgcn_s_setprio(1); _Pragma("unroll") for (int m = 0; m < 4; ++m) _Pragma("unroll") for (int n = 0; n < 2; ++n) _Pragma("unroll") for (int k = 0; k < 2; ++k) \
;         acc[ai][bj][m][n] = __builtin_amdgcn_mfma_f32_16x16x32_bf16(Bt[n][k], At[m][k], acc[ai][bj][m][n], 0, 0, 0); __builtin_amdgcn_s_setprio(0); } while (0)
; #define PG8_WAIT_V(n) asm volatile("s_waitcnt vmcnt(" #n ")" ::: "memory")
; #define PG8_WAIT_L(n) asm volatile("s_waitcnt lgkmcnt(" #n ")" ::: "memory")
; template <class Epi>
; __device__ __forceinline__ void gemm_phase(LAS unsigned char* lds, const Gemm g, const Sched& S, const Epi& E) {
;     ...
;         for (int t = 0; t < nt; t += 2) {
;             const bool last = (t == nt - 2);
;             const char* a1 = cA + (size_t)(t + 1) * kstep;
;             const char* a2 = last ? nA : cA + (size_t)(t + 2) * kstep; const char* b2 = last ? nB : cB + (size_t)(t + 2) * kstep;
;             const char* a3 = a2 + kstep; const char* b3 = b2 + kstep;
;             PG8_LDB(B0, 0, 0); PG8_SCHED; PG8_LDA(At, 0, 0); PG8_STAGE(PG8_SA(1, 1), a1 + hstepA, voffA);
;             PG8_WAIT_L(8); PG8_BAR; PG8_WAIT_L(0); PG8_MMA(0, 0, At, B0); PG8_BAR; PG8_SCHED;
;             PG8_LDB(B1, 0, 1); PG8_STAGE(PG8_SB(0, 0), b2, voffB);
;             PG8_BAR; PG8_WAIT_L(0); PG8_MMA(0, 1, At, B1); PG8_BAR;
;             PG8_LDA(At, 0, 1); PG8_STAGE(PG8_SA(0, 0), a2, voffA);
;             PG8_BAR; PG8_WAIT_L(0); PG8_MMA(1, 0, At, B0); PG8_BAR; PG8_SCHED;
;             PG8_STAGE(PG8_SB(0, 1), b2 + hstepB, voffB);
;             PG8_WAIT_V(6); PG8_BAR; PG8_MMA(1, 1, At, B1); PG8_BAR;
.Lresync_y_555:
.LBB0_555:
	s_add_i32 s14, s6, 2
	s_add_u32 s8, s4, 0x80
	s_addc_u32 s7, s5, 0
	s_add_i32 s9, 0, 0x10000
	v_add_u32_e32 v160, s9, v156
	ds_read_b128 v[142:145], v160
	ds_read_b128 v[146:149], v160 offset:1024
	ds_read_b128 v[150:153], v160 offset:2048
	ds_read_b128 v[160:163], v160 offset:3072
	s_cmp_eq_u32 s43, s6
	s_cselect_b32 s6, s57, s8
	s_cselect_b32 s7, s55, s7
	s_cselect_b32 s91, s59, s35
	s_cselect_b32 s90, s95, s34
	v_lshl_add_u64 v[192:193], s[4:5], 0, v[136:137]
	s_add_i32 m0, s33, 0xc000
	ds_read_b128 v[164:167], v159
	ds_read_b128 v[168:171], v159 offset:1024
	ds_read_b128 v[172:175], v159 offset:2048
	ds_read_b128 v[176:179], v159 offset:3072
	ds_read_b128 v[180:183], v159 offset:4096
	ds_read_b128 v[184:187], v159 offset:5120
	ds_read_b128 v[188:191], v159 offset:6144
	ds_read_b128 v[196:199], v159 offset:7168
	global_load_lds_dwordx4 v[192:193], off
	v_lshl_add_u64 v[192:193], s[4:5], 0, v[138:139]
	s_add_i32 m0, s33, 0xe000
	s_nop 0
	global_load_lds_dwordx4 v[192:193], off
	s_add_i32 s8, 0, 0x14000
	v_add_u32_e32 v192, s8, v156
	ds_read_b128 v[200:203], v192
	ds_read_b128 v[204:207], v192 offset:1024
	ds_read_b128 v[208:211], v192 offset:2048
	ds_read_b128 v[212:215], v192 offset:3072
	s_waitcnt vmcnt(8)
	s_waitcnt lgkmcnt(0)
	v_mfma_f32_16x16x32_bf16 v[126:129], v[142:145], v[164:167], v[126:129]
	v_mfma_f32_16x16x32_bf16 v[122:125], v[150:153], v[164:167], v[122:125]
	v_mfma_f32_16x16x32_bf16 v[110:113], v[142:145], v[172:175], v[110:113]
	v_mfma_f32_16x16x32_bf16 v[106:109], v[150:153], v[172:175], v[106:109]
	s_barrier
	s_setprio 1
	v_mfma_f32_16x16x32_bf16 v[94:97], v[142:145], v[180:183], v[94:97]
	v_mfma_f32_16x16x32_bf16 v[90:93], v[150:153], v[180:183], v[90:93]
	v_mfma_f32_16x16x32_bf16 v[78:81], v[142:145], v[188:191], v[78:81]
	v_mfma_f32_16x16x32_bf16 v[74:77], v[150:153], v[188:191], v[74:77]
	v_mfma_f32_16x16x32_bf16 v[126:129], v[146:149], v[168:171], v[126:129]
	v_mfma_f32_16x16x32_bf16 v[122:125], v[160:163], v[168:171], v[122:125]
	v_mfma_f32_16x16x32_bf16 v[110:113], v[146:149], v[176:179], v[110:113]
	v_mfma_f32_16x16x32_bf16 v[106:109], v[160:163], v[176:179], v[106:109]
	v_mfma_f32_16x16x32_bf16 v[94:97], v[146:149], v[184:187], v[94:97]
	v_mfma_f32_16x16x32_bf16 v[90:93], v[160:163], v[184:187], v[90:93]
	v_mfma_f32_16x16x32_bf16 v[78:81], v[146:149], v[196:199], v[78:81]
	v_mfma_f32_16x16x32_bf16 v[74:77], v[160:163], v[196:199], v[74:77]
	v_mfma_f32_16x16x32_bf16 v[118:121], v[200:203], v[164:167], v[118:121]
	v_mfma_f32_16x16x32_bf16 v[114:117], v[208:211], v[164:167], v[114:117]
	v_mfma_f32_16x16x32_bf16 v[102:105], v[200:203], v[172:175], v[102:105]
	v_mfma_f32_16x16x32_bf16 v[98:101], v[208:211], v[172:175], v[98:101]
	v_mfma_f32_16x16x32_bf16 v[86:89], v[200:203], v[180:183], v[86:89]
	v_mfma_f32_16x16x32_bf16 v[82:85], v[208:211], v[180:183], v[82:85]
	v_mfma_f32_16x16x32_bf16 v[70:73], v[200:203], v[188:191], v[70:73]
	v_mfma_f32_16x16x32_bf16 v[66:69], v[208:211], v[188:191], v[66:69]
	v_mfma_f32_16x16x32_bf16 v[118:121], v[204:207], v[168:171], v[118:121]
	v_mfma_f32_16x16x32_bf16 v[114:117], v[212:215], v[168:171], v[114:117]
	v_mfma_f32_16x16x32_bf16 v[102:105], v[204:207], v[176:179], v[102:105]
	v_mfma_f32_16x16x32_bf16 v[98:101], v[212:215], v[176:179], v[98:101]
	v_mfma_f32_16x16x32_bf16 v[86:89], v[204:207], v[184:187], v[86:89]
	v_mfma_f32_16x16x32_bf16 v[82:85], v[212:215], v[184:187], v[82:85]
	v_mfma_f32_16x16x32_bf16 v[70:73], v[204:207], v[196:199], v[70:73]
	v_mfma_f32_16x16x32_bf16 v[66:69], v[212:215], v[196:199], v[66:69]
	s_setprio 0
	s_barrier
	s_add_i32 s9, s9, s3
	v_lshl_add_u64 v[192:193], s[90:91], 0, v[0:1]
	s_mov_b32 m0, s9
	v_lshl_add_u64 v[194:195], s[90:91], 0, v[134:135]
	global_load_lds_dwordx4 v[192:193], off
	s_add_i32 m0, s9, 0x2000
	s_nop 0
	global_load_lds_dwordx4 v[194:195], off
	s_mov_b32 m0, s33
	v_lshl_add_u64 v[216:217], s[6:7], 0, v[130:131]
	ds_read_b128 v[164:167], v159 offset:16384
	ds_read_b128 v[168:171], v159 offset:17408
	ds_read_b128 v[172:175], v159 offset:18432
	ds_read_b128 v[176:179], v159 offset:19456
	ds_read_b128 v[180:183], v159 offset:20480
	ds_read_b128 v[184:187], v159 offset:21504
	ds_read_b128 v[188:191], v159 offset:22528
	ds_read_b128 v[196:199], v159 offset:23552
	global_load_lds_dwordx4 v[216:217], off
	v_lshl_add_u64 v[222:223], s[6:7], 0, v[132:133]
	s_mov_b32 m0, s38
	s_nop 0
	global_load_lds_dwordx4 v[222:223], off
	s_add_u32 s90, s90, s76
	s_addc_u32 s91, s91, s77
	s_add_i32 s8, s8, s3
	v_lshl_add_u64 v[224:225], s[90:91], 0, v[0:1]
	s_mov_b32 m0, s8
	v_lshl_add_u64 v[226:227], s[90:91], 0, v[134:135]
	global_load_lds_dwordx4 v[224:225], off
	s_add_i32 m0, s8, 0x2000
	s_nop 0
	global_load_lds_dwordx4 v[226:227], off
	s_waitcnt vmcnt(8)
	s_waitcnt lgkmcnt(0)
	v_mfma_f32_16x16x32_bf16 v[62:65], v[142:145], v[164:167], v[62:65]
	v_mfma_f32_16x16x32_bf16 v[58:61], v[150:153], v[164:167], v[58:61]
	v_mfma_f32_16x16x32_bf16 v[46:49], v[142:145], v[172:175], v[46:49]
	v_mfma_f32_16x16x32_bf16 v[42:45], v[150:153], v[172:175], v[42:45]
	s_barrier
; #define PG8_STAGE(bufoff, gbase, voff) do { _Pragma("unroll") for (int _i = 0; _i < 2; ++_i) \
;         __builtin_amdgcn_global_load_lds((const unsigned*)((const char*)(gbase) + (voff)[_i]), (LAS unsigned*)(lds + (bufoff) + ldsw + _i * 8192), 16, 0, 0); } while (0)
; #define PG8_LDA(dst, b, h) do { _Pragma("unroll") for (int m = 0; m < 4; ++m) _Pragma("unroll") for (int k = 0; k < 2; ++k) dst[m][k] = *(const LAS bf16x8*)(lds + PG8_SA(b, h) + aoff + m * 2048 + k * 1024); } while (0)
; #define PG8_LDB(dst, b, h) do { _Pragma("unroll") for (int n = 0; n < 2; ++n) _Pragma("unroll") for (int k = 0; k < 2; ++k) dst[n][k] = *(const LAS bf16x8*)(lds + PG8_SB(b, h) + boff + n * 2048 + k * 1024); } while (0)
; #define PG8_MMA(ai, bj, At, Bt) do { __builtin_amdgcn_s_setprio(1); _Pragma("unroll") for (int m = 0; m < 4; ++m) _Pragma("unroll") for (int n = 0; n < 2; ++n) _Pragma("unroll") for (int k = 0; k < 2; ++k) \
;         acc[ai][bj][m][n] = __builtin_amdgcn_mfma_f32_16x16x32_bf16(Bt[n][k], At[m][k], acc[ai][bj][m][n], 0, 0, 0); __builtin_amdgcn_s_setprio(0); } while (0)
; #define PG8_WAIT_V(n) asm volatile("s_waitcnt vmcnt(" #n ")" ::: "memory")
; #define PG8_WAIT_L(n) asm volatile("s_waitcnt lgkmcnt(" #n ")" ::: "memory")
; #define PG8_BAR __builtin_amdgcn_s_barrier()
; #define PG8_SCHED __builtin_amdgcn_sched_barrier(0)
; template <class Epi>
; __device__ __forceinline__ void gemm_phase(LAS unsigned char* lds, const Gemm g, const Sched& S, const Epi& E) {
;     ...
;             PG8_BAR; PG8_WAIT_L(0); PG8_MMA(1, 0, At, B0); PG8_BAR; PG8_SCHED;
;             PG8_STAGE(PG8_SB(0, 1), b2 + hstepB, voffB);
;             PG8_WAIT_V(6); PG8_BAR; PG8_MMA(1, 1, At, B1); PG8_BAR;
;             PG8_LDB(B0, 1, 0); PG8_SCHED; PG8_LDA(At, 1, 0); PG8_STAGE(PG8_SA(0, 1), a2 + hstepA, voffA);
;             PG8_WAIT_L(8); PG8_BAR; PG8_WAIT_L(0); PG8_MMA(0, 0, At, B0); PG8_BAR; PG8_SCHED;
;             PG8_LDB(B1, 1, 1); PG8_STAGE(PG8_SB(1, 0), b3, voffB);
;             PG8_BAR; PG8_WAIT_L(0); PG8_MMA(0, 1, At, B1); PG8_BAR;
	s_setprio 1
	v_mfma_f32_16x16x32_bf16 v[30:33], v[142:145], v[180:183], v[30:33]
	v_mfma_f32_16x16x32_bf16 v[26:29], v[150:153], v[180:183], v[26:29]
	v_mfma_f32_16x16x32_bf16 v[14:17], v[142:145], v[188:191], v[14:17]
	v_mfma_f32_16x16x32_bf16 v[10:13], v[150:153], v[188:191], v[10:13]
	v_mfma_f32_16x16x32_bf16 v[62:65], v[146:149], v[168:171], v[62:65]
	v_mfma_f32_16x16x32_bf16 v[58:61], v[160:163], v[168:171], v[58:61]
	v_mfma_f32_16x16x32_bf16 v[46:49], v[146:149], v[176:179], v[46:49]
	v_mfma_f32_16x16x32_bf16 v[42:45], v[160:163], v[176:179], v[42:45]
	v_mfma_f32_16x16x32_bf16 v[30:33], v[146:149], v[184:187], v[30:33]
	v_mfma_f32_16x16x32_bf16 v[26:29], v[160:163], v[184:187], v[26:29]
	v_mfma_f32_16x16x32_bf16 v[14:17], v[146:149], v[196:199], v[14:17]
	v_mfma_f32_16x16x32_bf16 v[10:13], v[160:163], v[196:199], v[10:13]
	v_mfma_f32_16x16x32_bf16 v[54:57], v[200:203], v[164:167], v[54:57]
	v_mfma_f32_16x16x32_bf16 v[50:53], v[208:211], v[164:167], v[50:53]
	v_mfma_f32_16x16x32_bf16 v[38:41], v[200:203], v[172:175], v[38:41]
	v_mfma_f32_16x16x32_bf16 v[34:37], v[208:211], v[172:175], v[34:37]
	v_mfma_f32_16x16x32_bf16 v[22:25], v[200:203], v[180:183], v[22:25]
	v_mfma_f32_16x16x32_bf16 v[18:21], v[208:211], v[180:183], v[18:21]
	v_mfma_f32_16x16x32_bf16 v[6:9], v[200:203], v[188:191], v[6:9]
	v_mfma_f32_16x16x32_bf16 v[2:5], v[208:211], v[188:191], v[2:5]
	v_mfma_f32_16x16x32_bf16 v[54:57], v[204:207], v[168:171], v[54:57]
	v_mfma_f32_16x16x32_bf16 v[50:53], v[212:215], v[168:171], v[50:53]
	v_mfma_f32_16x16x32_bf16 v[38:41], v[204:207], v[176:179], v[38:41]
	v_mfma_f32_16x16x32_bf16 v[34:37], v[212:215], v[176:179], v[34:37]
	v_mfma_f32_16x16x32_bf16 v[22:25], v[204:207], v[184:187], v[22:25]
	v_mfma_f32_16x16x32_bf16 v[18:21], v[212:215], v[184:187], v[18:21]
	v_mfma_f32_16x16x32_bf16 v[6:9], v[204:207], v[196:199], v[6:9]
	v_mfma_f32_16x16x32_bf16 v[2:5], v[212:215], v[196:199], v[2:5]
	s_setprio 0
	s_barrier
	s_add_i32 s8, 0, 0x18000
	v_add_u32_e32 v160, s8, v156
	ds_read_b128 v[142:145], v160
	ds_read_b128 v[146:149], v160 offset:1024
	ds_read_b128 v[150:153], v160 offset:2048
	ds_read_b128 v[160:163], v160 offset:3072
	s_add_u32 s6, s6, s36
	s_addc_u32 s7, s7, s37
	s_mov_b32 m0, s39
	v_lshl_add_u64 v[200:201], s[6:7], 0, v[130:131]
	ds_read_b128 v[164:167], v159 offset:32768
	ds_read_b128 v[168:171], v159 offset:33792
	ds_read_b128 v[172:175], v159 offset:34816
	ds_read_b128 v[176:179], v159 offset:35840
	ds_read_b128 v[180:183], v159 offset:36864
	ds_read_b128 v[184:187], v159 offset:37888
	ds_read_b128 v[188:191], v159 offset:38912
	ds_read_b128 v[196:199], v159 offset:39936
	global_load_lds_dwordx4 v[200:201], off
	v_lshl_add_u64 v[200:201], s[6:7], 0, v[132:133]
	s_mov_b32 m0, s40
	s_nop 0
	global_load_lds_dwordx4 v[200:201], off
	s_add_i32 s6, 0, 0x1c000
	v_add_u32_e32 v212, s6, v156
	ds_read_b128 v[200:203], v212
	ds_read_b128 v[204:207], v212 offset:1024
	ds_read_b128 v[208:211], v212 offset:2048
	ds_read_b128 v[212:215], v212 offset:3072
	s_waitcnt vmcnt(8)
	s_waitcnt lgkmcnt(0)
	v_mfma_f32_16x16x32_bf16 v[126:129], v[142:145], v[164:167], v[126:129]
	v_mfma_f32_16x16x32_bf16 v[122:125], v[150:153], v[164:167], v[122:125]
	v_mfma_f32_16x16x32_bf16 v[110:113], v[142:145], v[172:175], v[110:113]
	v_mfma_f32_16x16x32_bf16 v[106:109], v[150:153], v[172:175], v[106:109]
	s_barrier
	s_setprio 1
	v_mfma_f32_16x16x32_bf16 v[94:97], v[142:145], v[180:183], v[94:97]
	v_mfma_f32_16x16x32_bf16 v[90:93], v[150:153], v[180:183], v[90:93]
	v_mfma_f32_16x16x32_bf16 v[78:81], v[142:145], v[188:191], v[78:81]
	v_mfma_f32_16x16x32_bf16 v[74:77], v[150:153], v[188:191], v[74:77]
	v_mfma_f32_16x16x32_bf16 v[126:129], v[146:149], v[168:171], v[126:129]
	v_mfma_f32_16x16x32_bf16 v[122:125], v[160:163], v[168:171], v[122:125]
	v_mfma_f32_16x16x32_bf16 v[110:113], v[146:149], v[176:179], v[110:113]
	v_mfma_f32_16x16x32_bf16 v[106:109], v[160:163], v[176:179], v[106:109]
	v_mfma_f32_16x16x32_bf16 v[94:97], v[146:149], v[184:187], v[94:97]
	v_mfma_f32_16x16x32_bf16 v[90:93], v[160:163], v[184:187], v[90:93]
	v_mfma_f32_16x16x32_bf16 v[78:81], v[146:149], v[196:199], v[78:81]
	v_mfma_f32_16x16x32_bf16 v[74:77], v[160:163], v[196:199], v[74:77]
	v_mfma_f32_16x16x32_bf16 v[118:121], v[200:203], v[164:167], v[118:121]
	v_mfma_f32_16x16x32_bf16 v[114:117], v[208:211], v[164:167], v[114:117]
	v_mfma_f32_16x16x32_bf16 v[102:105], v[200:203], v[172:175], v[102:105]
	v_mfma_f32_16x16x32_bf16 v[98:101], v[208:211], v[172:175], v[98:101]
	v_mfma_f32_16x16x32_bf16 v[86:89], v[200:203], v[180:183], v[86:89]
	v_mfma_f32_16x16x32_bf16 v[82:85], v[208:211], v[180:183], v[82:85]
	v_mfma_f32_16x16x32_bf16 v[70:73], v[200:203], v[188:191], v[70:73]
	v_mfma_f32_16x16x32_bf16 v[66:69], v[208:211], v[188:191], v[66:69]
	v_mfma_f32_16x16x32_bf16 v[118:121], v[204:207], v[168:171], v[118:121]
	v_mfma_f32_16x16x32_bf16 v[114:117], v[212:215], v[168:171], v[114:117]
	v_mfma_f32_16x16x32_bf16 v[102:105], v[204:207], v[176:179], v[102:105]
	v_mfma_f32_16x16x32_bf16 v[98:101], v[212:215], v[176:179], v[98:101]
	v_mfma_f32_16x16x32_bf16 v[86:89], v[204:207], v[184:187], v[86:89]
	v_mfma_f32_16x16x32_bf16 v[82:85], v[212:215], v[184:187], v[82:85]
	v_mfma_f32_16x16x32_bf16 v[70:73], v[204:207], v[196:199], v[70:73]
	v_mfma_f32_16x16x32_bf16 v[66:69], v[212:215], v[196:199], v[66:69]
	s_setprio 0
	s_barrier
; __device__ __forceinline__ float pre_get(const Pre& p, int ai, int m, int fr) { return __shfl(p.v[ai], m * 16 + fr); }
; __device__ __forceinline__ float rstd_pre(const float* ss, float v) { return ss ? rsqrtf(v * (1.0f / 2048.0f) + 1e-6f) : 1.0f; }
; #define PG8_STAGE(bufoff, gbase, voff) do { _Pragma("unroll") for (int _i = 0; _i < 2; ++_i) \
;         __builtin_amdgcn_global_load_lds((const unsigned*)((const char*)(gbase) + (voff)[_i]), (LAS unsigned*)(lds + (bufoff) + ldsw + _i * 8192), 16, 0, 0); } while (0)
; #define PG8_LDA(dst, b, h) do { _Pragma("unroll") for (int m = 0; m < 4; ++m) _Pragma("unroll") for (int k = 0; k < 2; ++k) dst[m][k] = *(const LAS bf16x8*)(lds + PG8_SA(b, h) + aoff + m * 2048 + k * 1024); } while (0)
; #define PG8_WAIT_V(n) asm volatile("s_waitcnt vmcnt(" #n ")" ::: "memory")
; #define PG8_WAIT_L(n) asm volatile("s_waitcnt lgkmcnt(" #n ")" ::: "memory")
; #define PG8_BAR __builtin_amdgcn_s_barrier()
; #define PG8_SCHED __builtin_amdgcn_sched_barrier(0)
; template <class Epi>
; __device__ __forceinline__ void gemm_phase(LAS unsigned char* lds, const Gemm g, const Sched& S, const Epi& E) {
;     ...
;             PG8_LDA(At, 1, 1); PG8_STAGE(PG8_SA(1, 0), a3, voffA);
;             PG8_BAR; PG8_WAIT_L(0); PG8_MMA(1, 0, At, B0); PG8_BAR; PG8_SCHED;
;             PG8_STAGE(PG8_SB(1, 1), b3 + hstepB, voffB);
;             PG8_WAIT_V(6); PG8_BAR; PG8_MMA(1, 1, At, B1); PG8_BAR;
;         }
;     __device__ __forceinline__ void operator()(const Acc& acc, const Unit& u, int wr, int wc, int fr, int fq, const Pre& pre) const {
;         const int colt = (u.pn < split) ? base0 + u.pn * 256 : base1 + (u.pn - split) * 256;
;         const int row0 = u.pm * 256 + wr * 64 + fr, col0 = colt + wc * 32 + 8 * fq;
;         bf16_t* Oz = O + (size_t)(u.zb * sOb + u.zh * sOh);
;         float rsq[2][4];
; #pragma unroll
;         for (int ai = 0; ai < 2; ++ai)
; #pragma unroll
;             for (int m = 0; m < 4; ++m) rsq[ai][m] = rstd_pre(ss, pre_get(pre, ai, m, fr));
; #pragma unroll
;         for (int ai = 0; ai < 2; ++ai)
; #pragma unroll
;             for (int m = 0; m < 4; ++m) { const float rs = scale * rsq[ai][m];
; #pragma unroll
;                 for (int bj = 0; bj < 2; ++bj) { f32x4 v0 = acc[ai][bj][m][0] * rs, v1 = acc[ai][bj][m][1] * rs;
	s_add_i32 s7, s8, s3
	v_lshl_add_u64 v[192:193], v[192:193], 0, s[60:61]
	s_mov_b32 m0, s7
	s_nop 0
	global_load_lds_dwordx4 v[192:193], off
	v_lshl_add_u64 v[192:193], v[194:195], 0, s[60:61]
	s_add_i32 m0, s7, 0x2000
	s_nop 0
	global_load_lds_dwordx4 v[192:193], off
	s_mov_b32 m0, s41
	v_lshl_add_u64 v[192:193], v[216:217], 0, s[60:61]
	ds_read_b128 v[164:167], v159 offset:49152
	ds_read_b128 v[168:171], v159 offset:50176
	ds_read_b128 v[172:175], v159 offset:51200
	ds_read_b128 v[176:179], v159 offset:52224
	ds_read_b128 v[180:183], v159 offset:53248
	ds_read_b128 v[184:187], v159 offset:54272
	ds_read_b128 v[188:191], v159 offset:55296
	ds_read_b128 v[196:199], v159 offset:56320
	global_load_lds_dwordx4 v[192:193], off
	v_lshl_add_u64 v[192:193], v[222:223], 0, s[60:61]
	s_mov_b32 m0, s42
	s_nop 0
	global_load_lds_dwordx4 v[192:193], off
	s_add_i32 s6, s6, s3
	v_lshl_add_u64 v[192:193], v[224:225], 0, s[60:61]
	s_mov_b32 m0, s6
	s_nop 0
	global_load_lds_dwordx4 v[192:193], off
	v_lshl_add_u64 v[192:193], v[226:227], 0, s[60:61]
	s_add_i32 m0, s6, 0x2000
	s_nop 0
	global_load_lds_dwordx4 v[192:193], off
	s_waitcnt vmcnt(8)
	s_waitcnt lgkmcnt(0)
	v_mfma_f32_16x16x32_bf16 v[62:65], v[142:145], v[164:167], v[62:65]
	v_mfma_f32_16x16x32_bf16 v[58:61], v[150:153], v[164:167], v[58:61]
	v_mfma_f32_16x16x32_bf16 v[46:49], v[142:145], v[172:175], v[46:49]
	v_mfma_f32_16x16x32_bf16 v[42:45], v[150:153], v[172:175], v[42:45]
	s_barrier
	s_setprio 1
	v_mfma_f32_16x16x32_bf16 v[30:33], v[142:145], v[180:183], v[30:33]
	v_mfma_f32_16x16x32_bf16 v[26:29], v[150:153], v[180:183], v[26:29]
	v_mfma_f32_16x16x32_bf16 v[14:17], v[142:145], v[188:191], v[14:17]
	v_mfma_f32_16x16x32_bf16 v[10:13], v[150:153], v[188:191], v[10:13]
	v_mfma_f32_16x16x32_bf16 v[62:65], v[146:149], v[168:171], v[62:65]
	v_mfma_f32_16x16x32_bf16 v[58:61], v[160:163], v[168:171], v[58:61]
	v_mfma_f32_16x16x32_bf16 v[46:49], v[146:149], v[176:179], v[46:49]
	v_mfma_f32_16x16x32_bf16 v[42:45], v[160:163], v[176:179], v[42:45]
	v_mfma_f32_16x16x32_bf16 v[30:33], v[146:149], v[184:187], v[30:33]
	v_mfma_f32_16x16x32_bf16 v[26:29], v[160:163], v[184:187], v[26:29]
	v_mfma_f32_16x16x32_bf16 v[14:17], v[146:149], v[196:199], v[14:17]
	v_mfma_f32_16x16x32_bf16 v[10:13], v[160:163], v[196:199], v[10:13]
	v_mfma_f32_16x16x32_bf16 v[54:57], v[200:203], v[164:167], v[54:57]
	v_mfma_f32_16x16x32_bf16 v[50:53], v[208:211], v[164:167], v[50:53]
	v_mfma_f32_16x16x32_bf16 v[38:41], v[200:203], v[172:175], v[38:41]
	v_mfma_f32_16x16x32_bf16 v[34:37], v[208:211], v[172:175], v[34:37]
	v_mfma_f32_16x16x32_bf16 v[22:25], v[200:203], v[180:183], v[22:25]
	v_mfma_f32_16x16x32_bf16 v[18:21], v[208:211], v[180:183], v[18:21]
	v_mfma_f32_16x16x32_bf16 v[6:9], v[200:203], v[188:191], v[6:9]
	v_mfma_f32_16x16x32_bf16 v[2:5], v[208:211], v[188:191], v[2:5]
	v_mfma_f32_16x16x32_bf16 v[54:57], v[204:207], v[168:171], v[54:57]
	v_mfma_f32_16x16x32_bf16 v[50:53], v[212:215], v[168:171], v[50:53]
	v_mfma_f32_16x16x32_bf16 v[38:41], v[204:207], v[176:179], v[38:41]
	v_mfma_f32_16x16x32_bf16 v[34:37], v[212:215], v[176:179], v[34:37]
	v_mfma_f32_16x16x32_bf16 v[22:25], v[204:207], v[184:187], v[22:25]
	v_mfma_f32_16x16x32_bf16 v[18:21], v[212:215], v[184:187], v[18:21]
	v_mfma_f32_16x16x32_bf16 v[6:9], v[204:207], v[196:199], v[6:9]
	v_mfma_f32_16x16x32_bf16 v[2:5], v[212:215], v[196:199], v[2:5]
	s_setprio 0
	s_add_u32 s4, s4, 0x100
	s_addc_u32 s5, s5, 0
	s_add_u32 s34, s34, 0x100
	s_addc_u32 s35, s35, 0
	s_cmp_ge_u32 s14, s73
	s_mov_b32 s6, s14
	s_barrier
	s_cbranch_scc0 .LBB0_555
	v_and_or_b32 v142, v220, 64, v154
	v_lshlrev_b32_e32 v148, 2, v142
	ds_bpermute_b32 v143, v148, v141
	ds_bpermute_b32 v142, v148, v141 offset:64
	s_mov_b32 s4, 0x3a000000
	ds_bpermute_b32 v145, v148, v141 offset:128
	ds_bpermute_b32 v144, v148, v141 offset:192
	v_readlane_b32 s8, v254, 29
	s_waitcnt lgkmcnt(0)
	v_pk_fma_f32 v[146:147], v[142:143], s[4:5], v[232:233] op_sel_hi:[1,0,0]
	ds_bpermute_b32 v143, v148, v140
	v_mul_f32_e32 v141, 0x4b800000, v147
	v_cmp_gt_f32_e32 vcc, s97, v147
	ds_bpermute_b32 v142, v148, v140 offset:64
	v_readlane_b32 s9, v254, 30
	v_cndmask_b32_e32 v141, v147, v141, vcc
	v_rsq_f32_e32 v141, v141
	v_cmp_gt_f32_e64 s[4:5], s97, v146
	s_mov_b64 s[90:91], -1
	v_mul_f32_e32 v147, 0x45800000, v141
	v_cndmask_b32_e32 v141, v141, v147, vcc
	v_cndmask_b32_e64 v147, v141, 1.0, s[78:79]
	ds_bpermute_b32 v141, v148, v140 offset:128
	ds_bpermute_b32 v140, v148, v140 offset:192
	v_mul_f32_e32 v148, s70, v147
	v_pk_mul_f32 v[152:153], v[122:123], v[148:149] op_sel_hi:[1,0]
	v_cndmask_b32_e64 v122, 0, 1, s[8:9]
	v_pk_mul_f32 v[128:129], v[128:129], v[148:149] op_sel_hi:[1,0]
	v_pk_mul_f32 v[150:151], v[126:127], v[148:149] op_sel_hi:[1,0]
	v_pk_mul_f32 v[126:127], v[124:125], v[148:149] op_sel_hi:[1,0]
	v_cmp_ne_u32_e64 s[6:7], 1, v122
	v_readfirstlane_b32 s98, v219
	s_nop 1
	s_bitcmp1_b32 s98, 8
	s_cbranch_scc1 .Lresync_x_555
	s_barrier
.Lresync_x_555:
	s_andn2_b64 vcc, exec, s[8:9]
	s_cbranch_vccnz .LBB0_558
	s_mov_b64 s[90:91], 0

; #define PG8_STAGE(bufoff, gbase, voff) do { _Pragma("unroll") for (int _i = 0; _i < 2; ++_i) \
;         __builtin_amdgcn_global_load_lds((const unsigned*)((const char*)(gbase) + (voff)[_i]), (LAS unsigned*)(lds + (bufoff) + ldsw + _i * 8192), 16, 0, 0); } while (0)
; #define PG8_LDA(dst, b, h) do { _Pragma("unroll") for (int m = 0; m < 4; ++m) _Pragma("unroll") for (int k = 0; k < 2; ++k) dst[m][k] = *(const LAS bf16x8*)(lds + PG8_SA(b, h) + aoff + m * 2048 + k * 1024); } while (0)
; #define PG8_LDB(dst, b, h) do { _Pragma("unroll") for (int n = 0; n < 2; ++n) _Pragma("unroll") for (int k = 0; k < 2; ++k) dst[n][k] = *(const LAS bf16x8*)(lds + PG8_SB(b, h) + boff + n * 2048 + k * 1024); } while (0)
; #define PG8_MMA(ai, bj, At, Bt) do { __builtin_amdgcn_s_setprio(1); _Pragma("unroll") for (int m = 0; m < 4; ++m) _Pragma("unroll") for (int n = 0; n < 2; ++n) _Pragma("unroll") for (int k = 0; k < 2; ++k) \
;         acc[ai][bj][m][n] = __builtin_amdgcn_mfma_f32_16x16x32_bf16(Bt[n][k], At[m][k], acc[ai][bj][m][n], 0, 0, 0); __builtin_amdgcn_s_setprio(0); } while (0)
; #define PG8_WAIT_V(n) asm volatile("s_waitcnt vmcnt(" #n ")" ::: "memory")
; #define PG8_WAIT_L(n) asm volatile("s_waitcnt lgkmcnt(" #n ")" ::: "memory")
; template <class Epi>
; __device__ __forceinline__ void gemm_phase(LAS unsigned char* lds, const Gemm g, const Sched& S, const Epi& E) {
;     ...
;         for (int t = 0; t < nt; t += 2) {
;             const bool last = (t == nt - 2);
;             const char* a1 = cA + (size_t)(t + 1) * kstep;
;             const char* a2 = last ? nA : cA + (size_t)(t + 2) * kstep; const char* b2 = last ? nB : cB + (size_t)(t + 2) * kstep;
;             const char* a3 = a2 + kstep; const char* b3 = b2 + kstep;
;             PG8_LDB(B0, 0, 0); PG8_SCHED; PG8_LDA(At, 0, 0); PG8_STAGE(PG8_SA(1, 1), a1 + hstepA, voffA);
;             PG8_WAIT_L(8); PG8_BAR; PG8_WAIT_L(0); PG8_MMA(0, 0, At, B0); PG8_BAR; PG8_SCHED;
;             PG8_LDB(B1, 0, 1); PG8_STAGE(PG8_SB(0, 0), b2, voffB);
;             PG8_BAR; PG8_WAIT_L(0); PG8_MMA(0, 1, At, B1); PG8_BAR;
;             PG8_LDA(At, 0, 1); PG8_STAGE(PG8_SA(0, 0), a2, voffA);
;             PG8_BAR; PG8_WAIT_L(0); PG8_MMA(1, 0, At, B0); PG8_BAR; PG8_SCHED;
;             PG8_STAGE(PG8_SB(0, 1), b2 + hstepB, voffB);
;             PG8_WAIT_V(6); PG8_BAR; PG8_MMA(1, 1, At, B1); PG8_BAR;
.Lresync_y_719:
.LBB0_719:
	s_add_i32 s14, s4, 2
	s_add_u32 s15, s0, 0x80
	s_addc_u32 s5, s1, 0
	s_add_i32 s8, 0, 0x10000
	v_add_u32_e32 v118, s8, v217
	ds_read_b128 v[106:109], v118
	ds_read_b128 v[110:113], v118 offset:1024
	ds_read_b128 v[114:117], v118 offset:2048
	ds_read_b128 v[118:121], v118 offset:3072
	s_cmp_eq_u32 s48, s4
	s_cselect_b32 s4, s59, s15
	s_cselect_b32 s5, s57, s5
	s_cselect_b32 s95, vcc_lo, s35
	s_cselect_b32 s94, vcc_hi, s34
	v_lshl_add_u64 v[154:155], s[0:1], 0, v[202:203]
	s_add_i32 m0, s52, 0xc000
	ds_read_b128 v[122:125], v235
	ds_read_b128 v[126:129], v235 offset:1024
	ds_read_b128 v[130:133], v235 offset:2048
	ds_read_b128 v[134:137], v235 offset:3072
	ds_read_b128 v[138:141], v235 offset:4096
	ds_read_b128 v[142:145], v235 offset:5120
	ds_read_b128 v[146:149], v235 offset:6144
	ds_read_b128 v[150:153], v235 offset:7168
	global_load_lds_dwordx4 v[154:155], off
	v_lshl_add_u64 v[154:155], s[0:1], 0, v[204:205]
	s_add_i32 m0, s52, 0xe000
	s_nop 0
	global_load_lds_dwordx4 v[154:155], off
	s_waitcnt lgkmcnt(8)
	s_waitcnt lgkmcnt(0)
	v_mfma_f32_16x16x32_bf16 v[162:165], v[114:117], v[130:133], v[162:165]
	v_mfma_f32_16x16x32_bf16 v[94:97], v[106:109], v[138:141], v[94:97]
	v_mfma_f32_16x16x32_bf16 v[90:93], v[114:117], v[138:141], v[90:93]
	v_mfma_f32_16x16x32_bf16 v[78:81], v[106:109], v[146:149], v[78:81]
	s_barrier
	s_waitcnt lgkmcnt(0)
	s_setprio 1
	s_waitcnt lgkmcnt(0)
	v_mfma_f32_16x16x32_bf16 v[74:77], v[114:117], v[146:149], v[74:77]
	v_mfma_f32_16x16x32_bf16 v[154:157], v[106:109], v[122:125], v[190:193]
	v_mfma_f32_16x16x32_bf16 v[158:161], v[114:117], v[122:125], v[186:189]
	v_mfma_f32_16x16x32_bf16 v[166:169], v[106:109], v[130:133], v[174:177]
	v_mfma_f32_16x16x32_bf16 v[162:165], v[118:121], v[134:137], v[162:165]
	v_mfma_f32_16x16x32_bf16 v[94:97], v[110:113], v[142:145], v[94:97]
	v_mfma_f32_16x16x32_bf16 v[90:93], v[118:121], v[142:145], v[90:93]
	v_mfma_f32_16x16x32_bf16 v[78:81], v[110:113], v[150:153], v[78:81]
	v_mfma_f32_16x16x32_bf16 v[74:77], v[118:121], v[150:153], v[74:77]
	v_mfma_f32_16x16x32_bf16 v[154:157], v[110:113], v[126:129], v[154:157]
	v_mfma_f32_16x16x32_bf16 v[158:161], v[118:121], v[126:129], v[158:161]
	v_mfma_f32_16x16x32_bf16 v[166:169], v[110:113], v[134:137], v[166:169]
	s_setprio 0
	s_barrier
	s_add_i32 s9, 0, 0x14000
	s_add_i32 s8, s8, s43
	v_add_u32_e32 v190, s9, v217
	v_lshl_add_u64 v[210:211], s[94:95], 0, v[0:1]
	s_mov_b32 m0, s8
	ds_read_b128 v[170:173], v190
	ds_read_b128 v[174:177], v190 offset:1024
	ds_read_b128 v[186:189], v190 offset:2048
	ds_read_b128 v[190:193], v190 offset:3072
	global_load_lds_dwordx4 v[210:211], off
	v_lshl_add_u64 v[212:213], s[94:95], 0, v[200:201]
	s_add_i32 m0, s8, 0x2000
	s_nop 0
	global_load_lds_dwordx4 v[212:213], off
	s_waitcnt lgkmcnt(0)
	v_mfma_f32_16x16x32_bf16 v[182:185], v[170:173], v[122:125], v[182:185]
	v_mfma_f32_16x16x32_bf16 v[102:105], v[170:173], v[130:133], v[102:105]
	v_mfma_f32_16x16x32_bf16 v[98:101], v[186:189], v[130:133], v[98:101]
	v_mfma_f32_16x16x32_bf16 v[86:89], v[170:173], v[138:141], v[86:89]
	s_barrier
	s_waitcnt lgkmcnt(0)
	s_setprio 1
	s_waitcnt lgkmcnt(0)
	v_mfma_f32_16x16x32_bf16 v[82:85], v[186:189], v[138:141], v[82:85]
	v_mfma_f32_16x16x32_bf16 v[70:73], v[170:173], v[146:149], v[70:73]
	v_mfma_f32_16x16x32_bf16 v[66:69], v[186:189], v[146:149], v[66:69]
	v_mfma_f32_16x16x32_bf16 v[182:185], v[174:177], v[126:129], v[182:185]
	v_mfma_f32_16x16x32_bf16 v[122:125], v[186:189], v[122:125], v[178:181]
	v_mfma_f32_16x16x32_bf16 v[102:105], v[174:177], v[134:137], v[102:105]
	v_mfma_f32_16x16x32_bf16 v[98:101], v[190:193], v[134:137], v[98:101]
	v_mfma_f32_16x16x32_bf16 v[86:89], v[174:177], v[142:145], v[86:89]
	v_mfma_f32_16x16x32_bf16 v[82:85], v[190:193], v[142:145], v[82:85]
	v_mfma_f32_16x16x32_bf16 v[70:73], v[174:177], v[150:153], v[70:73]
	v_mfma_f32_16x16x32_bf16 v[66:69], v[190:193], v[150:153], v[66:69]
	v_mfma_f32_16x16x32_bf16 v[122:125], v[190:193], v[126:129], v[122:125]
	s_setprio 0
	s_mov_b32 m0, s52
	v_lshl_add_u64 v[214:215], s[4:5], 0, v[196:197]
	s_barrier
	ds_read_b128 v[126:129], v235 offset:16384
	ds_read_b128 v[130:133], v235 offset:17408
	ds_read_b128 v[134:137], v235 offset:18432
	ds_read_b128 v[138:141], v235 offset:19456
	ds_read_b128 v[142:145], v235 offset:20480
	ds_read_b128 v[146:149], v235 offset:21504
	ds_read_b128 v[150:153], v235 offset:22528
	ds_read_b128 v[178:181], v235 offset:23552
	global_load_lds_dwordx4 v[214:215], off
	v_lshl_add_u64 v[222:223], s[4:5], 0, v[198:199]
	s_mov_b32 m0, s53
	s_nop 0
	global_load_lds_dwordx4 v[222:223], off
	s_add_u32 s94, s94, s76
	s_addc_u32 s95, s95, s77
	s_add_i32 s8, s9, s43
	v_lshl_add_u64 v[224:225], s[94:95], 0, v[0:1]
	s_mov_b32 m0, s8
	v_lshl_add_u64 v[226:227], s[94:95], 0, v[200:201]
	global_load_lds_dwordx4 v[224:225], off
	s_add_i32 m0, s8, 0x2000
	s_nop 0
	global_load_lds_dwordx4 v[226:227], off
	s_waitcnt vmcnt(6)
	s_waitcnt lgkmcnt(0)
	v_mfma_f32_16x16x32_bf16 v[62:65], v[106:109], v[126:129], v[62:65]
	v_mfma_f32_16x16x32_bf16 v[58:61], v[114:117], v[126:129], v[58:61]
	v_mfma_f32_16x16x32_bf16 v[46:49], v[106:109], v[134:137], v[46:49]
	v_mfma_f32_16x16x32_bf16 v[42:45], v[114:117], v[134:137], v[42:45]
	s_barrier
; #define PG8_STAGE(bufoff, gbase, voff) do { _Pragma("unroll") for (int _i = 0; _i < 2; ++_i) \
;         __builtin_amdgcn_global_load_lds((const unsigned*)((const char*)(gbase) + (voff)[_i]), (LAS unsigned*)(lds + (bufoff) + ldsw + _i * 8192), 16, 0, 0); } while (0)
; #define PG8_LDA(dst, b, h) do { _Pragma("unroll") for (int m = 0; m < 4; ++m) _Pragma("unroll") for (int k = 0; k < 2; ++k) dst[m][k] = *(const LAS bf16x8*)(lds + PG8_SA(b, h) + aoff + m * 2048 + k * 1024); } while (0)
; #define PG8_LDB(dst, b, h) do { _Pragma("unroll") for (int n = 0; n < 2; ++n) _Pragma("unroll") for (int k = 0; k < 2; ++k) dst[n][k] = *(const LAS bf16x8*)(lds + PG8_SB(b, h) + boff + n * 2048 + k * 1024); } while (0)
; #define PG8_MMA(ai, bj, At, Bt) do { __builtin_amdgcn_s_setprio(1); _Pragma("unroll") for (int m = 0; m < 4; ++m) _Pragma("unroll") for (int n = 0; n < 2; ++n) _Pragma("unroll") for (int k = 0; k < 2; ++k) \
;         acc[ai][bj][m][n] = __builtin_amdgcn_mfma_f32_16x16x32_bf16(Bt[n][k], At[m][k], acc[ai][bj][m][n], 0, 0, 0); __builtin_amdgcn_s_setprio(0); } while (0)
; #define PG8_WAIT_V(n) asm volatile("s_waitcnt vmcnt(" #n ")" ::: "memory")
; #define PG8_WAIT_L(n) asm volatile("s_waitcnt lgkmcnt(" #n ")" ::: "memory")
; #define PG8_BAR __builtin_amdgcn_s_barrier()
; #define PG8_SCHED __builtin_amdgcn_sched_barrier(0)
; template <class Epi>
; __device__ __forceinline__ void gemm_phase(LAS unsigned char* lds, const Gemm g, const Sched& S, const Epi& E) {
;     ...
;             PG8_WAIT_V(6); PG8_BAR; PG8_MMA(1, 1, At, B1); PG8_BAR;
;             PG8_LDB(B0, 1, 0); PG8_SCHED; PG8_LDA(At, 1, 0); PG8_STAGE(PG8_SA(0, 1), a2 + hstepA, voffA);
;             PG8_WAIT_L(8); PG8_BAR; PG8_WAIT_L(0); PG8_MMA(0, 0, At, B0); PG8_BAR; PG8_SCHED;
;             PG8_LDB(B1, 1, 1); PG8_STAGE(PG8_SB(1, 0), b3, voffB);
;             PG8_BAR; PG8_WAIT_L(0); PG8_MMA(0, 1, At, B1); PG8_BAR;
;             PG8_LDA(At, 1, 1); PG8_STAGE(PG8_SA(1, 0), a3, voffA);
;             PG8_BAR; PG8_WAIT_L(0); PG8_MMA(1, 0, At, B0); PG8_BAR; PG8_SCHED;
;             PG8_STAGE(PG8_SB(1, 1), b3 + hstepB, voffB);
;             PG8_WAIT_V(6); PG8_BAR; PG8_MMA(1, 1, At, B1); PG8_BAR;
	s_setprio 1
	v_mfma_f32_16x16x32_bf16 v[30:33], v[106:109], v[142:145], v[30:33]
	v_mfma_f32_16x16x32_bf16 v[26:29], v[114:117], v[142:145], v[26:29]
	v_mfma_f32_16x16x32_bf16 v[14:17], v[106:109], v[150:153], v[14:17]
	v_mfma_f32_16x16x32_bf16 v[10:13], v[114:117], v[150:153], v[10:13]
	v_mfma_f32_16x16x32_bf16 v[62:65], v[110:113], v[130:133], v[62:65]
	v_mfma_f32_16x16x32_bf16 v[58:61], v[118:121], v[130:133], v[58:61]
	v_mfma_f32_16x16x32_bf16 v[46:49], v[110:113], v[138:141], v[46:49]
	v_mfma_f32_16x16x32_bf16 v[42:45], v[118:121], v[138:141], v[42:45]
	v_mfma_f32_16x16x32_bf16 v[30:33], v[110:113], v[146:149], v[30:33]
	v_mfma_f32_16x16x32_bf16 v[26:29], v[118:121], v[146:149], v[26:29]
	v_mfma_f32_16x16x32_bf16 v[14:17], v[110:113], v[178:181], v[14:17]
	v_mfma_f32_16x16x32_bf16 v[10:13], v[118:121], v[178:181], v[10:13]
	v_mfma_f32_16x16x32_bf16 v[54:57], v[170:173], v[126:129], v[54:57]
	v_mfma_f32_16x16x32_bf16 v[50:53], v[186:189], v[126:129], v[50:53]
	v_mfma_f32_16x16x32_bf16 v[38:41], v[170:173], v[134:137], v[38:41]
	v_mfma_f32_16x16x32_bf16 v[34:37], v[186:189], v[134:137], v[34:37]
	v_mfma_f32_16x16x32_bf16 v[22:25], v[170:173], v[142:145], v[22:25]
	v_mfma_f32_16x16x32_bf16 v[18:21], v[186:189], v[142:145], v[18:21]
	v_mfma_f32_16x16x32_bf16 v[6:9], v[170:173], v[150:153], v[6:9]
	v_mfma_f32_16x16x32_bf16 v[2:5], v[186:189], v[150:153], v[2:5]
	v_mfma_f32_16x16x32_bf16 v[54:57], v[174:177], v[130:133], v[54:57]
	v_mfma_f32_16x16x32_bf16 v[50:53], v[190:193], v[130:133], v[50:53]
	v_mfma_f32_16x16x32_bf16 v[38:41], v[174:177], v[138:141], v[38:41]
	v_mfma_f32_16x16x32_bf16 v[34:37], v[190:193], v[138:141], v[34:37]
	v_mfma_f32_16x16x32_bf16 v[22:25], v[174:177], v[146:149], v[22:25]
	v_mfma_f32_16x16x32_bf16 v[18:21], v[190:193], v[146:149], v[18:21]
	v_mfma_f32_16x16x32_bf16 v[6:9], v[174:177], v[178:181], v[6:9]
	v_mfma_f32_16x16x32_bf16 v[2:5], v[190:193], v[178:181], v[2:5]
	s_setprio 0
	s_add_i32 s8, 0, 0x18000
	v_add_u32_e32 v118, s8, v217
	s_barrier
	ds_read_b128 v[106:109], v118
	ds_read_b128 v[110:113], v118 offset:1024
	ds_read_b128 v[114:117], v118 offset:2048
	ds_read_b128 v[118:121], v118 offset:3072
	s_add_u32 s4, s4, s40
	s_addc_u32 s5, s5, s41
	s_mov_b32 m0, s56
	v_lshl_add_u64 v[174:175], s[4:5], 0, v[196:197]
	ds_read_b128 v[126:129], v235 offset:32768
	ds_read_b128 v[130:133], v235 offset:33792
	ds_read_b128 v[134:137], v235 offset:34816
	ds_read_b128 v[138:141], v235 offset:35840
	ds_read_b128 v[142:145], v235 offset:36864
	ds_read_b128 v[146:149], v235 offset:37888
	ds_read_b128 v[150:153], v235 offset:38912
	ds_read_b128 v[170:173], v235 offset:39936
	global_load_lds_dwordx4 v[174:175], off
	v_lshl_add_u64 v[174:175], s[4:5], 0, v[198:199]
	s_mov_b32 m0, s67
	s_nop 0
	global_load_lds_dwordx4 v[174:175], off
	s_waitcnt lgkmcnt(8)
	s_waitcnt lgkmcnt(0)
	v_mfma_f32_16x16x32_bf16 v[154:157], v[106:109], v[126:129], v[154:157]
	v_mfma_f32_16x16x32_bf16 v[190:193], v[110:113], v[130:133], v[154:157]
	v_mfma_f32_16x16x32_bf16 v[154:157], v[114:117], v[126:129], v[158:161]
	v_mfma_f32_16x16x32_bf16 v[186:189], v[118:121], v[130:133], v[154:157]
	s_barrier
	s_waitcnt lgkmcnt(0)
	s_setprio 1
	s_waitcnt lgkmcnt(0)
	v_mfma_f32_16x16x32_bf16 v[154:157], v[106:109], v[134:137], v[166:169]
	v_mfma_f32_16x16x32_bf16 v[174:177], v[110:113], v[138:141], v[154:157]
	v_mfma_f32_16x16x32_bf16 v[154:157], v[114:117], v[134:137], v[162:165]
	v_mfma_f32_16x16x32_bf16 v[94:97], v[106:109], v[142:145], v[94:97]
	v_mfma_f32_16x16x32_bf16 v[90:93], v[114:117], v[142:145], v[90:93]
	v_mfma_f32_16x16x32_bf16 v[78:81], v[106:109], v[150:153], v[78:81]
	v_mfma_f32_16x16x32_bf16 v[74:77], v[114:117], v[150:153], v[74:77]
	v_mfma_f32_16x16x32_bf16 v[162:165], v[118:121], v[138:141], v[154:157]
	v_mfma_f32_16x16x32_bf16 v[94:97], v[110:113], v[146:149], v[94:97]
	v_mfma_f32_16x16x32_bf16 v[90:93], v[118:121], v[146:149], v[90:93]
	v_mfma_f32_16x16x32_bf16 v[78:81], v[110:113], v[170:173], v[78:81]
	v_mfma_f32_16x16x32_bf16 v[74:77], v[118:121], v[170:173], v[74:77]
	s_setprio 0
	s_barrier
	s_add_i32 s4, 0, 0x1c000
	v_add_u32_e32 v178, s4, v217
	s_add_i32 s5, s8, s43
	ds_read_b128 v[154:157], v178
	ds_read_b128 v[158:161], v178 offset:1024
	ds_read_b128 v[166:169], v178 offset:2048
	ds_read_b128 v[206:209], v178 offset:3072
	v_lshl_add_u64 v[178:179], v[210:211], 0, s[60:61]
	s_mov_b32 m0, s5
	s_nop 0
	global_load_lds_dwordx4 v[178:179], off
	v_lshl_add_u64 v[178:179], v[212:213], 0, s[60:61]
	s_add_i32 m0, s5, 0x2000
	s_nop 0
	global_load_lds_dwordx4 v[178:179], off
	s_waitcnt lgkmcnt(0)
	v_mfma_f32_16x16x32_bf16 v[178:181], v[154:157], v[126:129], v[182:185]
	v_mfma_f32_16x16x32_bf16 v[122:125], v[166:169], v[126:129], v[122:125]
	v_mfma_f32_16x16x32_bf16 v[102:105], v[154:157], v[134:137], v[102:105]
	v_mfma_f32_16x16x32_bf16 v[98:101], v[166:169], v[134:137], v[98:101]
	s_barrier
	s_waitcnt lgkmcnt(0)
	s_setprio 1
	s_waitcnt lgkmcnt(0)
	v_mfma_f32_16x16x32_bf16 v[86:89], v[154:157], v[142:145], v[86:89]
	v_mfma_f32_16x16x32_bf16 v[82:85], v[166:169], v[142:145], v[82:85]
	v_mfma_f32_16x16x32_bf16 v[70:73], v[154:157], v[150:153], v[70:73]
	v_mfma_f32_16x16x32_bf16 v[66:69], v[166:169], v[150:153], v[66:69]
	v_mfma_f32_16x16x32_bf16 v[182:185], v[158:161], v[130:133], v[178:181]
	v_mfma_f32_16x16x32_bf16 v[178:181], v[206:209], v[130:133], v[122:125]
	v_mfma_f32_16x16x32_bf16 v[102:105], v[158:161], v[138:141], v[102:105]
	v_mfma_f32_16x16x32_bf16 v[98:101], v[206:209], v[138:141], v[98:101]
	v_mfma_f32_16x16x32_bf16 v[86:89], v[158:161], v[146:149], v[86:89]
	v_mfma_f32_16x16x32_bf16 v[82:85], v[206:209], v[146:149], v[82:85]
	v_mfma_f32_16x16x32_bf16 v[70:73], v[158:161], v[170:173], v[70:73]
	v_mfma_f32_16x16x32_bf16 v[66:69], v[206:209], v[170:173], v[66:69]
	s_setprio 0
	s_mov_b32 m0, s51
	v_lshl_add_u64 v[170:171], v[214:215], 0, s[60:61]
	s_barrier
; #define PG8_STAGE(bufoff, gbase, voff) do { _Pragma("unroll") for (int _i = 0; _i < 2; ++_i) \
;         __builtin_amdgcn_global_load_lds((const unsigned*)((const char*)(gbase) + (voff)[_i]), (LAS unsigned*)(lds + (bufoff) + ldsw + _i * 8192), 16, 0, 0); } while (0)
; #define PG8_LDA(dst, b, h) do { _Pragma("unroll") for (int m = 0; m < 4; ++m) _Pragma("unroll") for (int k = 0; k < 2; ++k) dst[m][k] = *(const LAS bf16x8*)(lds + PG8_SA(b, h) + aoff + m * 2048 + k * 1024); } while (0)
; #define PG8_MMA(ai, bj, At, Bt) do { __builtin_amdgcn_s_setprio(1); _Pragma("unroll") for (int m = 0; m < 4; ++m) _Pragma("unroll") for (int n = 0; n < 2; ++n) _Pragma("unroll") for (int k = 0; k < 2; ++k) \
;         acc[ai][bj][m][n] = __builtin_amdgcn_mfma_f32_16x16x32_bf16(Bt[n][k], At[m][k], acc[ai][bj][m][n], 0, 0, 0); __builtin_amdgcn_s_setprio(0); } while (0)
; #define PG8_WAIT_V(n) asm volatile("s_waitcnt vmcnt(" #n ")" ::: "memory")
; #define PG8_WAIT_L(n) asm volatile("s_waitcnt lgkmcnt(" #n ")" ::: "memory")
; #define PG8_BAR __builtin_amdgcn_s_barrier()
; #define PG8_SCHED __builtin_amdgcn_sched_barrier(0)
; template <class Epi>
; __device__ __forceinline__ void gemm_phase(LAS unsigned char* lds, const Gemm g, const Sched& S, const Epi& E) {
;     ...
;             PG8_LDA(At, 1, 1); PG8_STAGE(PG8_SA(1, 0), a3, voffA);
;             PG8_BAR; PG8_WAIT_L(0); PG8_MMA(1, 0, At, B0); PG8_BAR; PG8_SCHED;
;             PG8_STAGE(PG8_SB(1, 1), b3 + hstepB, voffB);
;             PG8_WAIT_V(6); PG8_BAR; PG8_MMA(1, 1, At, B1); PG8_BAR;
;     __device__ __forceinline__ void operator()(const Acc& acc, const Unit& u, int wr, int wc, int fr, int fq, const Pre& pre) const {
;         const int row0 = u.pm * 256 + wr * 64 + fr, col0 = u.pn * 256 + wc * 32 + 8 * fq;
;         const size_t zo = (size_t)(u.zb * sOb + u.zh * sOh);
; #pragma unroll
;         for (int ai = 0; ai < 2; ++ai) {
;             f32x4 bv[4][2][2];
;             if (base) {
; #pragma unroll
;                 for (int m = 0; m < 4; ++m) { const size_t off = zo + (size_t)(row0 + ai * 128 + m * 16) * ldc + col0;
; #pragma unroll
;                     for (int bj = 0; bj < 2; ++bj)
; #pragma unroll
;                         for (int n = 0; n < 2; ++n) bv[m][bj][n] = *(const f32x4*)(base + off + bj * 128 + n * 4); }
	ds_read_b128 v[122:125], v235 offset:49152
	ds_read_b128 v[126:129], v235 offset:50176
	ds_read_b128 v[130:133], v235 offset:51200
	ds_read_b128 v[134:137], v235 offset:52224
	ds_read_b128 v[138:141], v235 offset:53248
	ds_read_b128 v[142:145], v235 offset:54272
	ds_read_b128 v[146:149], v235 offset:55296
	ds_read_b128 v[150:153], v235 offset:56320
	global_load_lds_dwordx4 v[170:171], off
	v_lshl_add_u64 v[170:171], v[222:223], 0, s[60:61]
	s_mov_b32 m0, s2
	s_nop 0
	global_load_lds_dwordx4 v[170:171], off
	s_add_i32 s4, s4, s43
	v_lshl_add_u64 v[170:171], v[224:225], 0, s[60:61]
	s_mov_b32 m0, s4
	s_nop 0
	global_load_lds_dwordx4 v[170:171], off
	v_lshl_add_u64 v[170:171], v[226:227], 0, s[60:61]
	s_add_i32 m0, s4, 0x2000
	s_nop 0
	global_load_lds_dwordx4 v[170:171], off
	s_waitcnt vmcnt(6)
	s_waitcnt lgkmcnt(0)
	v_mfma_f32_16x16x32_bf16 v[62:65], v[106:109], v[122:125], v[62:65]
	v_mfma_f32_16x16x32_bf16 v[58:61], v[114:117], v[122:125], v[58:61]
	v_mfma_f32_16x16x32_bf16 v[46:49], v[106:109], v[130:133], v[46:49]
	v_mfma_f32_16x16x32_bf16 v[42:45], v[114:117], v[130:133], v[42:45]
	s_barrier
	s_setprio 1
	v_mfma_f32_16x16x32_bf16 v[30:33], v[106:109], v[138:141], v[30:33]
	v_mfma_f32_16x16x32_bf16 v[26:29], v[114:117], v[138:141], v[26:29]
	v_mfma_f32_16x16x32_bf16 v[14:17], v[106:109], v[146:149], v[14:17]
	v_mfma_f32_16x16x32_bf16 v[10:13], v[114:117], v[146:149], v[10:13]
	v_mfma_f32_16x16x32_bf16 v[62:65], v[110:113], v[126:129], v[62:65]
	v_mfma_f32_16x16x32_bf16 v[58:61], v[118:121], v[126:129], v[58:61]
	v_mfma_f32_16x16x32_bf16 v[46:49], v[110:113], v[134:137], v[46:49]
	v_mfma_f32_16x16x32_bf16 v[42:45], v[118:121], v[134:137], v[42:45]
	v_mfma_f32_16x16x32_bf16 v[30:33], v[110:113], v[142:145], v[30:33]
	v_mfma_f32_16x16x32_bf16 v[26:29], v[118:121], v[142:145], v[26:29]
	v_mfma_f32_16x16x32_bf16 v[14:17], v[110:113], v[150:153], v[14:17]
	v_mfma_f32_16x16x32_bf16 v[10:13], v[118:121], v[150:153], v[10:13]
	v_mfma_f32_16x16x32_bf16 v[54:57], v[154:157], v[122:125], v[54:57]
	v_mfma_f32_16x16x32_bf16 v[50:53], v[166:169], v[122:125], v[50:53]
	v_mfma_f32_16x16x32_bf16 v[38:41], v[154:157], v[130:133], v[38:41]
	v_mfma_f32_16x16x32_bf16 v[34:37], v[166:169], v[130:133], v[34:37]
	v_mfma_f32_16x16x32_bf16 v[22:25], v[154:157], v[138:141], v[22:25]
	v_mfma_f32_16x16x32_bf16 v[18:21], v[166:169], v[138:141], v[18:21]
	v_mfma_f32_16x16x32_bf16 v[6:9], v[154:157], v[146:149], v[6:9]
	v_mfma_f32_16x16x32_bf16 v[2:5], v[166:169], v[146:149], v[2:5]
	v_mfma_f32_16x16x32_bf16 v[54:57], v[158:161], v[126:129], v[54:57]
	v_mfma_f32_16x16x32_bf16 v[50:53], v[206:209], v[126:129], v[50:53]
	v_mfma_f32_16x16x32_bf16 v[38:41], v[158:161], v[134:137], v[38:41]
	v_mfma_f32_16x16x32_bf16 v[34:37], v[206:209], v[134:137], v[34:37]
	v_mfma_f32_16x16x32_bf16 v[22:25], v[158:161], v[142:145], v[22:25]
	v_mfma_f32_16x16x32_bf16 v[18:21], v[206:209], v[142:145], v[18:21]
	v_mfma_f32_16x16x32_bf16 v[6:9], v[158:161], v[150:153], v[6:9]
	v_mfma_f32_16x16x32_bf16 v[2:5], v[206:209], v[150:153], v[2:5]
	s_setprio 0
	s_add_u32 s0, s0, 0x100
	s_addc_u32 s1, s1, 0
	s_add_u32 s34, s34, 0x100
	s_addc_u32 s35, s35, 0
	s_cmp_ge_u32 s14, s73
	s_mov_b32 s4, s14
	s_barrier
	s_cbranch_scc0 .LBB0_719
	s_ashr_i32 s0, s42, 31
	s_ashr_i32 s4, s24, 31
	v_readlane_b32 s8, v253, 59
	s_mul_hi_u32 s1, s74, s42
	s_mul_i32 s0, s74, s0
	v_readlane_b32 s9, v253, 60
	s_mul_hi_u32 s5, s8, s24
	s_mul_i32 s4, s8, s4
	s_add_i32 s0, s1, s0
	s_mul_i32 s1, s75, s42
	s_add_i32 s4, s5, s4
	s_mul_i32 s5, s9, s24
	v_lshl_add_u32 v206, s97, 8, v216
	s_add_i32 s0, s0, s1
	s_mul_i32 s1, s74, s42
	s_add_i32 s4, s4, s5
	s_mul_i32 s5, s8, s24
	v_lshl_or_b32 v210, s96, 8, v234
	s_add_u32 s94, s1, s5
	v_ashrrev_i32_e32 v207, 31, v206
	s_addc_u32 s95, s0, s4
	v_ashrrev_i32_e32 v211, 31, v210
	s_mov_b64 s[0:1], -1
	v_readfirstlane_b32 s98, v219
	s_nop 1
	s_bitcmp1_b32 s98, 8
	s_cbranch_scc1 .Lresync_x_719
	s_barrier
.Lresync_x_719:
	s_and_b64 vcc, exec, s[78:79]
	v_mul_lo_u32 v208, s13, v206
	v_mul_lo_u32 v236, s12, v207
	v_or_b32_e32 v239, 16, v206
	v_or_b32_e32 v238, 32, v206
	v_or_b32_e32 v237, 48, v206
	s_cbranch_vccz .LBB0_722
	s_lshl_b64 s[0:1], s[94:95], 2
	v_readlane_b32 s4, v254, 7
	v_readlane_b32 s5, v254, 8
	s_add_u32 s0, s4, s0
	s_addc_u32 s1, s5, s1
	v_lshl_add_u64 v[154:155], v[210:211], 2, s[0:1]
	v_mad_u64_u32 v[212:213], s[0:1], s12, v206, 0
	v_mul_lo_u32 v124, s13, v239
	v_mad_u64_u32 v[122:123], s[0:1], s12, v239, 0
	v_mul_lo_u32 v140, s13, v238
	v_mad_u64_u32 v[138:139], s[0:1], s12, v238, 0
	v_mul_lo_u32 v158, s13, v237
	v_mad_u64_u32 v[156:157], s[0:1], s12, v237, 0
	v_add3_u32 v213, v213, v236, v208
	v_add3_u32 v123, v123, v236, v124
	v_add3_u32 v139, v139, v236, v140
	v_add3_u32 v157, v157, v236, v158
	v_lshl_add_u64 v[118:119], v[212:213], 2, v[154:155]
	v_lshl_add_u64 v[134:135], v[122:123], 2, v[154:155]
	v_lshl_add_u64 v[150:151], v[138:139], 2, v[154:155]
	v_lshl_add_u64 v[170:171], v[156:157], 2, v[154:155]
	flat_load_dwordx4 v[106:109], v[118:119]
	flat_load_dwordx4 v[110:113], v[118:119] offset:16
	flat_load_dwordx4 v[114:117], v[118:119] offset:512
	s_nop 0
	flat_load_dwordx4 v[118:121], v[118:119] offset:528
	s_nop 0
	flat_load_dwordx4 v[122:125], v[134:135]
	flat_load_dwordx4 v[126:129], v[134:135] offset:16
	flat_load_dwordx4 v[130:133], v[134:135] offset:512
	s_nop 0
	flat_load_dwordx4 v[134:137], v[134:135] offset:528
	s_nop 0
	flat_load_dwordx4 v[138:141], v[150:151]
	flat_load_dwordx4 v[142:145], v[150:151] offset:16
	flat_load_dwordx4 v[146:149], v[150:151] offset:512
	s_nop 0
	flat_load_dwordx4 v[150:153], v[150:151] offset:528
	s_nop 0
	flat_load_dwordx4 v[154:157], v[170:171]
	flat_load_dwordx4 v[158:161], v[170:171] offset:16
	flat_load_dwordx4 v[166:169], v[170:171] offset:512
	s_nop 0
	flat_load_dwordx4 v[170:173], v[170:171] offset:528
	s_mov_b64 s[0:1], 0

; #define PG8_STAGE(bufoff, gbase, voff) do { _Pragma("unroll") for (int _i = 0; _i < 2; ++_i) \
;         __builtin_amdgcn_global_load_lds((const unsigned*)((const char*)(gbase) + (voff)[_i]), (LAS unsigned*)(lds + (bufoff) + ldsw + _i * 8192), 16, 0, 0); } while (0)
; #define PG8_LDA(dst, b, h) do { _Pragma("unroll") for (int m = 0; m < 4; ++m) _Pragma("unroll") for (int k = 0; k < 2; ++k) dst[m][k] = *(const LAS bf16x8*)(lds + PG8_SA(b, h) + aoff + m * 2048 + k * 1024); } while (0)
; #define PG8_LDB(dst, b, h) do { _Pragma("unroll") for (int n = 0; n < 2; ++n) _Pragma("unroll") for (int k = 0; k < 2; ++k) dst[n][k] = *(const LAS bf16x8*)(lds + PG8_SB(b, h) + boff + n * 2048 + k * 1024); } while (0)
; #define PG8_MMA(ai, bj, At, Bt) do { __builtin_amdgcn_s_setprio(1); _Pragma("unroll") for (int m = 0; m < 4; ++m) _Pragma("unroll") for (int n = 0; n < 2; ++n) _Pragma("unroll") for (int k = 0; k < 2; ++k) \
;         acc[ai][bj][m][n] = __builtin_amdgcn_mfma_f32_16x16x32_bf16(Bt[n][k], At[m][k], acc[ai][bj][m][n], 0, 0, 0); __builtin_amdgcn_s_setprio(0); } while (0)
; #define PG8_WAIT_V(n) asm volatile("s_waitcnt vmcnt(" #n ")" ::: "memory")
; #define PG8_WAIT_L(n) asm volatile("s_waitcnt lgkmcnt(" #n ")" ::: "memory")
; template <class Epi>
; __device__ __forceinline__ void gemm_phase(LAS unsigned char* lds, const Gemm g, const Sched& S, const Epi& E) {
;     ...
;         for (int t = 0; t < nt; t += 2) {
;             const bool last = (t == nt - 2);
;             const char* a1 = cA + (size_t)(t + 1) * kstep;
;             const char* a2 = last ? nA : cA + (size_t)(t + 2) * kstep; const char* b2 = last ? nB : cB + (size_t)(t + 2) * kstep;
;             const char* a3 = a2 + kstep; const char* b3 = b2 + kstep;
;             PG8_LDB(B0, 0, 0); PG8_SCHED; PG8_LDA(At, 0, 0); PG8_STAGE(PG8_SA(1, 1), a1 + hstepA, voffA);
;             PG8_WAIT_L(8); PG8_BAR; PG8_WAIT_L(0); PG8_MMA(0, 0, At, B0); PG8_BAR; PG8_SCHED;
;             PG8_LDB(B1, 0, 1); PG8_STAGE(PG8_SB(0, 0), b2, voffB);
;             PG8_BAR; PG8_WAIT_L(0); PG8_MMA(0, 1, At, B1); PG8_BAR;
;             PG8_LDA(At, 0, 1); PG8_STAGE(PG8_SA(0, 0), a2, voffA);
;             PG8_BAR; PG8_WAIT_L(0); PG8_MMA(1, 0, At, B0); PG8_BAR; PG8_SCHED;
;             PG8_STAGE(PG8_SB(0, 1), b2 + hstepB, voffB);
;             PG8_WAIT_V(6); PG8_BAR; PG8_MMA(1, 1, At, B1); PG8_BAR;
.Lresync_y_825:
.LBB0_825:
	s_add_i32 s86, s68, 2
	s_add_u32 s70, s4, 0x80
	s_addc_u32 s69, s5, 0
	s_add_i32 s87, 0, 0x10000
	v_add_u32_e32 v144, s87, v145
	ds_read_b128 v[152:155], v144
	ds_read_b128 v[156:159], v144 offset:1024
	ds_read_b128 v[160:163], v144 offset:2048
	ds_read_b128 v[164:167], v144 offset:3072
	s_cmp_eq_u32 s77, s68
	s_cselect_b32 s68, s59, s70
	s_cselect_b32 s69, s57, s69
	s_cselect_b32 s71, s82, s85
	s_cselect_b32 s70, s83, s84
	v_lshl_add_u64 v[192:193], s[4:5], 0, v[136:137]
	s_add_i32 m0, s33, 0xc000
	ds_read_b128 v[168:171], v151
	ds_read_b128 v[172:175], v151 offset:1024
	ds_read_b128 v[176:179], v151 offset:2048
	ds_read_b128 v[180:183], v151 offset:3072
	ds_read_b128 v[184:187], v151 offset:4096
	ds_read_b128 v[188:191], v151 offset:5120
	ds_read_b128 v[196:199], v151 offset:6144
	ds_read_b128 v[200:203], v151 offset:7168
	global_load_lds_dwordx4 v[192:193], off
	v_lshl_add_u64 v[192:193], s[4:5], 0, v[138:139]
	s_add_i32 m0, s33, 0xe000
	s_nop 0
	global_load_lds_dwordx4 v[192:193], off
	s_add_i32 s88, 0, 0x14000
	v_add_u32_e32 v144, s88, v145
	ds_read_b128 v[204:207], v144
	ds_read_b128 v[208:211], v144 offset:1024
	ds_read_b128 v[212:215], v144 offset:2048
	ds_read_b128 v[234:237], v144 offset:3072
	s_waitcnt vmcnt(8)
	s_waitcnt lgkmcnt(0)
	v_mfma_f32_16x16x32_bf16 v[126:129], v[152:155], v[168:171], v[126:129]
	v_mfma_f32_16x16x32_bf16 v[122:125], v[160:163], v[168:171], v[122:125]
	v_mfma_f32_16x16x32_bf16 v[110:113], v[152:155], v[176:179], v[110:113]
	v_mfma_f32_16x16x32_bf16 v[106:109], v[160:163], v[176:179], v[106:109]
	s_barrier
	s_setprio 1
	v_mfma_f32_16x16x32_bf16 v[94:97], v[152:155], v[184:187], v[94:97]
	v_mfma_f32_16x16x32_bf16 v[90:93], v[160:163], v[184:187], v[90:93]
	v_mfma_f32_16x16x32_bf16 v[78:81], v[152:155], v[196:199], v[78:81]
	v_mfma_f32_16x16x32_bf16 v[74:77], v[160:163], v[196:199], v[74:77]
	v_mfma_f32_16x16x32_bf16 v[126:129], v[156:159], v[172:175], v[126:129]
	v_mfma_f32_16x16x32_bf16 v[122:125], v[164:167], v[172:175], v[122:125]
	v_mfma_f32_16x16x32_bf16 v[110:113], v[156:159], v[180:183], v[110:113]
	v_mfma_f32_16x16x32_bf16 v[106:109], v[164:167], v[180:183], v[106:109]
	v_mfma_f32_16x16x32_bf16 v[94:97], v[156:159], v[188:191], v[94:97]
	v_mfma_f32_16x16x32_bf16 v[90:93], v[164:167], v[188:191], v[90:93]
	v_mfma_f32_16x16x32_bf16 v[78:81], v[156:159], v[200:203], v[78:81]
	v_mfma_f32_16x16x32_bf16 v[74:77], v[164:167], v[200:203], v[74:77]
	v_mfma_f32_16x16x32_bf16 v[118:121], v[204:207], v[168:171], v[118:121]
	v_mfma_f32_16x16x32_bf16 v[114:117], v[212:215], v[168:171], v[114:117]
	v_mfma_f32_16x16x32_bf16 v[102:105], v[204:207], v[176:179], v[102:105]
	v_mfma_f32_16x16x32_bf16 v[98:101], v[212:215], v[176:179], v[98:101]
	v_mfma_f32_16x16x32_bf16 v[86:89], v[204:207], v[184:187], v[86:89]
	v_mfma_f32_16x16x32_bf16 v[82:85], v[212:215], v[184:187], v[82:85]
	v_mfma_f32_16x16x32_bf16 v[70:73], v[204:207], v[196:199], v[70:73]
	v_mfma_f32_16x16x32_bf16 v[66:69], v[212:215], v[196:199], v[66:69]
	v_mfma_f32_16x16x32_bf16 v[118:121], v[208:211], v[172:175], v[118:121]
	v_mfma_f32_16x16x32_bf16 v[114:117], v[234:237], v[172:175], v[114:117]
	v_mfma_f32_16x16x32_bf16 v[102:105], v[208:211], v[180:183], v[102:105]
	v_mfma_f32_16x16x32_bf16 v[98:101], v[234:237], v[180:183], v[98:101]
	v_mfma_f32_16x16x32_bf16 v[86:89], v[208:211], v[188:191], v[86:89]
	v_mfma_f32_16x16x32_bf16 v[82:85], v[234:237], v[188:191], v[82:85]
	v_mfma_f32_16x16x32_bf16 v[70:73], v[208:211], v[200:203], v[70:73]
	v_mfma_f32_16x16x32_bf16 v[66:69], v[234:237], v[200:203], v[66:69]
	s_setprio 0
	s_barrier
	s_add_i32 s87, s87, s51
	v_lshl_add_u64 v[192:193], s[70:71], 0, v[0:1]
	s_mov_b32 m0, s87
	s_nop 0
	global_load_lds_dwordx4 v[192:193], off
	v_lshl_add_u64 v[216:217], s[70:71], 0, v[134:135]
	s_add_i32 m0, s87, 0x2000
	s_nop 0
	global_load_lds_dwordx4 v[216:217], off
	s_mov_b32 m0, s33
	v_lshl_add_u64 v[222:223], s[68:69], 0, v[130:131]
	ds_read_b128 v[168:171], v151 offset:16384
	ds_read_b128 v[172:175], v151 offset:17408
	ds_read_b128 v[176:179], v151 offset:18432
	ds_read_b128 v[180:183], v151 offset:19456
	ds_read_b128 v[184:187], v151 offset:20480
	ds_read_b128 v[188:191], v151 offset:21504
	ds_read_b128 v[196:199], v151 offset:22528
	ds_read_b128 v[200:203], v151 offset:23552
	global_load_lds_dwordx4 v[222:223], off
	v_lshl_add_u64 v[224:225], s[68:69], 0, v[132:133]
	s_mov_b32 m0, s48
	s_nop 0
	global_load_lds_dwordx4 v[224:225], off
	s_add_u32 s70, s70, s14
	s_addc_u32 s71, s71, s15
	s_add_i32 s87, s88, s51
	v_lshl_add_u64 v[226:227], s[70:71], 0, v[0:1]
	s_mov_b32 m0, s87
	v_lshl_add_u64 v[228:229], s[70:71], 0, v[134:135]
	global_load_lds_dwordx4 v[226:227], off
	s_add_i32 m0, s87, 0x2000
	s_nop 0
	global_load_lds_dwordx4 v[228:229], off
	s_waitcnt vmcnt(8)
	s_waitcnt lgkmcnt(0)
	v_mfma_f32_16x16x32_bf16 v[62:65], v[152:155], v[168:171], v[62:65]
	v_mfma_f32_16x16x32_bf16 v[58:61], v[160:163], v[168:171], v[58:61]
	v_mfma_f32_16x16x32_bf16 v[46:49], v[152:155], v[176:179], v[46:49]
	v_mfma_f32_16x16x32_bf16 v[42:45], v[160:163], v[176:179], v[42:45]
	s_barrier
; #define PG8_STAGE(bufoff, gbase, voff) do { _Pragma("unroll") for (int _i = 0; _i < 2; ++_i) \
;         __builtin_amdgcn_global_load_lds((const unsigned*)((const char*)(gbase) + (voff)[_i]), (LAS unsigned*)(lds + (bufoff) + ldsw + _i * 8192), 16, 0, 0); } while (0)
; #define PG8_LDA(dst, b, h) do { _Pragma("unroll") for (int m = 0; m < 4; ++m) _Pragma("unroll") for (int k = 0; k < 2; ++k) dst[m][k] = *(const LAS bf16x8*)(lds + PG8_SA(b, h) + aoff + m * 2048 + k * 1024); } while (0)
; #define PG8_LDB(dst, b, h) do { _Pragma("unroll") for (int n = 0; n < 2; ++n) _Pragma("unroll") for (int k = 0; k < 2; ++k) dst[n][k] = *(const LAS bf16x8*)(lds + PG8_SB(b, h) + boff + n * 2048 + k * 1024); } while (0)
; #define PG8_MMA(ai, bj, At, Bt) do { __builtin_amdgcn_s_setprio(1); _Pragma("unroll") for (int m = 0; m < 4; ++m) _Pragma("unroll") for (int n = 0; n < 2; ++n) _Pragma("unroll") for (int k = 0; k < 2; ++k) \
;         acc[ai][bj][m][n] = __builtin_amdgcn_mfma_f32_16x16x32_bf16(Bt[n][k], At[m][k], acc[ai][bj][m][n], 0, 0, 0); __builtin_amdgcn_s_setprio(0); } while (0)
; #define PG8_WAIT_V(n) asm volatile("s_waitcnt vmcnt(" #n ")" ::: "memory")
; #define PG8_WAIT_L(n) asm volatile("s_waitcnt lgkmcnt(" #n ")" ::: "memory")
; #define PG8_BAR __builtin_amdgcn_s_barrier()
; #define PG8_SCHED __builtin_amdgcn_sched_barrier(0)
; template <class Epi>
; __device__ __forceinline__ void gemm_phase(LAS unsigned char* lds, const Gemm g, const Sched& S, const Epi& E) {
;     ...
;             PG8_WAIT_V(6); PG8_BAR; PG8_MMA(1, 1, At, B1); PG8_BAR;
;             PG8_LDB(B0, 1, 0); PG8_SCHED; PG8_LDA(At, 1, 0); PG8_STAGE(PG8_SA(0, 1), a2 + hstepA, voffA);
;             PG8_WAIT_L(8); PG8_BAR; PG8_WAIT_L(0); PG8_MMA(0, 0, At, B0); PG8_BAR; PG8_SCHED;
;             PG8_LDB(B1, 1, 1); PG8_STAGE(PG8_SB(1, 0), b3, voffB);
;             PG8_BAR; PG8_WAIT_L(0); PG8_MMA(0, 1, At, B1); PG8_BAR;
	s_setprio 1
	v_mfma_f32_16x16x32_bf16 v[30:33], v[152:155], v[184:187], v[30:33]
	v_mfma_f32_16x16x32_bf16 v[26:29], v[160:163], v[184:187], v[26:29]
	v_mfma_f32_16x16x32_bf16 v[14:17], v[152:155], v[196:199], v[14:17]
	v_mfma_f32_16x16x32_bf16 v[10:13], v[160:163], v[196:199], v[10:13]
	v_mfma_f32_16x16x32_bf16 v[62:65], v[156:159], v[172:175], v[62:65]
	v_mfma_f32_16x16x32_bf16 v[58:61], v[164:167], v[172:175], v[58:61]
	v_mfma_f32_16x16x32_bf16 v[46:49], v[156:159], v[180:183], v[46:49]
	v_mfma_f32_16x16x32_bf16 v[42:45], v[164:167], v[180:183], v[42:45]
	v_mfma_f32_16x16x32_bf16 v[30:33], v[156:159], v[188:191], v[30:33]
	v_mfma_f32_16x16x32_bf16 v[26:29], v[164:167], v[188:191], v[26:29]
	v_mfma_f32_16x16x32_bf16 v[14:17], v[156:159], v[200:203], v[14:17]
	v_mfma_f32_16x16x32_bf16 v[10:13], v[164:167], v[200:203], v[10:13]
	v_mfma_f32_16x16x32_bf16 v[54:57], v[204:207], v[168:171], v[54:57]
	v_mfma_f32_16x16x32_bf16 v[50:53], v[212:215], v[168:171], v[50:53]
	v_mfma_f32_16x16x32_bf16 v[38:41], v[204:207], v[176:179], v[38:41]
	v_mfma_f32_16x16x32_bf16 v[34:37], v[212:215], v[176:179], v[34:37]
	v_mfma_f32_16x16x32_bf16 v[22:25], v[204:207], v[184:187], v[22:25]
	v_mfma_f32_16x16x32_bf16 v[18:21], v[212:215], v[184:187], v[18:21]
	v_mfma_f32_16x16x32_bf16 v[6:9], v[204:207], v[196:199], v[6:9]
	v_mfma_f32_16x16x32_bf16 v[2:5], v[212:215], v[196:199], v[2:5]
	v_mfma_f32_16x16x32_bf16 v[54:57], v[208:211], v[172:175], v[54:57]
	v_mfma_f32_16x16x32_bf16 v[50:53], v[234:237], v[172:175], v[50:53]
	v_mfma_f32_16x16x32_bf16 v[38:41], v[208:211], v[180:183], v[38:41]
	v_mfma_f32_16x16x32_bf16 v[34:37], v[234:237], v[180:183], v[34:37]
	v_mfma_f32_16x16x32_bf16 v[22:25], v[208:211], v[188:191], v[22:25]
	v_mfma_f32_16x16x32_bf16 v[18:21], v[234:237], v[188:191], v[18:21]
	v_mfma_f32_16x16x32_bf16 v[6:9], v[208:211], v[200:203], v[6:9]
	v_mfma_f32_16x16x32_bf16 v[2:5], v[234:237], v[200:203], v[2:5]
	s_setprio 0
	s_barrier
	s_add_i32 s70, 0, 0x18000
	v_add_u32_e32 v144, s70, v145
	ds_read_b128 v[152:155], v144
	ds_read_b128 v[156:159], v144 offset:1024
	ds_read_b128 v[160:163], v144 offset:2048
	ds_read_b128 v[164:167], v144 offset:3072
	s_add_u32 s68, s68, s6
	s_addc_u32 s69, s69, s7
	s_mov_b32 m0, s58
	v_lshl_add_u64 v[204:205], s[68:69], 0, v[130:131]
	ds_read_b128 v[168:171], v151 offset:32768
	ds_read_b128 v[172:175], v151 offset:33792
	ds_read_b128 v[176:179], v151 offset:34816
	ds_read_b128 v[180:183], v151 offset:35840
	ds_read_b128 v[184:187], v151 offset:36864
	ds_read_b128 v[188:191], v151 offset:37888
	ds_read_b128 v[196:199], v151 offset:38912
	ds_read_b128 v[200:203], v151 offset:39936
	global_load_lds_dwordx4 v[204:205], off
	v_lshl_add_u64 v[204:205], s[68:69], 0, v[132:133]
	s_mov_b32 m0, s72
	s_nop 0
	global_load_lds_dwordx4 v[204:205], off
	s_add_i32 s68, 0, 0x1c000
	v_add_u32_e32 v144, s68, v145
	ds_read_b128 v[204:207], v144
	ds_read_b128 v[208:211], v144 offset:1024
	ds_read_b128 v[212:215], v144 offset:2048
	ds_read_b128 v[234:237], v144 offset:3072
	s_waitcnt vmcnt(8)
	s_waitcnt lgkmcnt(0)
	v_mfma_f32_16x16x32_bf16 v[126:129], v[152:155], v[168:171], v[126:129]
	v_mfma_f32_16x16x32_bf16 v[122:125], v[160:163], v[168:171], v[122:125]
	v_mfma_f32_16x16x32_bf16 v[110:113], v[152:155], v[176:179], v[110:113]
	v_mfma_f32_16x16x32_bf16 v[106:109], v[160:163], v[176:179], v[106:109]
	s_barrier
	s_setprio 1
	v_mfma_f32_16x16x32_bf16 v[94:97], v[152:155], v[184:187], v[94:97]
	v_mfma_f32_16x16x32_bf16 v[90:93], v[160:163], v[184:187], v[90:93]
	v_mfma_f32_16x16x32_bf16 v[78:81], v[152:155], v[196:199], v[78:81]
	v_mfma_f32_16x16x32_bf16 v[74:77], v[160:163], v[196:199], v[74:77]
	v_mfma_f32_16x16x32_bf16 v[126:129], v[156:159], v[172:175], v[126:129]
	v_mfma_f32_16x16x32_bf16 v[122:125], v[164:167], v[172:175], v[122:125]
	v_mfma_f32_16x16x32_bf16 v[110:113], v[156:159], v[180:183], v[110:113]
	v_mfma_f32_16x16x32_bf16 v[106:109], v[164:167], v[180:183], v[106:109]
	v_mfma_f32_16x16x32_bf16 v[94:97], v[156:159], v[188:191], v[94:97]
	v_mfma_f32_16x16x32_bf16 v[90:93], v[164:167], v[188:191], v[90:93]
	v_mfma_f32_16x16x32_bf16 v[78:81], v[156:159], v[200:203], v[78:81]
	v_mfma_f32_16x16x32_bf16 v[74:77], v[164:167], v[200:203], v[74:77]
	v_mfma_f32_16x16x32_bf16 v[118:121], v[204:207], v[168:171], v[118:121]
	v_mfma_f32_16x16x32_bf16 v[114:117], v[212:215], v[168:171], v[114:117]
	v_mfma_f32_16x16x32_bf16 v[102:105], v[204:207], v[176:179], v[102:105]
	v_mfma_f32_16x16x32_bf16 v[98:101], v[212:215], v[176:179], v[98:101]
	v_mfma_f32_16x16x32_bf16 v[86:89], v[204:207], v[184:187], v[86:89]
	v_mfma_f32_16x16x32_bf16 v[82:85], v[212:215], v[184:187], v[82:85]
	v_mfma_f32_16x16x32_bf16 v[70:73], v[204:207], v[196:199], v[70:73]
	v_mfma_f32_16x16x32_bf16 v[66:69], v[212:215], v[196:199], v[66:69]
	v_mfma_f32_16x16x32_bf16 v[118:121], v[208:211], v[172:175], v[118:121]
	v_mfma_f32_16x16x32_bf16 v[114:117], v[234:237], v[172:175], v[114:117]
	v_mfma_f32_16x16x32_bf16 v[102:105], v[208:211], v[180:183], v[102:105]
	v_mfma_f32_16x16x32_bf16 v[98:101], v[234:237], v[180:183], v[98:101]
	v_mfma_f32_16x16x32_bf16 v[86:89], v[208:211], v[188:191], v[86:89]
	v_mfma_f32_16x16x32_bf16 v[82:85], v[234:237], v[188:191], v[82:85]
	v_mfma_f32_16x16x32_bf16 v[70:73], v[208:211], v[200:203], v[70:73]
	v_mfma_f32_16x16x32_bf16 v[66:69], v[234:237], v[200:203], v[66:69]
	s_setprio 0
	s_barrier
; __device__ __forceinline__ float pre_get(const Pre& p, int ai, int m, int fr) { return __shfl(p.v[ai], m * 16 + fr); }
; __device__ __forceinline__ float rstd_pre(const float* ss, float v) { return ss ? rsqrtf(v * (1.0f / 2048.0f) + 1e-6f) : 1.0f; }
; #define PG8_STAGE(bufoff, gbase, voff) do { _Pragma("unroll") for (int _i = 0; _i < 2; ++_i) \
;         __builtin_amdgcn_global_load_lds((const unsigned*)((const char*)(gbase) + (voff)[_i]), (LAS unsigned*)(lds + (bufoff) + ldsw + _i * 8192), 16, 0, 0); } while (0)
; #define PG8_LDA(dst, b, h) do { _Pragma("unroll") for (int m = 0; m < 4; ++m) _Pragma("unroll") for (int k = 0; k < 2; ++k) dst[m][k] = *(const LAS bf16x8*)(lds + PG8_SA(b, h) + aoff + m * 2048 + k * 1024); } while (0)
; #define PG8_MMA(ai, bj, At, Bt) do { __builtin_amdgcn_s_setprio(1); _Pragma("unroll") for (int m = 0; m < 4; ++m) _Pragma("unroll") for (int n = 0; n < 2; ++n) _Pragma("unroll") for (int k = 0; k < 2; ++k) \
;         acc[ai][bj][m][n] = __builtin_amdgcn_mfma_f32_16x16x32_bf16(Bt[n][k], At[m][k], acc[ai][bj][m][n], 0, 0, 0); __builtin_amdgcn_s_setprio(0); } while (0)
; #define PG8_WAIT_V(n) asm volatile("s_waitcnt vmcnt(" #n ")" ::: "memory")
; #define PG8_WAIT_L(n) asm volatile("s_waitcnt lgkmcnt(" #n ")" ::: "memory")
; #define PG8_BAR __builtin_amdgcn_s_barrier()
; #define PG8_SCHED __builtin_amdgcn_sched_barrier(0)
; template <class Epi>
; __device__ __forceinline__ void gemm_phase(LAS unsigned char* lds, const Gemm g, const Sched& S, const Epi& E) {
;     ...
;             PG8_LDA(At, 1, 1); PG8_STAGE(PG8_SA(1, 0), a3, voffA);
;             PG8_BAR; PG8_WAIT_L(0); PG8_MMA(1, 0, At, B0); PG8_BAR; PG8_SCHED;
;             PG8_STAGE(PG8_SB(1, 1), b3 + hstepB, voffB);
;             PG8_WAIT_V(6); PG8_BAR; PG8_MMA(1, 1, At, B1); PG8_BAR;
;         }
;     __device__ __forceinline__ Pre prefetch(const Unit& u, int wr, int fr) const { return pre_rows(ss, u.pm * 256 + wr * 64 + (int)(threadIdx.x & 63)); }
;     __device__ __forceinline__ void operator()(const Acc& acc, const Unit& u, int wr, int wc, int fr, int fq, const Pre& pre) const {
;         const int row0 = u.pm * 256 + wr * 64 + fr, col0 = u.pn * 128 + wc * 32 + 8 * fq;
;         float rsq[2][4];
; #pragma unroll
;         for (int ai = 0; ai < 2; ++ai)
; #pragma unroll
;             for (int m = 0; m < 4; ++m) rsq[ai][m] = rstd_pre(ss, pre_get(pre, ai, m, fr));
	s_add_i32 s69, s70, s51
	v_lshl_add_u64 v[192:193], v[192:193], 0, s[60:61]
	s_mov_b32 m0, s69
	s_nop 0
	global_load_lds_dwordx4 v[192:193], off
	v_lshl_add_u64 v[192:193], v[216:217], 0, s[60:61]
	s_add_i32 m0, s69, 0x2000
	s_nop 0
	global_load_lds_dwordx4 v[192:193], off
	s_mov_b32 m0, s75
	v_lshl_add_u64 v[192:193], v[222:223], 0, s[60:61]
	ds_read_b128 v[168:171], v151 offset:49152
	ds_read_b128 v[172:175], v151 offset:50176
	ds_read_b128 v[176:179], v151 offset:51200
	ds_read_b128 v[180:183], v151 offset:52224
	ds_read_b128 v[184:187], v151 offset:53248
	ds_read_b128 v[188:191], v151 offset:54272
	ds_read_b128 v[196:199], v151 offset:55296
	ds_read_b128 v[200:203], v151 offset:56320
	global_load_lds_dwordx4 v[192:193], off
	v_lshl_add_u64 v[192:193], v[224:225], 0, s[60:61]
	s_mov_b32 m0, s76
	s_nop 0
	global_load_lds_dwordx4 v[192:193], off
	s_add_i32 s68, s68, s51
	v_lshl_add_u64 v[192:193], v[226:227], 0, s[60:61]
	s_mov_b32 m0, s68
	s_nop 0
	global_load_lds_dwordx4 v[192:193], off
	v_lshl_add_u64 v[192:193], v[228:229], 0, s[60:61]
	s_add_i32 m0, s68, 0x2000
	s_nop 0
	global_load_lds_dwordx4 v[192:193], off
	s_waitcnt vmcnt(8)
	s_waitcnt lgkmcnt(0)
	v_mfma_f32_16x16x32_bf16 v[62:65], v[152:155], v[168:171], v[62:65]
	v_mfma_f32_16x16x32_bf16 v[58:61], v[160:163], v[168:171], v[58:61]
	v_mfma_f32_16x16x32_bf16 v[46:49], v[152:155], v[176:179], v[46:49]
	v_mfma_f32_16x16x32_bf16 v[42:45], v[160:163], v[176:179], v[42:45]
	s_barrier
	s_setprio 1
	v_mfma_f32_16x16x32_bf16 v[30:33], v[152:155], v[184:187], v[30:33]
	v_mfma_f32_16x16x32_bf16 v[26:29], v[160:163], v[184:187], v[26:29]
	v_mfma_f32_16x16x32_bf16 v[14:17], v[152:155], v[196:199], v[14:17]
	v_mfma_f32_16x16x32_bf16 v[10:13], v[160:163], v[196:199], v[10:13]
	v_mfma_f32_16x16x32_bf16 v[62:65], v[156:159], v[172:175], v[62:65]
	v_mfma_f32_16x16x32_bf16 v[58:61], v[164:167], v[172:175], v[58:61]
	v_mfma_f32_16x16x32_bf16 v[46:49], v[156:159], v[180:183], v[46:49]
	v_mfma_f32_16x16x32_bf16 v[42:45], v[164:167], v[180:183], v[42:45]
	v_mfma_f32_16x16x32_bf16 v[30:33], v[156:159], v[188:191], v[30:33]
	v_mfma_f32_16x16x32_bf16 v[26:29], v[164:167], v[188:191], v[26:29]
	v_mfma_f32_16x16x32_bf16 v[14:17], v[156:159], v[200:203], v[14:17]
	v_mfma_f32_16x16x32_bf16 v[10:13], v[164:167], v[200:203], v[10:13]
	v_mfma_f32_16x16x32_bf16 v[54:57], v[204:207], v[168:171], v[54:57]
	v_mfma_f32_16x16x32_bf16 v[50:53], v[212:215], v[168:171], v[50:53]
	v_mfma_f32_16x16x32_bf16 v[38:41], v[204:207], v[176:179], v[38:41]
	v_mfma_f32_16x16x32_bf16 v[34:37], v[212:215], v[176:179], v[34:37]
	v_mfma_f32_16x16x32_bf16 v[22:25], v[204:207], v[184:187], v[22:25]
	v_mfma_f32_16x16x32_bf16 v[18:21], v[212:215], v[184:187], v[18:21]
	v_mfma_f32_16x16x32_bf16 v[6:9], v[204:207], v[196:199], v[6:9]
	v_mfma_f32_16x16x32_bf16 v[2:5], v[212:215], v[196:199], v[2:5]
	v_mfma_f32_16x16x32_bf16 v[54:57], v[208:211], v[172:175], v[54:57]
	v_mfma_f32_16x16x32_bf16 v[50:53], v[234:237], v[172:175], v[50:53]
	v_mfma_f32_16x16x32_bf16 v[38:41], v[208:211], v[180:183], v[38:41]
	v_mfma_f32_16x16x32_bf16 v[34:37], v[234:237], v[180:183], v[34:37]
	v_mfma_f32_16x16x32_bf16 v[22:25], v[208:211], v[188:191], v[22:25]
	v_mfma_f32_16x16x32_bf16 v[18:21], v[234:237], v[188:191], v[18:21]
	v_mfma_f32_16x16x32_bf16 v[6:9], v[208:211], v[200:203], v[6:9]
	v_mfma_f32_16x16x32_bf16 v[2:5], v[234:237], v[200:203], v[2:5]
	s_setprio 0
	s_add_u32 s4, s4, 0x100
	s_addc_u32 s5, s5, 0
	s_add_u32 s84, s84, 0x100
	s_addc_u32 s85, s85, 0
	s_cmp_ge_u32 s86, s73
	s_mov_b32 s68, s86
	s_barrier
	s_cbranch_scc0 .LBB0_825
	v_and_or_b32 v144, v220, 64, v141
	v_lshlrev_b32_e32 v160, 2, v144
	ds_bpermute_b32 v155, v160, v142
	ds_bpermute_b32 v154, v160, v142 offset:64
	s_mov_b32 s4, 0x358637bd
	v_mov_b64_e32 v[156:157], s[4:5]
	s_mov_b32 s8, 0x3a000000
	v_lshl_add_u32 v153, s81, 8, v143
	s_waitcnt lgkmcnt(0)
	v_pk_fma_f32 v[158:159], v[154:155], s[8:9], v[156:157] op_sel_hi:[1,0,0]
	s_mov_b32 s81, s80
	v_mul_f32_e32 v144, 0x4b800000, v159
	v_cmp_gt_f32_e64 s[4:5], s97, v159
	v_cmp_gt_f32_e32 vcc, s97, v158
	s_mov_b64 s[68:69], s[66:67]
	v_cndmask_b32_e64 v144, v159, v144, s[4:5]
	v_rsq_f32_e32 v144, v144
	ds_bpermute_b32 v159, v160, v142 offset:128
	v_mul_f32_e32 v146, 0x45800000, v144
	v_cndmask_b32_e64 v144, v144, v146, s[4:5]
	v_cndmask_b32_e64 v154, v144, 1.0, s[34:35]
	v_mul_f32_e32 v144, 0x4b800000, v158
	v_cndmask_b32_e32 v144, v158, v144, vcc
	ds_bpermute_b32 v158, v160, v142 offset:192
	v_rsq_f32_e32 v144, v144
	s_waitcnt lgkmcnt(0)
	v_pk_fma_f32 v[158:159], v[158:159], s[8:9], v[156:157] op_sel_hi:[1,0,0]
	s_nop 0
	v_mul_f32_e32 v142, 0x4b800000, v159
	v_cmp_gt_f32_e64 s[4:5], s97, v159
	v_mul_f32_e32 v146, 0x45800000, v144
	v_cndmask_b32_e32 v144, v144, v146, vcc
	v_cndmask_b32_e64 v142, v159, v142, s[4:5]
	v_rsq_f32_e32 v142, v142
	v_cndmask_b32_e64 v152, v144, 1.0, s[34:35]
	v_cmp_gt_f32_e32 vcc, s97, v158
	ds_bpermute_b32 v159, v160, v140
	v_mul_f32_e32 v144, 0x45800000, v142
	v_cndmask_b32_e64 v142, v142, v144, s[4:5]
	v_cndmask_b32_e64 v150, v142, 1.0, s[34:35]
	v_mul_f32_e32 v142, 0x4b800000, v158
	v_cndmask_b32_e32 v142, v158, v142, vcc
	v_rsq_f32_e32 v142, v142
	ds_bpermute_b32 v158, v160, v140 offset:64
	v_pk_mul_f32 v[110:111], v[110:111], v[152:153] op_sel_hi:[1,0]
	v_pk_mul_f32 v[102:103], v[102:103], v[152:153] op_sel_hi:[1,0]
	v_mul_f32_e32 v144, 0x45800000, v142
	v_cndmask_b32_e32 v142, v142, v144, vcc
	s_waitcnt lgkmcnt(0)
; __device__ __forceinline__ float silu_f(float x) { return x * __builtin_amdgcn_rcpf(1.f + __builtin_amdgcn_exp2f(-LOG2E * x)); }
; __device__ __forceinline__ float pre_get(const Pre& p, int ai, int m, int fr) { return __shfl(p.v[ai], m * 16 + fr); }
; __device__ __forceinline__ float rstd_pre(const float* ss, float v) { return ss ? rsqrtf(v * (1.0f / 2048.0f) + 1e-6f) : 1.0f; }
;     __device__ __forceinline__ void operator()(const Acc& acc, const Unit& u, int wr, int wc, int fr, int fq, const Pre& pre) const {
;     ...
;             for (int m = 0; m < 4; ++m) rsq[ai][m] = rstd_pre(ss, pre_get(pre, ai, m, fr));
; #pragma unroll
;         for (int ai = 0; ai < 2; ++ai)
; #pragma unroll
;             for (int m = 0; m < 4; ++m) {
;                 f32x4 v0, v1; const float rs = rsq[ai][m];
; #pragma unroll
;                 for (int e = 0; e < 4; ++e) { v0[e] = silu_f(acc[ai][0][m][0][e] * rs) * (acc[ai][1][m][0][e] * rs); v1[e] = silu_f(acc[ai][0][m][1][e] * rs) * (acc[ai][1][m][1][e] * rs); }
	v_pk_fma_f32 v[158:159], v[158:159], s[8:9], v[156:157] op_sel_hi:[1,0,0]
	v_cndmask_b32_e64 v148, v142, 1.0, s[34:35]
	v_mul_f32_e32 v142, 0x4b800000, v159
	v_cmp_gt_f32_e64 s[4:5], s97, v159
	v_cmp_gt_f32_e32 vcc, s97, v158
	v_pk_mul_f32 v[106:107], v[106:107], v[152:153] op_sel_hi:[1,0]
	v_cndmask_b32_e64 v142, v159, v142, s[4:5]
	v_rsq_f32_e32 v142, v142
	ds_bpermute_b32 v159, v160, v140 offset:128
	v_pk_mul_f32 v[98:99], v[98:99], v[152:153] op_sel_hi:[1,0]
	v_pk_mul_f32 v[104:105], v[104:105], v[152:153] op_sel_hi:[1,0]
	v_mul_f32_e32 v144, 0x45800000, v142
	v_cndmask_b32_e64 v142, v142, v144, s[4:5]
	v_cndmask_b32_e64 v146, v142, 1.0, s[34:35]
	v_mul_f32_e32 v142, 0x4b800000, v158
	v_cndmask_b32_e32 v142, v158, v142, vcc
	ds_bpermute_b32 v158, v160, v140 offset:192
	v_rsq_f32_e32 v142, v142
	v_pk_mul_f32 v[100:101], v[100:101], v[152:153] op_sel_hi:[1,0]
	v_pk_mul_f32 v[94:95], v[94:95], v[150:151] op_sel_hi:[1,0]
	v_pk_mul_f32 v[86:87], v[86:87], v[150:151] op_sel_hi:[1,0]
	s_waitcnt lgkmcnt(0)
	v_pk_fma_f32 v[156:157], v[158:159], s[8:9], v[156:157] op_sel_hi:[1,0,0]
	v_mul_f32_e32 v144, 0x45800000, v142
	v_mul_f32_e32 v140, 0x4b800000, v157
	v_cmp_gt_f32_e64 s[4:5], s97, v157
	v_cndmask_b32_e32 v142, v142, v144, vcc
	v_cndmask_b32_e64 v144, v142, 1.0, s[34:35]
	v_cndmask_b32_e64 v140, v157, v140, s[4:5]
	v_rsq_f32_e32 v140, v140
	v_cmp_gt_f32_e32 vcc, s97, v156
	v_pk_mul_f32 v[90:91], v[90:91], v[150:151] op_sel_hi:[1,0]
	v_pk_mul_f32 v[82:83], v[82:83], v[150:151] op_sel_hi:[1,0]
	v_mul_f32_e32 v142, 0x45800000, v140
	v_cndmask_b32_e64 v140, v140, v142, s[4:5]
	v_cndmask_b32_e64 v142, v140, 1.0, s[34:35]
	v_mul_f32_e32 v140, 0x4b800000, v156
	v_cndmask_b32_e32 v140, v156, v140, vcc
	v_rsq_f32_e32 v140, v140
	v_lshl_or_b32 v156, s55, 7, v149
	v_ashrrev_i32_e32 v157, 31, v156
	v_pk_mul_f32 v[88:89], v[88:89], v[150:151] op_sel_hi:[1,0]
	v_mul_f32_e32 v155, 0x45800000, v140
	v_pk_mul_f32 v[126:127], v[126:127], v[154:155] op_sel_hi:[1,0]
	v_cndmask_b32_e32 v140, v140, v155, vcc
	v_mul_f32_e32 v155, 0xbfb8aa3b, v126
	v_exp_f32_e32 v155, v155
	v_pk_mul_f32 v[84:85], v[84:85], v[150:151] op_sel_hi:[1,0]
	v_pk_mul_f32 v[78:79], v[78:79], v[148:149] op_sel_hi:[1,0]
	v_pk_mul_f32 v[70:71], v[70:71], v[148:149] op_sel_hi:[1,0]
	v_add_f32_e32 v155, 1.0, v155
	v_rcp_f32_e32 v158, v155
	v_mul_f32_e32 v155, 0xbfb8aa3b, v127
	v_exp_f32_e32 v155, v155
	v_pk_mul_f32 v[74:75], v[74:75], v[148:149] op_sel_hi:[1,0]
	v_pk_mul_f32 v[66:67], v[66:67], v[148:149] op_sel_hi:[1,0]
	v_pk_mul_f32 v[72:73], v[72:73], v[148:149] op_sel_hi:[1,0]
	v_add_f32_e32 v155, 1.0, v155
	v_rcp_f32_e32 v159, v155
	v_pk_mul_f32 v[118:119], v[118:119], v[154:155] op_sel_hi:[1,0]
	v_pk_mul_f32 v[122:123], v[122:123], v[154:155] op_sel_hi:[1,0]
	v_readfirstlane_b32 s98, v219
	s_nop 1
	s_bitcmp1_b32 s98, 8
	s_cbranch_scc1 .Lresync_x_825
	s_barrier
.Lresync_x_825:
	v_pk_mul_f32 v[114:115], v[114:115], v[154:155] op_sel_hi:[1,0]
	v_pk_mul_f32 v[126:127], v[126:127], v[158:159]
	v_pk_mul_f32 v[120:121], v[120:121], v[154:155] op_sel_hi:[1,0]
	v_pk_mul_f32 v[118:119], v[118:119], v[126:127]
	v_mul_f32_e32 v126, 0xbfb8aa3b, v122
	v_mul_f32_e32 v127, 0xbfb8aa3b, v123
	v_exp_f32_e32 v126, v126
	v_exp_f32_e32 v127, v127
	v_pk_mul_f32 v[116:117], v[116:117], v[154:155] op_sel_hi:[1,0]
	v_cvt_pk_bf16_f32 v118, v118, v119
	v_add_f32_e32 v126, 1.0, v126
	v_add_f32_e32 v127, 1.0, v127
	v_rcp_f32_e32 v126, v126
	v_rcp_f32_e32 v127, v127
	v_pk_mul_f32 v[68:69], v[68:69], v[148:149] op_sel_hi:[1,0]
	v_pk_mul_f32 v[62:63], v[62:63], v[146:147] op_sel_hi:[1,0]
	v_pk_mul_f32 v[54:55], v[54:55], v[146:147] op_sel_hi:[1,0]
	v_pk_mul_f32 v[122:123], v[122:123], v[126:127]
	v_pk_mul_f32 v[58:59], v[58:59], v[146:147] op_sel_hi:[1,0]
	v_pk_mul_f32 v[114:115], v[114:115], v[122:123]
	v_pk_mul_f32 v[122:123], v[128:129], v[154:155] op_sel_hi:[1,0]
	v_pk_mul_f32 v[50:51], v[50:51], v[146:147] op_sel_hi:[1,0]
	v_mul_f32_e32 v126, 0xbfb8aa3b, v122
	v_mul_f32_e32 v127, 0xbfb8aa3b, v123
	v_exp_f32_e32 v126, v126
	v_exp_f32_e32 v127, v127
	v_pk_mul_f32 v[56:57], v[56:57], v[146:147] op_sel_hi:[1,0]
	v_pk_mul_f32 v[52:53], v[52:53], v[146:147] op_sel_hi:[1,0]
	v_add_f32_e32 v126, 1.0, v126
	v_add_f32_e32 v127, 1.0, v127
	v_rcp_f32_e32 v126, v126
	v_rcp_f32_e32 v127, v127
	v_pk_mul_f32 v[46:47], v[46:47], v[144:145] op_sel_hi:[1,0]
	v_pk_mul_f32 v[38:39], v[38:39], v[144:145] op_sel_hi:[1,0]
	v_pk_mul_f32 v[42:43], v[42:43], v[144:145] op_sel_hi:[1,0]
	v_pk_mul_f32 v[122:123], v[122:123], v[126:127]
	v_pk_mul_f32 v[34:35], v[34:35], v[144:145] op_sel_hi:[1,0]
	v_pk_mul_f32 v[120:121], v[120:121], v[122:123]
	v_pk_mul_f32 v[122:123], v[124:125], v[154:155] op_sel_hi:[1,0]
	v_cvt_pk_bf16_f32 v119, v120, v121
	v_mul_f32_e32 v124, 0xbfb8aa3b, v122
	v_mul_f32_e32 v125, 0xbfb8aa3b, v123
	v_exp_f32_e32 v124, v124
	v_exp_f32_e32 v125, v125
	v_cvt_pk_bf16_f32 v120, v114, v115
	v_ashrrev_i32_e32 v114, 31, v153
	v_add_f32_e32 v124, 1.0, v124
	v_add_f32_e32 v125, 1.0, v125
	v_rcp_f32_e32 v124, v124
	v_rcp_f32_e32 v125, v125
	v_pk_mul_f32 v[40:41], v[40:41], v[144:145] op_sel_hi:[1,0]
	v_pk_mul_f32 v[36:37], v[36:37], v[144:145] op_sel_hi:[1,0]
	v_pk_mul_f32 v[30:31], v[30:31], v[142:143] op_sel_hi:[1,0]
	v_pk_mul_f32 v[122:123], v[122:123], v[124:125]
	v_pk_mul_f32 v[22:23], v[22:23], v[142:143] op_sel_hi:[1,0]
	v_pk_mul_f32 v[116:117], v[116:117], v[122:123]
	v_pk_mul_f32 v[26:27], v[26:27], v[142:143] op_sel_hi:[1,0]
	v_cvt_pk_bf16_f32 v121, v116, v117
	v_mul_lo_u32 v116, s12, v114
	v_mul_lo_u32 v117, s13, v153
	v_mad_u64_u32 v[114:115], s[4:5], s12, v153, 0
	v_add3_u32 v115, v115, v116, v117
	v_mul_f32_e32 v117, 0xbfb8aa3b, v110
; __device__ __forceinline__ float silu_f(float x) { return x * __builtin_amdgcn_rcpf(1.f + __builtin_amdgcn_exp2f(-LOG2E * x)); }
; __device__ __forceinline__ u32x4 pk8(const f32x4 a, const f32x4 b) { u32x4 w; w.x = pk2(a[0], a[1]); w.y = pk2(a[2], a[3]); w.z = pk2(b[0], b[1]); w.w = pk2(b[2], b[3]); return w; }
;     __device__ __forceinline__ void operator()(const Acc& acc, const Unit& u, int wr, int wc, int fr, int fq, const Pre& pre) const {
;     ...
;                 f32x4 v0, v1; const float rs = rsq[ai][m];
; #pragma unroll
;                 for (int e = 0; e < 4; ++e) { v0[e] = silu_f(acc[ai][0][m][0][e] * rs) * (acc[ai][1][m][0][e] * rs); v1[e] = silu_f(acc[ai][0][m][1][e] * rs) * (acc[ai][1][m][1][e] * rs); }
;                 *(u32x4*)(O + (size_t)(row0 + ai * 128 + m * 16) * ldc + col0) = pk8(v0, v1);
	v_exp_f32_e32 v117, v117
	v_lshl_add_u64 v[122:123], v[114:115], 1, s[62:63]
	v_lshlrev_b64 v[114:115], 1, v[156:157]
	v_lshl_add_u64 v[122:123], v[122:123], 0, v[114:115]
	v_add_f32_e32 v117, 1.0, v117
	global_store_dwordx4 v[122:123], v[118:121], off
	v_pk_mul_f32 v[18:19], v[18:19], v[142:143] op_sel_hi:[1,0]
	v_pk_mul_f32 v[24:25], v[24:25], v[142:143] op_sel_hi:[1,0]
	v_rcp_f32_e32 v118, v117
	v_mul_f32_e32 v117, 0xbfb8aa3b, v111
	v_exp_f32_e32 v117, v117
	v_pk_mul_f32 v[20:21], v[20:21], v[142:143] op_sel_hi:[1,0]
	v_cndmask_b32_e64 v140, v140, 1.0, s[34:35]
	v_pk_mul_f32 v[14:15], v[14:15], v[140:141] op_sel_hi:[1,0]
	v_add_f32_e32 v117, 1.0, v117
	v_rcp_f32_e32 v119, v117
	v_pk_mul_f32 v[6:7], v[6:7], v[140:141] op_sel_hi:[1,0]
	v_pk_mul_f32 v[10:11], v[10:11], v[140:141] op_sel_hi:[1,0]
	v_pk_mul_f32 v[2:3], v[2:3], v[140:141] op_sel_hi:[1,0]
	v_pk_mul_f32 v[110:111], v[110:111], v[118:119]
	v_pk_mul_f32 v[8:9], v[8:9], v[140:141] op_sel_hi:[1,0]
	v_pk_mul_f32 v[102:103], v[102:103], v[110:111]
	v_mul_f32_e32 v110, 0xbfb8aa3b, v106
	v_mul_f32_e32 v111, 0xbfb8aa3b, v107
	v_exp_f32_e32 v110, v110
	v_exp_f32_e32 v111, v111
	v_pk_mul_f32 v[4:5], v[4:5], v[140:141] op_sel_hi:[1,0]
	s_and_b64 vcc, exec, s[0:1]
	v_add_f32_e32 v110, 1.0, v110
	v_add_f32_e32 v111, 1.0, v111
	v_rcp_f32_e32 v110, v110
	v_rcp_f32_e32 v111, v111
	s_mov_b32 s55, s79
	v_pk_mul_f32 v[106:107], v[106:107], v[110:111]
	s_nop 0
	v_pk_mul_f32 v[106:107], v[98:99], v[106:107]
	v_pk_mul_f32 v[98:99], v[112:113], v[152:153] op_sel_hi:[1,0]
	s_nop 0
	v_mul_f32_e32 v110, 0xbfb8aa3b, v98
	v_mul_f32_e32 v111, 0xbfb8aa3b, v99
	v_exp_f32_e32 v110, v110
	v_exp_f32_e32 v111, v111
	v_add_f32_e32 v110, 1.0, v110
	v_add_f32_e32 v111, 1.0, v111
	v_rcp_f32_e32 v110, v110
	v_rcp_f32_e32 v111, v111
	s_nop 0
	v_pk_mul_f32 v[98:99], v[98:99], v[110:111]
	s_nop 0
	v_pk_mul_f32 v[104:105], v[104:105], v[98:99]
	v_pk_mul_f32 v[98:99], v[108:109], v[152:153] op_sel_hi:[1,0]
	s_nop 0
	v_mul_f32_e32 v108, 0xbfb8aa3b, v98
	v_mul_f32_e32 v109, 0xbfb8aa3b, v99
	v_exp_f32_e32 v108, v108
	v_exp_f32_e32 v109, v109
	v_add_f32_e32 v108, 1.0, v108
	v_add_f32_e32 v109, 1.0, v109
	v_rcp_f32_e32 v108, v108
	v_rcp_f32_e32 v109, v109
	s_nop 0
	v_pk_mul_f32 v[98:99], v[98:99], v[108:109]
	s_nop 0
	v_pk_mul_f32 v[108:109], v[100:101], v[98:99]
	v_cvt_pk_bf16_f32 v98, v102, v103
	v_or_b32_e32 v102, 16, v153
	v_cvt_pk_bf16_f32 v99, v104, v105
	v_mul_lo_u32 v104, s13, v102
	v_mad_u64_u32 v[102:103], s[4:5], s12, v102, 0
	v_add3_u32 v103, v103, v116, v104
	v_lshl_add_u64 v[102:103], v[102:103], 1, s[62:63]
	v_cvt_pk_bf16_f32 v100, v106, v107
	v_cvt_pk_bf16_f32 v101, v108, v109
	v_lshl_add_u64 v[102:103], v[102:103], 0, v[114:115]
	global_store_dwordx4 v[102:103], v[98:101], off
	s_nop 1
	v_mul_f32_e32 v98, 0xbfb8aa3b, v94
	v_mul_f32_e32 v99, 0xbfb8aa3b, v95
	v_exp_f32_e32 v98, v98
	v_exp_f32_e32 v99, v99
	v_add_f32_e32 v98, 1.0, v98
	v_add_f32_e32 v99, 1.0, v99
	v_rcp_f32_e32 v98, v98
	v_rcp_f32_e32 v99, v99
	s_nop 0
	v_pk_mul_f32 v[94:95], v[94:95], v[98:99]
	s_nop 0
	v_pk_mul_f32 v[86:87], v[86:87], v[94:95]
	v_mul_f32_e32 v94, 0xbfb8aa3b, v90
	v_mul_f32_e32 v95, 0xbfb8aa3b, v91
	v_exp_f32_e32 v94, v94
	v_exp_f32_e32 v95, v95
	v_add_f32_e32 v94, 1.0, v94
	v_add_f32_e32 v95, 1.0, v95
	v_rcp_f32_e32 v94, v94
	v_rcp_f32_e32 v95, v95
	s_nop 0
	v_pk_mul_f32 v[90:91], v[90:91], v[94:95]
	s_nop 0
	v_pk_mul_f32 v[90:91], v[82:83], v[90:91]
	v_pk_mul_f32 v[82:83], v[96:97], v[150:151] op_sel_hi:[1,0]
	s_nop 0
	v_mul_f32_e32 v94, 0xbfb8aa3b, v82
	v_mul_f32_e32 v95, 0xbfb8aa3b, v83
	v_exp_f32_e32 v94, v94
	v_exp_f32_e32 v95, v95
	v_add_f32_e32 v94, 1.0, v94
	v_add_f32_e32 v95, 1.0, v95
	v_rcp_f32_e32 v94, v94
	v_rcp_f32_e32 v95, v95
	s_nop 0
	v_pk_mul_f32 v[82:83], v[82:83], v[94:95]
	s_nop 0
	v_pk_mul_f32 v[88:89], v[88:89], v[82:83]
	v_pk_mul_f32 v[82:83], v[92:93], v[150:151] op_sel_hi:[1,0]
	s_nop 0
	v_mul_f32_e32 v92, 0xbfb8aa3b, v82
	v_mul_f32_e32 v93, 0xbfb8aa3b, v83
	v_exp_f32_e32 v92, v92
	v_exp_f32_e32 v93, v93
	v_add_f32_e32 v92, 1.0, v92
	v_add_f32_e32 v93, 1.0, v93
	v_rcp_f32_e32 v92, v92
	v_rcp_f32_e32 v93, v93
	s_nop 0
	v_pk_mul_f32 v[82:83], v[82:83], v[92:93]
	s_nop 0
	v_pk_mul_f32 v[92:93], v[84:85], v[82:83]
	v_cvt_pk_bf16_f32 v82, v86, v87
	v_or_b32_e32 v86, 32, v153
	v_cvt_pk_bf16_f32 v83, v88, v89
	v_mul_lo_u32 v88, s13, v86
	v_mad_u64_u32 v[86:87], s[4:5], s12, v86, 0
	v_add3_u32 v87, v87, v116, v88
	v_lshl_add_u64 v[86:87], v[86:87], 1, s[62:63]
	v_cvt_pk_bf16_f32 v84, v90, v91
	v_cvt_pk_bf16_f32 v85, v92, v93
	v_lshl_add_u64 v[86:87], v[86:87], 0, v[114:115]
	global_store_dwordx4 v[86:87], v[82:85], off
	s_nop 1
	v_mul_f32_e32 v82, 0xbfb8aa3b, v78
	v_mul_f32_e32 v83, 0xbfb8aa3b, v79
	v_exp_f32_e32 v82, v82
	v_exp_f32_e32 v83, v83
	v_add_f32_e32 v82, 1.0, v82
	v_add_f32_e32 v83, 1.0, v83
	v_rcp_f32_e32 v82, v82
	v_rcp_f32_e32 v83, v83
	s_nop 0
	v_pk_mul_f32 v[78:79], v[78:79], v[82:83]
	s_nop 0
	v_pk_mul_f32 v[70:71], v[70:71], v[78:79]
	v_mul_f32_e32 v78, 0xbfb8aa3b, v74
	v_mul_f32_e32 v79, 0xbfb8aa3b, v75
	v_exp_f32_e32 v78, v78
	v_exp_f32_e32 v79, v79
	v_add_f32_e32 v78, 1.0, v78
	v_add_f32_e32 v79, 1.0, v79
	v_rcp_f32_e32 v78, v78
	v_rcp_f32_e32 v79, v79
	s_nop 0
	v_pk_mul_f32 v[74:75], v[74:75], v[78:79]
	s_nop 0
	v_pk_mul_f32 v[74:75], v[66:67], v[74:75]
	v_pk_mul_f32 v[66:67], v[80:81], v[148:149] op_sel_hi:[1,0]
	s_nop 0
	v_mul_f32_e32 v78, 0xbfb8aa3b, v66
	v_mul_f32_e32 v79, 0xbfb8aa3b, v67
	v_exp_f32_e32 v78, v78
	v_exp_f32_e32 v79, v79
	v_add_f32_e32 v78, 1.0, v78
	v_add_f32_e32 v79, 1.0, v79
	v_rcp_f32_e32 v78, v78
	v_rcp_f32_e32 v79, v79
	s_nop 0
	v_pk_mul_f32 v[66:67], v[66:67], v[78:79]
; __device__ __forceinline__ float silu_f(float x) { return x * __builtin_amdgcn_rcpf(1.f + __builtin_amdgcn_exp2f(-LOG2E * x)); }
; __device__ __forceinline__ u32x4 pk8(const f32x4 a, const f32x4 b) { u32x4 w; w.x = pk2(a[0], a[1]); w.y = pk2(a[2], a[3]); w.z = pk2(b[0], b[1]); w.w = pk2(b[2], b[3]); return w; }
;     __device__ __forceinline__ void operator()(const Acc& acc, const Unit& u, int wr, int wc, int fr, int fq, const Pre& pre) const {
;     ...
;                 f32x4 v0, v1; const float rs = rsq[ai][m];
; #pragma unroll
;                 for (int e = 0; e < 4; ++e) { v0[e] = silu_f(acc[ai][0][m][0][e] * rs) * (acc[ai][1][m][0][e] * rs); v1[e] = silu_f(acc[ai][0][m][1][e] * rs) * (acc[ai][1][m][1][e] * rs); }
;                 *(u32x4*)(O + (size_t)(row0 + ai * 128 + m * 16) * ldc + col0) = pk8(v0, v1);
	s_nop 0
	v_pk_mul_f32 v[72:73], v[72:73], v[66:67]
	v_pk_mul_f32 v[66:67], v[76:77], v[148:149] op_sel_hi:[1,0]
	s_nop 0
	v_mul_f32_e32 v76, 0xbfb8aa3b, v66
	v_mul_f32_e32 v77, 0xbfb8aa3b, v67
	v_exp_f32_e32 v76, v76
	v_exp_f32_e32 v77, v77
	v_add_f32_e32 v76, 1.0, v76
	v_add_f32_e32 v77, 1.0, v77
	v_rcp_f32_e32 v76, v76
	v_rcp_f32_e32 v77, v77
	s_nop 0
	v_pk_mul_f32 v[66:67], v[66:67], v[76:77]
	s_nop 0
	v_pk_mul_f32 v[76:77], v[68:69], v[66:67]
	v_cvt_pk_bf16_f32 v66, v70, v71
	v_or_b32_e32 v70, 48, v153
	v_cvt_pk_bf16_f32 v67, v72, v73
	v_mul_lo_u32 v72, s13, v70
	v_mad_u64_u32 v[70:71], s[4:5], s12, v70, 0
	v_add3_u32 v71, v71, v116, v72
	v_lshl_add_u64 v[70:71], v[70:71], 1, s[62:63]
	v_cvt_pk_bf16_f32 v68, v74, v75
	v_cvt_pk_bf16_f32 v69, v76, v77
	v_lshl_add_u64 v[70:71], v[70:71], 0, v[114:115]
	global_store_dwordx4 v[70:71], v[66:69], off
	s_nop 1
	v_mul_f32_e32 v66, 0xbfb8aa3b, v62
	v_mul_f32_e32 v67, 0xbfb8aa3b, v63
	v_exp_f32_e32 v66, v66
	v_exp_f32_e32 v67, v67
	v_add_u32_e32 v68, 0x80, v153
	v_add_f32_e32 v66, 1.0, v66
	v_add_f32_e32 v67, 1.0, v67
	v_rcp_f32_e32 v66, v66
	v_rcp_f32_e32 v67, v67
	s_nop 0
	v_pk_mul_f32 v[62:63], v[62:63], v[66:67]
	s_nop 0
	v_pk_mul_f32 v[54:55], v[54:55], v[62:63]
	v_mul_f32_e32 v62, 0xbfb8aa3b, v58
	v_mul_f32_e32 v63, 0xbfb8aa3b, v59
	v_exp_f32_e32 v62, v62
	v_exp_f32_e32 v63, v63
	v_add_f32_e32 v62, 1.0, v62
	v_add_f32_e32 v63, 1.0, v63
	v_rcp_f32_e32 v62, v62
	v_rcp_f32_e32 v63, v63
	s_nop 0
	v_pk_mul_f32 v[58:59], v[58:59], v[62:63]
	s_nop 0
	v_pk_mul_f32 v[58:59], v[50:51], v[58:59]
	v_pk_mul_f32 v[50:51], v[64:65], v[146:147] op_sel_hi:[1,0]
	s_nop 0
	v_mul_f32_e32 v62, 0xbfb8aa3b, v50
	v_mul_f32_e32 v63, 0xbfb8aa3b, v51
	v_exp_f32_e32 v62, v62
	v_exp_f32_e32 v63, v63
	v_add_f32_e32 v62, 1.0, v62
	v_add_f32_e32 v63, 1.0, v63
	v_rcp_f32_e32 v62, v62
	v_rcp_f32_e32 v63, v63
	s_nop 0
	v_pk_mul_f32 v[50:51], v[50:51], v[62:63]
	s_nop 0
	v_pk_mul_f32 v[56:57], v[56:57], v[50:51]
	v_pk_mul_f32 v[50:51], v[60:61], v[146:147] op_sel_hi:[1,0]
	s_nop 0
	v_mul_f32_e32 v60, 0xbfb8aa3b, v50
	v_mul_f32_e32 v61, 0xbfb8aa3b, v51
	v_exp_f32_e32 v60, v60
	v_exp_f32_e32 v61, v61
	v_add_f32_e32 v60, 1.0, v60
	v_add_f32_e32 v61, 1.0, v61
	v_rcp_f32_e32 v60, v60
	v_rcp_f32_e32 v61, v61
	s_nop 0
	v_pk_mul_f32 v[50:51], v[50:51], v[60:61]
	s_nop 0
	v_pk_mul_f32 v[60:61], v[52:53], v[50:51]
	v_cvt_pk_bf16_f32 v50, v54, v55
	v_ashrrev_i32_e32 v54, 31, v68
	v_cvt_pk_bf16_f32 v51, v56, v57
	v_mul_lo_u32 v56, s12, v54
	v_mul_lo_u32 v57, s13, v68
	v_mad_u64_u32 v[54:55], s[4:5], s12, v68, 0
	v_add3_u32 v55, v55, v56, v57
	v_lshl_add_u64 v[54:55], v[54:55], 1, s[62:63]
	v_cvt_pk_bf16_f32 v52, v58, v59
	v_cvt_pk_bf16_f32 v53, v60, v61
	v_lshl_add_u64 v[54:55], v[54:55], 0, v[114:115]
	global_store_dwordx4 v[54:55], v[50:53], off
	s_nop 1
	v_mul_f32_e32 v50, 0xbfb8aa3b, v46
	v_mul_f32_e32 v51, 0xbfb8aa3b, v47
	v_exp_f32_e32 v50, v50
	v_exp_f32_e32 v51, v51
	v_add_f32_e32 v50, 1.0, v50
	v_add_f32_e32 v51, 1.0, v51
	v_rcp_f32_e32 v50, v50
	v_rcp_f32_e32 v51, v51
	s_nop 0
	v_pk_mul_f32 v[46:47], v[46:47], v[50:51]
	s_nop 0
	v_pk_mul_f32 v[38:39], v[38:39], v[46:47]
	v_mul_f32_e32 v46, 0xbfb8aa3b, v42
	v_mul_f32_e32 v47, 0xbfb8aa3b, v43
	v_exp_f32_e32 v46, v46
	v_exp_f32_e32 v47, v47
	v_add_f32_e32 v46, 1.0, v46
	v_add_f32_e32 v47, 1.0, v47
	v_rcp_f32_e32 v46, v46
	v_rcp_f32_e32 v47, v47
	s_nop 0
	v_pk_mul_f32 v[42:43], v[42:43], v[46:47]
	s_nop 0
	v_pk_mul_f32 v[42:43], v[34:35], v[42:43]
	v_pk_mul_f32 v[34:35], v[48:49], v[144:145] op_sel_hi:[1,0]
	s_nop 0
	v_mul_f32_e32 v46, 0xbfb8aa3b, v34
	v_mul_f32_e32 v47, 0xbfb8aa3b, v35
	v_exp_f32_e32 v46, v46
	v_exp_f32_e32 v47, v47
	v_add_f32_e32 v46, 1.0, v46
	v_add_f32_e32 v47, 1.0, v47
	v_rcp_f32_e32 v46, v46
	v_rcp_f32_e32 v47, v47
	s_nop 0
	v_pk_mul_f32 v[34:35], v[34:35], v[46:47]
	s_nop 0
	v_pk_mul_f32 v[40:41], v[40:41], v[34:35]
	v_pk_mul_f32 v[34:35], v[44:45], v[144:145] op_sel_hi:[1,0]
	s_nop 0
	v_mul_f32_e32 v44, 0xbfb8aa3b, v34
	v_mul_f32_e32 v45, 0xbfb8aa3b, v35
	v_exp_f32_e32 v44, v44
	v_exp_f32_e32 v45, v45
	v_add_f32_e32 v44, 1.0, v44
	v_add_f32_e32 v45, 1.0, v45
	v_rcp_f32_e32 v44, v44
	v_rcp_f32_e32 v45, v45
	s_nop 0
	v_pk_mul_f32 v[34:35], v[34:35], v[44:45]
	s_nop 0
	v_pk_mul_f32 v[44:45], v[36:37], v[34:35]
	v_cvt_pk_bf16_f32 v34, v38, v39
; __device__ __forceinline__ float silu_f(float x) { return x * __builtin_amdgcn_rcpf(1.f + __builtin_amdgcn_exp2f(-LOG2E * x)); }
; __device__ __forceinline__ u32x4 pk8(const f32x4 a, const f32x4 b) { u32x4 w; w.x = pk2(a[0], a[1]); w.y = pk2(a[2], a[3]); w.z = pk2(b[0], b[1]); w.w = pk2(b[2], b[3]); return w; }
; template <class Epi>
; __device__ __forceinline__ void gemm_phase(LAS unsigned char* lds, const Gemm g, const Sched& S, const Epi& E) {
;     ...
;         E(acc, cur, wr, wc, fr, fq, pre);
;         if (!has_next) break;
;     __device__ __forceinline__ void operator()(const Acc& acc, const Unit& u, int wr, int wc, int fr, int fq, const Pre& pre) const {
;     ...
;                 f32x4 v0, v1; const float rs = rsq[ai][m];
; #pragma unroll
;                 for (int e = 0; e < 4; ++e) { v0[e] = silu_f(acc[ai][0][m][0][e] * rs) * (acc[ai][1][m][0][e] * rs); v1[e] = silu_f(acc[ai][0][m][1][e] * rs) * (acc[ai][1][m][1][e] * rs); }
;                 *(u32x4*)(O + (size_t)(row0 + ai * 128 + m * 16) * ldc + col0) = pk8(v0, v1);
	v_add_u32_e32 v38, 0x90, v153
	v_ashrrev_i32_e32 v39, 31, v38
	v_cvt_pk_bf16_f32 v35, v40, v41
	v_mul_lo_u32 v40, s12, v39
	v_mul_lo_u32 v41, s13, v38
	v_mad_u64_u32 v[38:39], s[4:5], s12, v38, 0
	v_add3_u32 v39, v39, v40, v41
	v_lshl_add_u64 v[38:39], v[38:39], 1, s[62:63]
	v_cvt_pk_bf16_f32 v36, v42, v43
	v_cvt_pk_bf16_f32 v37, v44, v45
	v_lshl_add_u64 v[38:39], v[38:39], 0, v[114:115]
	global_store_dwordx4 v[38:39], v[34:37], off
	s_nop 1
	v_mul_f32_e32 v34, 0xbfb8aa3b, v30
	v_mul_f32_e32 v35, 0xbfb8aa3b, v31
	v_exp_f32_e32 v34, v34
	v_exp_f32_e32 v35, v35
	v_add_f32_e32 v34, 1.0, v34
	v_add_f32_e32 v35, 1.0, v35
	v_rcp_f32_e32 v34, v34
	v_rcp_f32_e32 v35, v35
	s_nop 0
	v_pk_mul_f32 v[30:31], v[30:31], v[34:35]
	s_nop 0
	v_pk_mul_f32 v[22:23], v[22:23], v[30:31]
	v_mul_f32_e32 v30, 0xbfb8aa3b, v26
	v_mul_f32_e32 v31, 0xbfb8aa3b, v27
	v_exp_f32_e32 v30, v30
	v_exp_f32_e32 v31, v31
	v_add_f32_e32 v30, 1.0, v30
	v_add_f32_e32 v31, 1.0, v31
	v_rcp_f32_e32 v30, v30
	v_rcp_f32_e32 v31, v31
	s_nop 0
	v_pk_mul_f32 v[26:27], v[26:27], v[30:31]
	s_nop 0
	v_pk_mul_f32 v[26:27], v[18:19], v[26:27]
	v_pk_mul_f32 v[18:19], v[32:33], v[142:143] op_sel_hi:[1,0]
	s_nop 0
	v_mul_f32_e32 v30, 0xbfb8aa3b, v18
	v_mul_f32_e32 v31, 0xbfb8aa3b, v19
	v_exp_f32_e32 v30, v30
	v_exp_f32_e32 v31, v31
	v_add_f32_e32 v30, 1.0, v30
	v_add_f32_e32 v31, 1.0, v31
	v_rcp_f32_e32 v30, v30
	v_rcp_f32_e32 v31, v31
	s_nop 0
	v_pk_mul_f32 v[18:19], v[18:19], v[30:31]
	s_nop 0
	v_pk_mul_f32 v[24:25], v[24:25], v[18:19]
	v_pk_mul_f32 v[18:19], v[28:29], v[142:143] op_sel_hi:[1,0]
	s_nop 0
	v_mul_f32_e32 v28, 0xbfb8aa3b, v18
	v_mul_f32_e32 v29, 0xbfb8aa3b, v19
	v_exp_f32_e32 v28, v28
	v_exp_f32_e32 v29, v29
	v_add_f32_e32 v28, 1.0, v28
	v_add_f32_e32 v29, 1.0, v29
	v_rcp_f32_e32 v28, v28
	v_rcp_f32_e32 v29, v29
	s_nop 0
	v_pk_mul_f32 v[18:19], v[18:19], v[28:29]
	s_nop 0
	v_pk_mul_f32 v[28:29], v[20:21], v[18:19]
	v_cvt_pk_bf16_f32 v18, v22, v23
	v_add_u32_e32 v22, 0xa0, v153
	v_ashrrev_i32_e32 v23, 31, v22
	v_cvt_pk_bf16_f32 v19, v24, v25
	v_mul_lo_u32 v24, s12, v23
	v_mul_lo_u32 v25, s13, v22
	v_mad_u64_u32 v[22:23], s[4:5], s12, v22, 0
	v_add3_u32 v23, v23, v24, v25
	v_lshl_add_u64 v[22:23], v[22:23], 1, s[62:63]
	v_cvt_pk_bf16_f32 v20, v26, v27
	v_cvt_pk_bf16_f32 v21, v28, v29
	v_lshl_add_u64 v[22:23], v[22:23], 0, v[114:115]
	global_store_dwordx4 v[22:23], v[18:21], off
	s_nop 1
	v_mul_f32_e32 v18, 0xbfb8aa3b, v14
	v_mul_f32_e32 v19, 0xbfb8aa3b, v15
	v_exp_f32_e32 v18, v18
	v_exp_f32_e32 v19, v19
	v_add_f32_e32 v18, 1.0, v18
	v_add_f32_e32 v19, 1.0, v19
	v_rcp_f32_e32 v18, v18
	v_rcp_f32_e32 v19, v19
	s_nop 0
	v_pk_mul_f32 v[14:15], v[14:15], v[18:19]
	s_nop 0
	v_pk_mul_f32 v[6:7], v[6:7], v[14:15]
	v_mul_f32_e32 v14, 0xbfb8aa3b, v10
	v_mul_f32_e32 v15, 0xbfb8aa3b, v11
	v_exp_f32_e32 v14, v14
	v_exp_f32_e32 v15, v15
	v_add_f32_e32 v14, 1.0, v14
	v_add_f32_e32 v15, 1.0, v15
	v_rcp_f32_e32 v14, v14
	v_rcp_f32_e32 v15, v15
	s_nop 0
	v_pk_mul_f32 v[10:11], v[10:11], v[14:15]
	s_nop 0
	v_pk_mul_f32 v[10:11], v[2:3], v[10:11]
	v_pk_mul_f32 v[2:3], v[16:17], v[140:141] op_sel_hi:[1,0]
	s_nop 0
	v_mul_f32_e32 v14, 0xbfb8aa3b, v2
	v_mul_f32_e32 v15, 0xbfb8aa3b, v3
	v_exp_f32_e32 v14, v14
	v_exp_f32_e32 v15, v15
	v_add_f32_e32 v14, 1.0, v14
	v_add_f32_e32 v15, 1.0, v15
	v_rcp_f32_e32 v14, v14
	v_rcp_f32_e32 v15, v15
	s_nop 0
	v_pk_mul_f32 v[2:3], v[2:3], v[14:15]
	s_nop 0
	v_pk_mul_f32 v[8:9], v[8:9], v[2:3]
	v_pk_mul_f32 v[2:3], v[12:13], v[140:141] op_sel_hi:[1,0]
	s_nop 0
	v_mul_f32_e32 v12, 0xbfb8aa3b, v2
	v_mul_f32_e32 v13, 0xbfb8aa3b, v3
	v_exp_f32_e32 v12, v12
	v_exp_f32_e32 v13, v13
	v_add_f32_e32 v12, 1.0, v12
	v_add_f32_e32 v13, 1.0, v13
	v_rcp_f32_e32 v12, v12
	v_rcp_f32_e32 v13, v13
	s_nop 0
	v_pk_mul_f32 v[2:3], v[2:3], v[12:13]
	s_nop 0
	v_pk_mul_f32 v[12:13], v[4:5], v[2:3]
	v_cvt_pk_bf16_f32 v2, v6, v7
	v_add_u32_e32 v6, 0xb0, v153
	v_ashrrev_i32_e32 v7, 31, v6
	v_cvt_pk_bf16_f32 v3, v8, v9
	v_mul_lo_u32 v8, s12, v7
	v_mul_lo_u32 v9, s13, v6
	v_mad_u64_u32 v[6:7], s[4:5], s12, v6, 0
	v_add3_u32 v7, v7, v8, v9
	v_lshl_add_u64 v[6:7], v[6:7], 1, s[62:63]
	v_cvt_pk_bf16_f32 v4, v10, v11
	v_cvt_pk_bf16_f32 v5, v12, v13
	v_lshl_add_u64 v[6:7], v[6:7], 0, v[114:115]
	s_mov_b64 s[4:5], s[64:65]
	global_store_dwordx4 v[6:7], v[2:5], off
	s_cbranch_vccz .LBB0_813
	s_branch .LBB0_828
